# v065 + barrier hand-off chain shortened: s_setprio 1 moved before the L->M barrier, s_setprio 0 after the M->L barrier, redundant lgkmcnt(0) after barrier dropped
# speedup vs baseline: 1.0086x; 1.0046x over previous
.LBB0_490:
	s_ashr_i32 s11, s10, 31
	s_lshl_b64 s[12:13], s[10:11], 20
	v_readlane_b32 s14, v253, 25
	v_readlane_b32 s15, v253, 26
	s_add_u32 s12, s14, s12
	s_addc_u32 s13, s15, s13
	s_and_b64 s[14:15], s[34:35], exec
	s_cselect_b32 s11, s13, s17
	s_cselect_b32 s49, s12, s16
	s_ashr_i32 s9, s8, 31
	s_lshl_b64 s[14:15], s[8:9], 20
	s_add_u32 s14, s25, s14
	s_addc_u32 s15, s36, s15
	s_and_b64 s[20:21], s[34:35], exec
	s_cselect_b32 s9, s15, s19
	s_cselect_b32 s50, s14, s18
	s_add_u32 s16, s16, 0x80080
	s_addc_u32 s17, s17, 0
	s_add_u32 s51, s18, 0x100
	s_addc_u32 s52, s19, 0
	s_mov_b32 s53, -2
	s_add_u32 s18, s16, 0xfff80080
	s_addc_u32 s19, s17, -1
	s_add_i32 s54, 0, 0x10000
	s_cmp_eq_u32 s53, 28
	s_cselect_b32 s21, s11, s19
	s_cselect_b32 s20, s49, s18
	s_cselect_b32 s19, s9, s52
	s_cselect_b32 s18, s50, s51
	s_add_i32 s56, 0, 0x14000
	v_add_u32_e32 v156, s54, v141
	v_add_u32_e32 v172, s56, v141
	ds_read_b128 v[144:147], v156
	ds_read_b128 v[148:151], v156 offset:1024
	ds_read_b128 v[152:155], v156 offset:2048
	ds_read_b128 v[156:159], v156 offset:3072
	ds_read_b128 v[160:163], v172
	ds_read_b128 v[164:167], v172 offset:1024
	ds_read_b128 v[168:171], v172 offset:2048
	ds_read_b128 v[172:175], v172 offset:3072
	v_lshl_add_u64 v[208:209], s[16:17], 0, v[136:137]
	s_add_i32 m0, s39, 0xc000
	ds_read_b128 v[176:179], v143
	ds_read_b128 v[180:183], v143 offset:1024
	ds_read_b128 v[184:187], v143 offset:2048
	ds_read_b128 v[188:191], v143 offset:3072
	ds_read_b128 v[192:195], v143 offset:4096
	ds_read_b128 v[196:199], v143 offset:5120
	ds_read_b128 v[200:203], v143 offset:6144
	ds_read_b128 v[204:207], v143 offset:7168
	global_load_lds_dwordx4 v[208:209], off
	v_lshl_add_u64 v[208:209], s[16:17], 0, v[138:139]
	s_add_i32 m0, s39, 0xe000
	s_nop 0
	global_load_lds_dwordx4 v[208:209], off
	s_waitcnt vmcnt(8)
	s_waitcnt lgkmcnt(0)
	s_setprio 1
	s_barrier
	v_mfma_f32_16x16x32_bf16 v[126:129], v[144:147], v[176:179], 0
	v_mfma_f32_16x16x32_bf16 v[122:125], v[152:155], v[176:179], 0
	v_mfma_f32_16x16x32_bf16 v[118:121], v[144:147], v[184:187], 0
	v_mfma_f32_16x16x32_bf16 v[114:117], v[152:155], v[184:187], 0
	v_mfma_f32_16x16x32_bf16 v[102:105], v[144:147], v[192:195], 0
	v_mfma_f32_16x16x32_bf16 v[98:101], v[152:155], v[192:195], 0
	v_mfma_f32_16x16x32_bf16 v[86:89], v[144:147], v[200:203], 0
	v_mfma_f32_16x16x32_bf16 v[82:85], v[152:155], v[200:203], 0
	v_mfma_f32_16x16x32_bf16 v[126:129], v[148:151], v[180:183], v[126:129]
	v_mfma_f32_16x16x32_bf16 v[122:125], v[156:159], v[180:183], v[122:125]
	v_mfma_f32_16x16x32_bf16 v[118:121], v[148:151], v[188:191], v[118:121]
	v_mfma_f32_16x16x32_bf16 v[114:117], v[156:159], v[188:191], v[114:117]
	v_mfma_f32_16x16x32_bf16 v[102:105], v[148:151], v[196:199], v[102:105]
	v_mfma_f32_16x16x32_bf16 v[98:101], v[156:159], v[196:199], v[98:101]
	v_mfma_f32_16x16x32_bf16 v[86:89], v[148:151], v[204:207], v[86:89]
	v_mfma_f32_16x16x32_bf16 v[82:85], v[156:159], v[204:207], v[82:85]
	s_setprio 0
	s_setprio 1
	v_mfma_f32_16x16x32_bf16 v[110:113], v[160:163], v[176:179], 0
	v_mfma_f32_16x16x32_bf16 v[106:109], v[168:171], v[176:179], 0
	v_mfma_f32_16x16x32_bf16 v[94:97], v[160:163], v[184:187], 0
	v_mfma_f32_16x16x32_bf16 v[90:93], v[168:171], v[184:187], 0
	v_mfma_f32_16x16x32_bf16 v[78:81], v[160:163], v[192:195], 0
	v_mfma_f32_16x16x32_bf16 v[74:77], v[168:171], v[192:195], 0
	v_mfma_f32_16x16x32_bf16 v[70:73], v[160:163], v[200:203], 0
	v_mfma_f32_16x16x32_bf16 v[66:69], v[168:171], v[200:203], 0
	v_mfma_f32_16x16x32_bf16 v[110:113], v[164:167], v[180:183], v[110:113]
	v_mfma_f32_16x16x32_bf16 v[106:109], v[172:175], v[180:183], v[106:109]
	v_mfma_f32_16x16x32_bf16 v[94:97], v[164:167], v[188:191], v[94:97]
	v_mfma_f32_16x16x32_bf16 v[90:93], v[172:175], v[188:191], v[90:93]
	v_mfma_f32_16x16x32_bf16 v[78:81], v[164:167], v[196:199], v[78:81]
	v_mfma_f32_16x16x32_bf16 v[74:77], v[172:175], v[196:199], v[74:77]
	v_mfma_f32_16x16x32_bf16 v[70:73], v[164:167], v[204:207], v[70:73]
	v_mfma_f32_16x16x32_bf16 v[66:69], v[172:175], v[204:207], v[66:69]
	s_barrier
	s_setprio 0
	s_add_i32 s54, s54, s37
	v_lshl_add_u64 v[208:209], s[18:19], 0, v[0:1]
	s_mov_b32 m0, s54
	ds_read_b128 v[176:179], v143 offset:16384
	ds_read_b128 v[180:183], v143 offset:17408
	ds_read_b128 v[184:187], v143 offset:18432
	ds_read_b128 v[188:191], v143 offset:19456
	ds_read_b128 v[192:195], v143 offset:20480
	ds_read_b128 v[196:199], v143 offset:21504
	ds_read_b128 v[200:203], v143 offset:22528
	ds_read_b128 v[204:207], v143 offset:23552
	global_load_lds_dwordx4 v[208:209], off
	s_add_i32 m0, s54, 0x2000
	s_add_u32 s54, s18, 0x80000
	v_lshl_add_u64 v[220:221], s[18:19], 0, v[130:131]
	s_addc_u32 s55, s19, 0
	s_add_i32 s56, s56, s37
	global_load_lds_dwordx4 v[220:221], off
	v_lshl_add_u64 v[222:223], s[54:55], 0, v[0:1]
	s_mov_b32 m0, s56
	v_lshl_add_u64 v[224:225], s[20:21], 0, v[132:133]
	global_load_lds_dwordx4 v[222:223], off
	v_lshl_add_u64 v[222:223], s[54:55], 0, v[130:131]
	s_add_i32 m0, s56, 0x2000
	s_nop 0
	global_load_lds_dwordx4 v[222:223], off
	v_lshl_add_u64 v[222:223], s[20:21], 0, v[134:135]
	s_mov_b32 m0, s39
	s_nop 0
	global_load_lds_dwordx4 v[222:223], off
	s_mov_b32 m0, s40
	s_nop 0
	global_load_lds_dwordx4 v[224:225], off
	s_waitcnt vmcnt(8)
	s_waitcnt lgkmcnt(0)
	s_setprio 1
	s_barrier
	v_mfma_f32_16x16x32_bf16 v[62:65], v[144:147], v[176:179], 0
	v_mfma_f32_16x16x32_bf16 v[58:61], v[152:155], v[176:179], 0
	v_mfma_f32_16x16x32_bf16 v[54:57], v[144:147], v[184:187], 0
	v_mfma_f32_16x16x32_bf16 v[50:53], v[152:155], v[184:187], 0
	v_mfma_f32_16x16x32_bf16 v[38:41], v[144:147], v[192:195], 0
	v_mfma_f32_16x16x32_bf16 v[34:37], v[152:155], v[192:195], 0
	v_mfma_f32_16x16x32_bf16 v[22:25], v[144:147], v[200:203], 0
	v_mfma_f32_16x16x32_bf16 v[18:21], v[152:155], v[200:203], 0
	v_mfma_f32_16x16x32_bf16 v[62:65], v[148:151], v[180:183], v[62:65]
	v_mfma_f32_16x16x32_bf16 v[58:61], v[156:159], v[180:183], v[58:61]
	v_mfma_f32_16x16x32_bf16 v[54:57], v[148:151], v[188:191], v[54:57]
	v_mfma_f32_16x16x32_bf16 v[50:53], v[156:159], v[188:191], v[50:53]
	v_mfma_f32_16x16x32_bf16 v[38:41], v[148:151], v[196:199], v[38:41]
	v_mfma_f32_16x16x32_bf16 v[34:37], v[156:159], v[196:199], v[34:37]
	v_mfma_f32_16x16x32_bf16 v[22:25], v[148:151], v[204:207], v[22:25]
	v_mfma_f32_16x16x32_bf16 v[18:21], v[156:159], v[204:207], v[18:21]
	s_setprio 0
	s_setprio 1
	v_mfma_f32_16x16x32_bf16 v[46:49], v[160:163], v[176:179], 0
	v_mfma_f32_16x16x32_bf16 v[42:45], v[168:171], v[176:179], 0
	v_mfma_f32_16x16x32_bf16 v[30:33], v[160:163], v[184:187], 0
	v_mfma_f32_16x16x32_bf16 v[26:29], v[168:171], v[184:187], 0
	v_mfma_f32_16x16x32_bf16 v[14:17], v[160:163], v[192:195], 0
	v_mfma_f32_16x16x32_bf16 v[10:13], v[168:171], v[192:195], 0
	v_mfma_f32_16x16x32_bf16 v[6:9], v[160:163], v[200:203], 0
	v_mfma_f32_16x16x32_bf16 v[2:5], v[168:171], v[200:203], 0
	v_mfma_f32_16x16x32_bf16 v[46:49], v[164:167], v[180:183], v[46:49]
	v_mfma_f32_16x16x32_bf16 v[42:45], v[172:175], v[180:183], v[42:45]
	v_mfma_f32_16x16x32_bf16 v[30:33], v[164:167], v[188:191], v[30:33]
	v_mfma_f32_16x16x32_bf16 v[26:29], v[172:175], v[188:191], v[26:29]
	v_mfma_f32_16x16x32_bf16 v[14:17], v[164:167], v[196:199], v[14:17]
	v_mfma_f32_16x16x32_bf16 v[10:13], v[172:175], v[196:199], v[10:13]
	v_mfma_f32_16x16x32_bf16 v[6:9], v[164:167], v[204:207], v[6:9]
	v_mfma_f32_16x16x32_bf16 v[2:5], v[172:175], v[204:207], v[2:5]
	s_barrier
	s_setprio 0
	s_add_i32 s54, 0, 0x18000
	s_add_i32 s55, 0, 0x1c000
	v_add_u32_e32 v156, s54, v141
	v_add_u32_e32 v172, s55, v141
	ds_read_b128 v[144:147], v156
	ds_read_b128 v[148:151], v156 offset:1024
	ds_read_b128 v[152:155], v156 offset:2048
	ds_read_b128 v[156:159], v156 offset:3072
	ds_read_b128 v[160:163], v172
	ds_read_b128 v[164:167], v172 offset:1024
	ds_read_b128 v[168:171], v172 offset:2048
	ds_read_b128 v[172:175], v172 offset:3072
	s_add_u32 s20, s20, 0x80000
	s_addc_u32 s21, s21, 0
	s_mov_b32 m0, s41
	v_lshl_add_u64 v[226:227], s[20:21], 0, v[134:135]
	ds_read_b128 v[176:179], v143 offset:32768
	ds_read_b128 v[180:183], v143 offset:33792
	ds_read_b128 v[184:187], v143 offset:34816
	ds_read_b128 v[188:191], v143 offset:35840
	ds_read_b128 v[192:195], v143 offset:36864
	ds_read_b128 v[196:199], v143 offset:37888
	ds_read_b128 v[200:203], v143 offset:38912
	ds_read_b128 v[204:207], v143 offset:39936
	global_load_lds_dwordx4 v[226:227], off
	v_lshl_add_u64 v[226:227], s[20:21], 0, v[132:133]
	s_mov_b32 m0, s44
	s_nop 0
	global_load_lds_dwordx4 v[226:227], off
	s_waitcnt vmcnt(8)
	s_waitcnt lgkmcnt(0)
	s_setprio 1
	s_barrier
	v_mfma_f32_16x16x32_bf16 v[126:129], v[144:147], v[176:179], v[126:129]
	v_mfma_f32_16x16x32_bf16 v[122:125], v[152:155], v[176:179], v[122:125]
	v_mfma_f32_16x16x32_bf16 v[118:121], v[144:147], v[184:187], v[118:121]
	v_mfma_f32_16x16x32_bf16 v[114:117], v[152:155], v[184:187], v[114:117]
	v_mfma_f32_16x16x32_bf16 v[102:105], v[144:147], v[192:195], v[102:105]
	v_mfma_f32_16x16x32_bf16 v[98:101], v[152:155], v[192:195], v[98:101]
	v_mfma_f32_16x16x32_bf16 v[86:89], v[144:147], v[200:203], v[86:89]
	v_mfma_f32_16x16x32_bf16 v[82:85], v[152:155], v[200:203], v[82:85]
	v_mfma_f32_16x16x32_bf16 v[126:129], v[148:151], v[180:183], v[126:129]
	v_mfma_f32_16x16x32_bf16 v[122:125], v[156:159], v[180:183], v[122:125]
	v_mfma_f32_16x16x32_bf16 v[118:121], v[148:151], v[188:191], v[118:121]
	v_mfma_f32_16x16x32_bf16 v[114:117], v[156:159], v[188:191], v[114:117]
	v_mfma_f32_16x16x32_bf16 v[102:105], v[148:151], v[196:199], v[102:105]
	v_mfma_f32_16x16x32_bf16 v[98:101], v[156:159], v[196:199], v[98:101]
	v_mfma_f32_16x16x32_bf16 v[86:89], v[148:151], v[204:207], v[86:89]
	v_mfma_f32_16x16x32_bf16 v[82:85], v[156:159], v[204:207], v[82:85]
	s_setprio 0
	s_setprio 1
	v_mfma_f32_16x16x32_bf16 v[110:113], v[160:163], v[176:179], v[110:113]
	v_mfma_f32_16x16x32_bf16 v[106:109], v[168:171], v[176:179], v[106:109]
	v_mfma_f32_16x16x32_bf16 v[94:97], v[160:163], v[184:187], v[94:97]
	v_mfma_f32_16x16x32_bf16 v[90:93], v[168:171], v[184:187], v[90:93]
	v_mfma_f32_16x16x32_bf16 v[78:81], v[160:163], v[192:195], v[78:81]
	v_mfma_f32_16x16x32_bf16 v[74:77], v[168:171], v[192:195], v[74:77]
	v_mfma_f32_16x16x32_bf16 v[70:73], v[160:163], v[200:203], v[70:73]
	v_mfma_f32_16x16x32_bf16 v[66:69], v[168:171], v[200:203], v[66:69]
	v_mfma_f32_16x16x32_bf16 v[110:113], v[164:167], v[180:183], v[110:113]
	v_mfma_f32_16x16x32_bf16 v[106:109], v[172:175], v[180:183], v[106:109]
	v_mfma_f32_16x16x32_bf16 v[94:97], v[164:167], v[188:191], v[94:97]
	v_mfma_f32_16x16x32_bf16 v[90:93], v[172:175], v[188:191], v[90:93]
	v_mfma_f32_16x16x32_bf16 v[78:81], v[164:167], v[196:199], v[78:81]
	v_mfma_f32_16x16x32_bf16 v[74:77], v[172:175], v[196:199], v[74:77]
	v_mfma_f32_16x16x32_bf16 v[70:73], v[164:167], v[204:207], v[70:73]
	v_mfma_f32_16x16x32_bf16 v[66:69], v[172:175], v[204:207], v[66:69]
	s_barrier
	s_setprio 0
	s_add_i32 s20, s54, s37
	v_lshl_add_u64 v[208:209], v[208:209], 0, s[2:3]
	s_mov_b32 m0, s20
	ds_read_b128 v[176:179], v143 offset:49152
	ds_read_b128 v[180:183], v143 offset:50176
	ds_read_b128 v[184:187], v143 offset:51200
	ds_read_b128 v[188:191], v143 offset:52224
	ds_read_b128 v[192:195], v143 offset:53248
	ds_read_b128 v[196:199], v143 offset:54272
	ds_read_b128 v[200:203], v143 offset:55296
	ds_read_b128 v[204:207], v143 offset:56320
	global_load_lds_dwordx4 v[208:209], off
	s_add_i32 m0, s20, 0x2000
	s_add_u32 s18, s18, 0x80080
	v_lshl_add_u64 v[208:209], v[220:221], 0, s[2:3]
	s_addc_u32 s19, s19, 0
	s_add_i32 s20, s55, s37
	global_load_lds_dwordx4 v[208:209], off
	v_lshl_add_u64 v[208:209], s[18:19], 0, v[0:1]
	s_mov_b32 m0, s20
	s_nop 0
	global_load_lds_dwordx4 v[208:209], off
	v_lshl_add_u64 v[208:209], s[18:19], 0, v[130:131]
	s_add_i32 m0, s20, 0x2000
	s_nop 0
	global_load_lds_dwordx4 v[208:209], off
	v_lshl_add_u64 v[208:209], v[222:223], 0, s[2:3]
	s_mov_b32 m0, s45
	s_nop 0
	global_load_lds_dwordx4 v[208:209], off
	v_lshl_add_u64 v[208:209], v[224:225], 0, s[2:3]
	s_mov_b32 m0, s46
	s_nop 0
	global_load_lds_dwordx4 v[208:209], off
	s_waitcnt vmcnt(8)
	s_waitcnt lgkmcnt(0)
	s_setprio 1
	s_barrier
	v_mfma_f32_16x16x32_bf16 v[62:65], v[144:147], v[176:179], v[62:65]
	v_mfma_f32_16x16x32_bf16 v[58:61], v[152:155], v[176:179], v[58:61]
	v_mfma_f32_16x16x32_bf16 v[54:57], v[144:147], v[184:187], v[54:57]
	v_mfma_f32_16x16x32_bf16 v[50:53], v[152:155], v[184:187], v[50:53]
	v_mfma_f32_16x16x32_bf16 v[38:41], v[144:147], v[192:195], v[38:41]
	v_mfma_f32_16x16x32_bf16 v[34:37], v[152:155], v[192:195], v[34:37]
	v_mfma_f32_16x16x32_bf16 v[22:25], v[144:147], v[200:203], v[22:25]
	v_mfma_f32_16x16x32_bf16 v[18:21], v[152:155], v[200:203], v[18:21]
	v_mfma_f32_16x16x32_bf16 v[62:65], v[148:151], v[180:183], v[62:65]
	v_mfma_f32_16x16x32_bf16 v[58:61], v[156:159], v[180:183], v[58:61]
	v_mfma_f32_16x16x32_bf16 v[54:57], v[148:151], v[188:191], v[54:57]
	v_mfma_f32_16x16x32_bf16 v[50:53], v[156:159], v[188:191], v[50:53]
	v_mfma_f32_16x16x32_bf16 v[38:41], v[148:151], v[196:199], v[38:41]
	v_mfma_f32_16x16x32_bf16 v[34:37], v[156:159], v[196:199], v[34:37]
	v_mfma_f32_16x16x32_bf16 v[22:25], v[148:151], v[204:207], v[22:25]
	v_mfma_f32_16x16x32_bf16 v[18:21], v[156:159], v[204:207], v[18:21]
	s_setprio 0
	s_setprio 1
	v_mfma_f32_16x16x32_bf16 v[46:49], v[160:163], v[176:179], v[46:49]
	v_mfma_f32_16x16x32_bf16 v[42:45], v[168:171], v[176:179], v[42:45]
	v_mfma_f32_16x16x32_bf16 v[30:33], v[160:163], v[184:187], v[30:33]
	v_mfma_f32_16x16x32_bf16 v[26:29], v[168:171], v[184:187], v[26:29]
	v_mfma_f32_16x16x32_bf16 v[14:17], v[160:163], v[192:195], v[14:17]
	v_mfma_f32_16x16x32_bf16 v[10:13], v[168:171], v[192:195], v[10:13]
	v_mfma_f32_16x16x32_bf16 v[6:9], v[160:163], v[200:203], v[6:9]
	v_mfma_f32_16x16x32_bf16 v[2:5], v[168:171], v[200:203], v[2:5]
	v_mfma_f32_16x16x32_bf16 v[46:49], v[164:167], v[180:183], v[46:49]
	v_mfma_f32_16x16x32_bf16 v[42:45], v[172:175], v[180:183], v[42:45]
	v_mfma_f32_16x16x32_bf16 v[30:33], v[164:167], v[188:191], v[30:33]
	v_mfma_f32_16x16x32_bf16 v[26:29], v[172:175], v[188:191], v[26:29]
	v_mfma_f32_16x16x32_bf16 v[14:17], v[164:167], v[196:199], v[14:17]
	v_mfma_f32_16x16x32_bf16 v[10:13], v[172:175], v[196:199], v[10:13]
	v_mfma_f32_16x16x32_bf16 v[6:9], v[164:167], v[204:207], v[6:9]
	v_mfma_f32_16x16x32_bf16 v[2:5], v[172:175], v[204:207], v[2:5]
	s_barrier
	s_setprio 0
	s_add_i32 s53, s53, 2
	s_add_u32 s16, s16, 0x100
	s_addc_u32 s17, s17, 0
	s_add_u32 s51, s51, 0x100
	s_addc_u32 s52, s52, 0
	s_cmp_gt_u32 s53, 29
	s_cbranch_scc1 .Lpeel_done_0
.LBB0_491:
	s_add_u32 s18, s16, 0xfff80080
	s_addc_u32 s19, s17, -1
	s_add_i32 s54, 0, 0x10000
	s_cmp_eq_u32 s53, 28
	s_cselect_b32 s21, s11, s19
	s_cselect_b32 s20, s49, s18
	s_cselect_b32 s19, s9, s52
	s_cselect_b32 s18, s50, s51
	s_add_i32 s56, 0, 0x14000
	v_add_u32_e32 v156, s54, v141
	v_add_u32_e32 v172, s56, v141
	ds_read_b128 v[144:147], v156
	ds_read_b128 v[148:151], v156 offset:1024
	ds_read_b128 v[152:155], v156 offset:2048
	ds_read_b128 v[156:159], v156 offset:3072
	ds_read_b128 v[160:163], v172
	ds_read_b128 v[164:167], v172 offset:1024
	ds_read_b128 v[168:171], v172 offset:2048
	ds_read_b128 v[172:175], v172 offset:3072
	v_lshl_add_u64 v[208:209], s[16:17], 0, v[136:137]
	s_add_i32 m0, s39, 0xc000
	ds_read_b128 v[176:179], v143
	ds_read_b128 v[180:183], v143 offset:1024
	ds_read_b128 v[184:187], v143 offset:2048
	ds_read_b128 v[188:191], v143 offset:3072
	ds_read_b128 v[192:195], v143 offset:4096
	ds_read_b128 v[196:199], v143 offset:5120
	ds_read_b128 v[200:203], v143 offset:6144
	ds_read_b128 v[204:207], v143 offset:7168
	global_load_lds_dwordx4 v[208:209], off
	v_lshl_add_u64 v[208:209], s[16:17], 0, v[138:139]
	s_add_i32 m0, s39, 0xe000
	s_nop 0
	global_load_lds_dwordx4 v[208:209], off
	s_waitcnt vmcnt(8)
	s_waitcnt lgkmcnt(0)
	s_setprio 1
	s_barrier
	v_mfma_f32_16x16x32_bf16 v[126:129], v[144:147], v[176:179], v[126:129]
	v_mfma_f32_16x16x32_bf16 v[122:125], v[152:155], v[176:179], v[122:125]
	v_mfma_f32_16x16x32_bf16 v[118:121], v[144:147], v[184:187], v[118:121]
	v_mfma_f32_16x16x32_bf16 v[114:117], v[152:155], v[184:187], v[114:117]
	v_mfma_f32_16x16x32_bf16 v[102:105], v[144:147], v[192:195], v[102:105]
	v_mfma_f32_16x16x32_bf16 v[98:101], v[152:155], v[192:195], v[98:101]
	v_mfma_f32_16x16x32_bf16 v[86:89], v[144:147], v[200:203], v[86:89]
	v_mfma_f32_16x16x32_bf16 v[82:85], v[152:155], v[200:203], v[82:85]
	v_mfma_f32_16x16x32_bf16 v[126:129], v[148:151], v[180:183], v[126:129]
	v_mfma_f32_16x16x32_bf16 v[122:125], v[156:159], v[180:183], v[122:125]
	v_mfma_f32_16x16x32_bf16 v[118:121], v[148:151], v[188:191], v[118:121]
	v_mfma_f32_16x16x32_bf16 v[114:117], v[156:159], v[188:191], v[114:117]
	v_mfma_f32_16x16x32_bf16 v[102:105], v[148:151], v[196:199], v[102:105]
	v_mfma_f32_16x16x32_bf16 v[98:101], v[156:159], v[196:199], v[98:101]
	v_mfma_f32_16x16x32_bf16 v[86:89], v[148:151], v[204:207], v[86:89]
	v_mfma_f32_16x16x32_bf16 v[82:85], v[156:159], v[204:207], v[82:85]
	s_setprio 0
	s_setprio 1
	v_mfma_f32_16x16x32_bf16 v[110:113], v[160:163], v[176:179], v[110:113]
	v_mfma_f32_16x16x32_bf16 v[106:109], v[168:171], v[176:179], v[106:109]
	v_mfma_f32_16x16x32_bf16 v[94:97], v[160:163], v[184:187], v[94:97]
	v_mfma_f32_16x16x32_bf16 v[90:93], v[168:171], v[184:187], v[90:93]
	v_mfma_f32_16x16x32_bf16 v[78:81], v[160:163], v[192:195], v[78:81]
	v_mfma_f32_16x16x32_bf16 v[74:77], v[168:171], v[192:195], v[74:77]
	v_mfma_f32_16x16x32_bf16 v[70:73], v[160:163], v[200:203], v[70:73]
	v_mfma_f32_16x16x32_bf16 v[66:69], v[168:171], v[200:203], v[66:69]
	v_mfma_f32_16x16x32_bf16 v[110:113], v[164:167], v[180:183], v[110:113]
	v_mfma_f32_16x16x32_bf16 v[106:109], v[172:175], v[180:183], v[106:109]
	v_mfma_f32_16x16x32_bf16 v[94:97], v[164:167], v[188:191], v[94:97]
	v_mfma_f32_16x16x32_bf16 v[90:93], v[172:175], v[188:191], v[90:93]
	v_mfma_f32_16x16x32_bf16 v[78:81], v[164:167], v[196:199], v[78:81]
	v_mfma_f32_16x16x32_bf16 v[74:77], v[172:175], v[196:199], v[74:77]
	v_mfma_f32_16x16x32_bf16 v[70:73], v[164:167], v[204:207], v[70:73]
	v_mfma_f32_16x16x32_bf16 v[66:69], v[172:175], v[204:207], v[66:69]
	s_barrier
	s_setprio 0
	s_add_i32 s54, s54, s37
	v_lshl_add_u64 v[208:209], s[18:19], 0, v[0:1]
	s_mov_b32 m0, s54
	ds_read_b128 v[176:179], v143 offset:16384
	ds_read_b128 v[180:183], v143 offset:17408
	ds_read_b128 v[184:187], v143 offset:18432
	ds_read_b128 v[188:191], v143 offset:19456
	ds_read_b128 v[192:195], v143 offset:20480
	ds_read_b128 v[196:199], v143 offset:21504
	ds_read_b128 v[200:203], v143 offset:22528
	ds_read_b128 v[204:207], v143 offset:23552
	global_load_lds_dwordx4 v[208:209], off
	s_add_i32 m0, s54, 0x2000
	s_add_u32 s54, s18, 0x80000
	v_lshl_add_u64 v[220:221], s[18:19], 0, v[130:131]
	s_addc_u32 s55, s19, 0
	s_add_i32 s56, s56, s37
	global_load_lds_dwordx4 v[220:221], off
	v_lshl_add_u64 v[222:223], s[54:55], 0, v[0:1]
	s_mov_b32 m0, s56
	v_lshl_add_u64 v[224:225], s[20:21], 0, v[132:133]
	global_load_lds_dwordx4 v[222:223], off
	v_lshl_add_u64 v[222:223], s[54:55], 0, v[130:131]
	s_add_i32 m0, s56, 0x2000
	s_nop 0
	global_load_lds_dwordx4 v[222:223], off
	v_lshl_add_u64 v[222:223], s[20:21], 0, v[134:135]
	s_mov_b32 m0, s39
	s_nop 0
	global_load_lds_dwordx4 v[222:223], off
	s_mov_b32 m0, s40
	s_nop 0
	global_load_lds_dwordx4 v[224:225], off
	s_waitcnt vmcnt(8)
	s_waitcnt lgkmcnt(0)
	s_setprio 1
	s_barrier
	v_mfma_f32_16x16x32_bf16 v[62:65], v[144:147], v[176:179], v[62:65]
	v_mfma_f32_16x16x32_bf16 v[58:61], v[152:155], v[176:179], v[58:61]
	v_mfma_f32_16x16x32_bf16 v[54:57], v[144:147], v[184:187], v[54:57]
	v_mfma_f32_16x16x32_bf16 v[50:53], v[152:155], v[184:187], v[50:53]
	v_mfma_f32_16x16x32_bf16 v[38:41], v[144:147], v[192:195], v[38:41]
	v_mfma_f32_16x16x32_bf16 v[34:37], v[152:155], v[192:195], v[34:37]
	v_mfma_f32_16x16x32_bf16 v[22:25], v[144:147], v[200:203], v[22:25]
	v_mfma_f32_16x16x32_bf16 v[18:21], v[152:155], v[200:203], v[18:21]
	v_mfma_f32_16x16x32_bf16 v[62:65], v[148:151], v[180:183], v[62:65]
	v_mfma_f32_16x16x32_bf16 v[58:61], v[156:159], v[180:183], v[58:61]
	v_mfma_f32_16x16x32_bf16 v[54:57], v[148:151], v[188:191], v[54:57]
	v_mfma_f32_16x16x32_bf16 v[50:53], v[156:159], v[188:191], v[50:53]
	v_mfma_f32_16x16x32_bf16 v[38:41], v[148:151], v[196:199], v[38:41]
	v_mfma_f32_16x16x32_bf16 v[34:37], v[156:159], v[196:199], v[34:37]
	v_mfma_f32_16x16x32_bf16 v[22:25], v[148:151], v[204:207], v[22:25]
	v_mfma_f32_16x16x32_bf16 v[18:21], v[156:159], v[204:207], v[18:21]
	s_setprio 0
	s_setprio 1
	v_mfma_f32_16x16x32_bf16 v[46:49], v[160:163], v[176:179], v[46:49]
	v_mfma_f32_16x16x32_bf16 v[42:45], v[168:171], v[176:179], v[42:45]
	v_mfma_f32_16x16x32_bf16 v[30:33], v[160:163], v[184:187], v[30:33]
	v_mfma_f32_16x16x32_bf16 v[26:29], v[168:171], v[184:187], v[26:29]
	v_mfma_f32_16x16x32_bf16 v[14:17], v[160:163], v[192:195], v[14:17]
	v_mfma_f32_16x16x32_bf16 v[10:13], v[168:171], v[192:195], v[10:13]
	v_mfma_f32_16x16x32_bf16 v[6:9], v[160:163], v[200:203], v[6:9]
	v_mfma_f32_16x16x32_bf16 v[2:5], v[168:171], v[200:203], v[2:5]
	v_mfma_f32_16x16x32_bf16 v[46:49], v[164:167], v[180:183], v[46:49]
	v_mfma_f32_16x16x32_bf16 v[42:45], v[172:175], v[180:183], v[42:45]
	v_mfma_f32_16x16x32_bf16 v[30:33], v[164:167], v[188:191], v[30:33]
	v_mfma_f32_16x16x32_bf16 v[26:29], v[172:175], v[188:191], v[26:29]
	v_mfma_f32_16x16x32_bf16 v[14:17], v[164:167], v[196:199], v[14:17]
	v_mfma_f32_16x16x32_bf16 v[10:13], v[172:175], v[196:199], v[10:13]
	v_mfma_f32_16x16x32_bf16 v[6:9], v[164:167], v[204:207], v[6:9]
	v_mfma_f32_16x16x32_bf16 v[2:5], v[172:175], v[204:207], v[2:5]
	s_barrier
	s_setprio 0
	s_add_i32 s54, 0, 0x18000
	s_add_i32 s55, 0, 0x1c000
	v_add_u32_e32 v156, s54, v141
	v_add_u32_e32 v172, s55, v141
	ds_read_b128 v[144:147], v156
	ds_read_b128 v[148:151], v156 offset:1024
	ds_read_b128 v[152:155], v156 offset:2048
	ds_read_b128 v[156:159], v156 offset:3072
	ds_read_b128 v[160:163], v172
	ds_read_b128 v[164:167], v172 offset:1024
	ds_read_b128 v[168:171], v172 offset:2048
	ds_read_b128 v[172:175], v172 offset:3072
	s_add_u32 s20, s20, 0x80000
	s_addc_u32 s21, s21, 0
	s_mov_b32 m0, s41
	v_lshl_add_u64 v[226:227], s[20:21], 0, v[134:135]
	ds_read_b128 v[176:179], v143 offset:32768
	ds_read_b128 v[180:183], v143 offset:33792
	ds_read_b128 v[184:187], v143 offset:34816
	ds_read_b128 v[188:191], v143 offset:35840
	ds_read_b128 v[192:195], v143 offset:36864
	ds_read_b128 v[196:199], v143 offset:37888
	ds_read_b128 v[200:203], v143 offset:38912
	ds_read_b128 v[204:207], v143 offset:39936
	global_load_lds_dwordx4 v[226:227], off
	v_lshl_add_u64 v[226:227], s[20:21], 0, v[132:133]
	s_mov_b32 m0, s44
	s_nop 0
	global_load_lds_dwordx4 v[226:227], off
	s_waitcnt vmcnt(8)
	s_waitcnt lgkmcnt(0)
	s_setprio 1
	s_barrier
	v_mfma_f32_16x16x32_bf16 v[126:129], v[144:147], v[176:179], v[126:129]
	v_mfma_f32_16x16x32_bf16 v[122:125], v[152:155], v[176:179], v[122:125]
	v_mfma_f32_16x16x32_bf16 v[118:121], v[144:147], v[184:187], v[118:121]
	v_mfma_f32_16x16x32_bf16 v[114:117], v[152:155], v[184:187], v[114:117]
	v_mfma_f32_16x16x32_bf16 v[102:105], v[144:147], v[192:195], v[102:105]
	v_mfma_f32_16x16x32_bf16 v[98:101], v[152:155], v[192:195], v[98:101]
	v_mfma_f32_16x16x32_bf16 v[86:89], v[144:147], v[200:203], v[86:89]
	v_mfma_f32_16x16x32_bf16 v[82:85], v[152:155], v[200:203], v[82:85]
	v_mfma_f32_16x16x32_bf16 v[126:129], v[148:151], v[180:183], v[126:129]
	v_mfma_f32_16x16x32_bf16 v[122:125], v[156:159], v[180:183], v[122:125]
	v_mfma_f32_16x16x32_bf16 v[118:121], v[148:151], v[188:191], v[118:121]
	v_mfma_f32_16x16x32_bf16 v[114:117], v[156:159], v[188:191], v[114:117]
	v_mfma_f32_16x16x32_bf16 v[102:105], v[148:151], v[196:199], v[102:105]
	v_mfma_f32_16x16x32_bf16 v[98:101], v[156:159], v[196:199], v[98:101]
	v_mfma_f32_16x16x32_bf16 v[86:89], v[148:151], v[204:207], v[86:89]
	v_mfma_f32_16x16x32_bf16 v[82:85], v[156:159], v[204:207], v[82:85]
	s_setprio 0
	s_setprio 1
	v_mfma_f32_16x16x32_bf16 v[110:113], v[160:163], v[176:179], v[110:113]
	v_mfma_f32_16x16x32_bf16 v[106:109], v[168:171], v[176:179], v[106:109]
	v_mfma_f32_16x16x32_bf16 v[94:97], v[160:163], v[184:187], v[94:97]
	v_mfma_f32_16x16x32_bf16 v[90:93], v[168:171], v[184:187], v[90:93]
	v_mfma_f32_16x16x32_bf16 v[78:81], v[160:163], v[192:195], v[78:81]
	v_mfma_f32_16x16x32_bf16 v[74:77], v[168:171], v[192:195], v[74:77]
	v_mfma_f32_16x16x32_bf16 v[70:73], v[160:163], v[200:203], v[70:73]
	v_mfma_f32_16x16x32_bf16 v[66:69], v[168:171], v[200:203], v[66:69]
	v_mfma_f32_16x16x32_bf16 v[110:113], v[164:167], v[180:183], v[110:113]
	v_mfma_f32_16x16x32_bf16 v[106:109], v[172:175], v[180:183], v[106:109]
	v_mfma_f32_16x16x32_bf16 v[94:97], v[164:167], v[188:191], v[94:97]
	v_mfma_f32_16x16x32_bf16 v[90:93], v[172:175], v[188:191], v[90:93]
	v_mfma_f32_16x16x32_bf16 v[78:81], v[164:167], v[196:199], v[78:81]
	v_mfma_f32_16x16x32_bf16 v[74:77], v[172:175], v[196:199], v[74:77]
	v_mfma_f32_16x16x32_bf16 v[70:73], v[164:167], v[204:207], v[70:73]
	v_mfma_f32_16x16x32_bf16 v[66:69], v[172:175], v[204:207], v[66:69]
	s_barrier
	s_setprio 0
	s_add_i32 s20, s54, s37
	v_lshl_add_u64 v[208:209], v[208:209], 0, s[2:3]
	s_mov_b32 m0, s20
	ds_read_b128 v[176:179], v143 offset:49152
	ds_read_b128 v[180:183], v143 offset:50176
	ds_read_b128 v[184:187], v143 offset:51200
	ds_read_b128 v[188:191], v143 offset:52224
	ds_read_b128 v[192:195], v143 offset:53248
	ds_read_b128 v[196:199], v143 offset:54272
	ds_read_b128 v[200:203], v143 offset:55296
	ds_read_b128 v[204:207], v143 offset:56320
	global_load_lds_dwordx4 v[208:209], off
	s_add_i32 m0, s20, 0x2000
	s_add_u32 s18, s18, 0x80080
	v_lshl_add_u64 v[208:209], v[220:221], 0, s[2:3]
	s_addc_u32 s19, s19, 0
	s_add_i32 s20, s55, s37
	global_load_lds_dwordx4 v[208:209], off
	v_lshl_add_u64 v[208:209], s[18:19], 0, v[0:1]
	s_mov_b32 m0, s20
	s_nop 0
	global_load_lds_dwordx4 v[208:209], off
	v_lshl_add_u64 v[208:209], s[18:19], 0, v[130:131]
	s_add_i32 m0, s20, 0x2000
	s_nop 0
	global_load_lds_dwordx4 v[208:209], off
	v_lshl_add_u64 v[208:209], v[222:223], 0, s[2:3]
	s_mov_b32 m0, s45
	s_nop 0
	global_load_lds_dwordx4 v[208:209], off
	v_lshl_add_u64 v[208:209], v[224:225], 0, s[2:3]
	s_mov_b32 m0, s46
	s_nop 0
	global_load_lds_dwordx4 v[208:209], off
	s_waitcnt vmcnt(8)
	s_waitcnt lgkmcnt(0)
	s_setprio 1
	s_barrier
	v_mfma_f32_16x16x32_bf16 v[62:65], v[144:147], v[176:179], v[62:65]
	v_mfma_f32_16x16x32_bf16 v[58:61], v[152:155], v[176:179], v[58:61]
	v_mfma_f32_16x16x32_bf16 v[54:57], v[144:147], v[184:187], v[54:57]
	v_mfma_f32_16x16x32_bf16 v[50:53], v[152:155], v[184:187], v[50:53]
	v_mfma_f32_16x16x32_bf16 v[38:41], v[144:147], v[192:195], v[38:41]
	v_mfma_f32_16x16x32_bf16 v[34:37], v[152:155], v[192:195], v[34:37]
	v_mfma_f32_16x16x32_bf16 v[22:25], v[144:147], v[200:203], v[22:25]
	v_mfma_f32_16x16x32_bf16 v[18:21], v[152:155], v[200:203], v[18:21]
	v_mfma_f32_16x16x32_bf16 v[62:65], v[148:151], v[180:183], v[62:65]
	v_mfma_f32_16x16x32_bf16 v[58:61], v[156:159], v[180:183], v[58:61]
	v_mfma_f32_16x16x32_bf16 v[54:57], v[148:151], v[188:191], v[54:57]
	v_mfma_f32_16x16x32_bf16 v[50:53], v[156:159], v[188:191], v[50:53]
	v_mfma_f32_16x16x32_bf16 v[38:41], v[148:151], v[196:199], v[38:41]
	v_mfma_f32_16x16x32_bf16 v[34:37], v[156:159], v[196:199], v[34:37]
	v_mfma_f32_16x16x32_bf16 v[22:25], v[148:151], v[204:207], v[22:25]
	v_mfma_f32_16x16x32_bf16 v[18:21], v[156:159], v[204:207], v[18:21]
	s_setprio 0
	s_setprio 1
	v_mfma_f32_16x16x32_bf16 v[46:49], v[160:163], v[176:179], v[46:49]
	v_mfma_f32_16x16x32_bf16 v[42:45], v[168:171], v[176:179], v[42:45]
	v_mfma_f32_16x16x32_bf16 v[30:33], v[160:163], v[184:187], v[30:33]
	v_mfma_f32_16x16x32_bf16 v[26:29], v[168:171], v[184:187], v[26:29]
	v_mfma_f32_16x16x32_bf16 v[14:17], v[160:163], v[192:195], v[14:17]
	v_mfma_f32_16x16x32_bf16 v[10:13], v[168:171], v[192:195], v[10:13]
	v_mfma_f32_16x16x32_bf16 v[6:9], v[160:163], v[200:203], v[6:9]
	v_mfma_f32_16x16x32_bf16 v[2:5], v[168:171], v[200:203], v[2:5]
	v_mfma_f32_16x16x32_bf16 v[46:49], v[164:167], v[180:183], v[46:49]
	v_mfma_f32_16x16x32_bf16 v[42:45], v[172:175], v[180:183], v[42:45]
	v_mfma_f32_16x16x32_bf16 v[30:33], v[164:167], v[188:191], v[30:33]
	v_mfma_f32_16x16x32_bf16 v[26:29], v[172:175], v[188:191], v[26:29]
	v_mfma_f32_16x16x32_bf16 v[14:17], v[164:167], v[196:199], v[14:17]
	v_mfma_f32_16x16x32_bf16 v[10:13], v[172:175], v[196:199], v[10:13]
	v_mfma_f32_16x16x32_bf16 v[6:9], v[164:167], v[204:207], v[6:9]
	v_mfma_f32_16x16x32_bf16 v[2:5], v[172:175], v[204:207], v[2:5]
	s_barrier
	s_setprio 0
	s_add_i32 s53, s53, 2
	s_add_u32 s16, s16, 0x100
	s_addc_u32 s17, s17, 0
	s_add_u32 s51, s51, 0x100
	s_addc_u32 s52, s52, 0
	s_cmp_gt_u32 s53, 29
	s_cbranch_scc0 .LBB0_491

.LBB0_882:
	s_add_u32 s38, s22, 0x80080
	s_addc_u32 s39, s23, 0
	s_add_u32 s15, s42, 0x100
	s_addc_u32 s21, s43, 0
	s_mov_b32 s22, 0
	s_add_i32 s41, s22, 2
	s_add_u32 s42, s38, 0xfff80080
	s_addc_u32 s23, s39, -1
	s_add_i32 s44, 0, 0x10000
	s_cmp_eq_u32 s63, s22
	s_cselect_b32 s23, s17, s23
	s_cselect_b32 s22, s16, s42
	v_add_u32_e32 v0, s44, v224
	s_cselect_b32 s43, s19, s21
	s_cselect_b32 s42, s18, s15
	s_add_i32 s45, 0, 0x14000
	ds_read_b128 v[30:33], v0
	ds_read_b128 v[134:137], v0 offset:1024
	ds_read_b128 v[138:141], v0 offset:2048
	ds_read_b128 v[142:145], v0 offset:3072
	v_add_u32_e32 v0, s45, v224
	ds_read_b128 v[146:149], v0
	ds_read_b128 v[150:153], v0 offset:1024
	ds_read_b128 v[154:157], v0 offset:2048
	ds_read_b128 v[158:161], v0 offset:3072
	v_lshl_add_u64 v[206:207], s[38:39], 0, v[202:203]
	s_add_i32 m0, s52, 0xc000
	ds_read_b128 v[162:165], v225
	ds_read_b128 v[166:169], v225 offset:1024
	ds_read_b128 v[170:173], v225 offset:2048
	ds_read_b128 v[174:177], v225 offset:3072
	ds_read_b128 v[178:181], v225 offset:4096
	ds_read_b128 v[182:185], v225 offset:5120
	ds_read_b128 v[186:189], v225 offset:6144
	ds_read_b128 v[190:193], v225 offset:7168
	global_load_lds_dwordx4 v[206:207], off
	v_lshl_add_u64 v[206:207], s[38:39], 0, v[204:205]
	s_add_i32 m0, s52, 0xe000
	s_nop 0
	global_load_lds_dwordx4 v[206:207], off
	s_waitcnt vmcnt(8)
	s_waitcnt lgkmcnt(0)
	s_setprio 1
	s_barrier
	v_mfma_f32_16x16x32_bf16 v[26:29], v[30:33], v[162:165], 0
	v_mfma_f32_16x16x32_bf16 v[22:25], v[138:141], v[162:165], 0
	v_mfma_f32_16x16x32_bf16 v[62:65], v[30:33], v[170:173], 0
	v_mfma_f32_16x16x32_bf16 v[14:17], v[138:141], v[170:173], 0
	v_mfma_f32_16x16x32_bf16 v[58:61], v[30:33], v[178:181], 0
	v_mfma_f32_16x16x32_bf16 v[54:57], v[138:141], v[178:181], 0
	v_mfma_f32_16x16x32_bf16 v[94:97], v[30:33], v[186:189], 0
	v_mfma_f32_16x16x32_bf16 v[46:49], v[138:141], v[186:189], 0
	v_mfma_f32_16x16x32_bf16 v[26:29], v[134:137], v[166:169], v[26:29]
	v_mfma_f32_16x16x32_bf16 v[22:25], v[142:145], v[166:169], v[22:25]
	v_mfma_f32_16x16x32_bf16 v[62:65], v[134:137], v[174:177], v[62:65]
	v_mfma_f32_16x16x32_bf16 v[14:17], v[142:145], v[174:177], v[14:17]
	v_mfma_f32_16x16x32_bf16 v[58:61], v[134:137], v[182:185], v[58:61]
	v_mfma_f32_16x16x32_bf16 v[54:57], v[142:145], v[182:185], v[54:57]
	v_mfma_f32_16x16x32_bf16 v[94:97], v[134:137], v[190:193], v[94:97]
	v_mfma_f32_16x16x32_bf16 v[46:49], v[142:145], v[190:193], v[46:49]
	s_setprio 0
	s_setprio 1
	v_mfma_f32_16x16x32_bf16 v[18:21], v[146:149], v[162:165], 0
	v_mfma_f32_16x16x32_bf16 v[10:13], v[154:157], v[162:165], 0
	v_mfma_f32_16x16x32_bf16 v[2:5], v[146:149], v[170:173], 0
	v_mfma_f32_16x16x32_bf16 v[6:9], v[154:157], v[170:173], 0
	v_mfma_f32_16x16x32_bf16 v[50:53], v[146:149], v[178:181], 0
	v_mfma_f32_16x16x32_bf16 v[42:45], v[154:157], v[178:181], 0
	v_mfma_f32_16x16x32_bf16 v[34:37], v[146:149], v[186:189], 0
	v_mfma_f32_16x16x32_bf16 v[38:41], v[154:157], v[186:189], 0
	v_mfma_f32_16x16x32_bf16 v[18:21], v[150:153], v[166:169], v[18:21]
	v_mfma_f32_16x16x32_bf16 v[10:13], v[158:161], v[166:169], v[10:13]
	v_mfma_f32_16x16x32_bf16 v[2:5], v[150:153], v[174:177], v[2:5]
	v_mfma_f32_16x16x32_bf16 v[6:9], v[158:161], v[174:177], v[6:9]
	v_mfma_f32_16x16x32_bf16 v[50:53], v[150:153], v[182:185], v[50:53]
	v_mfma_f32_16x16x32_bf16 v[42:45], v[158:161], v[182:185], v[42:45]
	v_mfma_f32_16x16x32_bf16 v[34:37], v[150:153], v[190:193], v[34:37]
	v_mfma_f32_16x16x32_bf16 v[38:41], v[158:161], v[190:193], v[38:41]
	s_barrier
	s_setprio 0
	s_add_i32 s44, s44, s49
	v_lshl_add_u64 v[206:207], s[42:43], 0, v[196:197]
	s_mov_b32 m0, s44
	ds_read_b128 v[162:165], v225 offset:16384
	ds_read_b128 v[166:169], v225 offset:17408
	ds_read_b128 v[170:173], v225 offset:18432
	ds_read_b128 v[174:177], v225 offset:19456
	ds_read_b128 v[178:181], v225 offset:20480
	ds_read_b128 v[182:185], v225 offset:21504
	ds_read_b128 v[186:189], v225 offset:22528
	ds_read_b128 v[190:193], v225 offset:23552
	global_load_lds_dwordx4 v[206:207], off
	s_add_i32 m0, s44, 0x2000
	v_lshl_add_u64 v[208:209], s[42:43], 0, v[200:201]
	s_add_u32 s42, s42, s50
	s_addc_u32 s43, s43, 0
	s_add_i32 s44, s45, s49
	global_load_lds_dwordx4 v[208:209], off
	v_lshl_add_u64 v[220:221], s[42:43], 0, v[196:197]
	s_mov_b32 m0, s44
	v_lshl_add_u64 v[226:227], s[42:43], 0, v[200:201]
	global_load_lds_dwordx4 v[220:221], off
	s_add_i32 m0, s44, 0x2000
	v_lshl_add_u64 v[228:229], s[22:23], 0, v[194:195]
	global_load_lds_dwordx4 v[226:227], off
	s_mov_b32 m0, s52
	v_lshl_add_u64 v[230:231], s[22:23], 0, v[198:199]
	global_load_lds_dwordx4 v[228:229], off
	s_mov_b32 m0, s53
	s_nop 0
	global_load_lds_dwordx4 v[230:231], off
	s_waitcnt vmcnt(8)
	s_waitcnt lgkmcnt(0)
	s_setprio 1
	s_barrier
	v_mfma_f32_16x16x32_bf16 v[90:93], v[30:33], v[162:165], 0
	v_mfma_f32_16x16x32_bf16 v[86:89], v[138:141], v[162:165], 0
	v_mfma_f32_16x16x32_bf16 v[130:133], v[30:33], v[170:173], 0
	v_mfma_f32_16x16x32_bf16 v[78:81], v[138:141], v[170:173], 0
	v_mfma_f32_16x16x32_bf16 v[126:129], v[30:33], v[178:181], 0
	v_mfma_f32_16x16x32_bf16 v[118:121], v[138:141], v[178:181], 0
	v_mfma_f32_16x16x32_bf16 v[110:113], v[138:141], v[186:189], 0
	v_mfma_f32_16x16x32_bf16 v[90:93], v[134:137], v[166:169], v[90:93]
	v_mfma_f32_16x16x32_bf16 v[86:89], v[142:145], v[166:169], v[86:89]
	v_mfma_f32_16x16x32_bf16 v[130:133], v[134:137], v[174:177], v[130:133]
	v_mfma_f32_16x16x32_bf16 v[78:81], v[142:145], v[174:177], v[78:81]
	v_mfma_f32_16x16x32_bf16 v[126:129], v[134:137], v[182:185], v[126:129]
	v_mfma_f32_16x16x32_bf16 v[118:121], v[142:145], v[182:185], v[118:121]
	v_mfma_f32_16x16x32_bf16 v[30:33], v[30:33], v[186:189], 0
	v_mfma_f32_16x16x32_bf16 v[110:113], v[142:145], v[190:193], v[110:113]
	v_mfma_f32_16x16x32_bf16 v[30:33], v[134:137], v[190:193], v[30:33]
	s_setprio 0
	s_setprio 1
	v_mfma_f32_16x16x32_bf16 v[82:85], v[146:149], v[162:165], 0
	v_mfma_f32_16x16x32_bf16 v[74:77], v[154:157], v[162:165], 0
	v_mfma_f32_16x16x32_bf16 v[66:69], v[146:149], v[170:173], 0
	v_mfma_f32_16x16x32_bf16 v[70:73], v[154:157], v[170:173], 0
	v_mfma_f32_16x16x32_bf16 v[114:117], v[146:149], v[178:181], 0
	v_mfma_f32_16x16x32_bf16 v[106:109], v[154:157], v[178:181], 0
	v_mfma_f32_16x16x32_bf16 v[98:101], v[146:149], v[186:189], 0
	v_mfma_f32_16x16x32_bf16 v[102:105], v[154:157], v[186:189], 0
	v_mfma_f32_16x16x32_bf16 v[82:85], v[150:153], v[166:169], v[82:85]
	v_mfma_f32_16x16x32_bf16 v[74:77], v[158:161], v[166:169], v[74:77]
	v_mfma_f32_16x16x32_bf16 v[66:69], v[150:153], v[174:177], v[66:69]
	v_mfma_f32_16x16x32_bf16 v[70:73], v[158:161], v[174:177], v[70:73]
	v_mfma_f32_16x16x32_bf16 v[114:117], v[150:153], v[182:185], v[114:117]
	v_mfma_f32_16x16x32_bf16 v[106:109], v[158:161], v[182:185], v[106:109]
	v_mfma_f32_16x16x32_bf16 v[98:101], v[150:153], v[190:193], v[98:101]
	v_mfma_f32_16x16x32_bf16 v[102:105], v[158:161], v[190:193], v[102:105]
	s_barrier
	s_setprio 0
	s_add_i32 s42, 0, 0x18000
	v_add_u32_e32 v0, s42, v224
	s_add_i32 s43, 0, 0x1c000
	ds_read_b128 v[122:125], v0
	ds_read_b128 v[134:137], v0 offset:1024
	ds_read_b128 v[138:141], v0 offset:2048
	ds_read_b128 v[142:145], v0 offset:3072
	v_add_u32_e32 v0, s43, v224
	ds_read_b128 v[146:149], v0
	ds_read_b128 v[150:153], v0 offset:1024
	ds_read_b128 v[154:157], v0 offset:2048
	ds_read_b128 v[158:161], v0 offset:3072
	s_add_u32 s22, s22, 0x80000
	s_addc_u32 s23, s23, 0
	s_mov_b32 m0, s54
	v_lshl_add_u64 v[232:233], s[22:23], 0, v[194:195]
	ds_read_b128 v[162:165], v225 offset:32768
	ds_read_b128 v[166:169], v225 offset:33792
	ds_read_b128 v[170:173], v225 offset:34816
	ds_read_b128 v[174:177], v225 offset:35840
	ds_read_b128 v[178:181], v225 offset:36864
	ds_read_b128 v[182:185], v225 offset:37888
	ds_read_b128 v[186:189], v225 offset:38912
	ds_read_b128 v[190:193], v225 offset:39936
	global_load_lds_dwordx4 v[232:233], off
	v_lshl_add_u64 v[232:233], s[22:23], 0, v[198:199]
	s_mov_b32 m0, s55
	s_nop 0
	global_load_lds_dwordx4 v[232:233], off
	s_waitcnt vmcnt(8)
	s_waitcnt lgkmcnt(0)
	s_setprio 1
	s_barrier
	v_mfma_f32_16x16x32_bf16 v[26:29], v[122:125], v[162:165], v[26:29]
	v_mfma_f32_16x16x32_bf16 v[22:25], v[138:141], v[162:165], v[22:25]
	v_mfma_f32_16x16x32_bf16 v[62:65], v[122:125], v[170:173], v[62:65]
	v_mfma_f32_16x16x32_bf16 v[14:17], v[138:141], v[170:173], v[14:17]
	v_mfma_f32_16x16x32_bf16 v[58:61], v[122:125], v[178:181], v[58:61]
	v_mfma_f32_16x16x32_bf16 v[54:57], v[138:141], v[178:181], v[54:57]
	v_mfma_f32_16x16x32_bf16 v[94:97], v[122:125], v[186:189], v[94:97]
	v_mfma_f32_16x16x32_bf16 v[46:49], v[138:141], v[186:189], v[46:49]
	v_mfma_f32_16x16x32_bf16 v[26:29], v[134:137], v[166:169], v[26:29]
	v_mfma_f32_16x16x32_bf16 v[22:25], v[142:145], v[166:169], v[22:25]
	v_mfma_f32_16x16x32_bf16 v[62:65], v[134:137], v[174:177], v[62:65]
	v_mfma_f32_16x16x32_bf16 v[14:17], v[142:145], v[174:177], v[14:17]
	v_mfma_f32_16x16x32_bf16 v[58:61], v[134:137], v[182:185], v[58:61]
	v_mfma_f32_16x16x32_bf16 v[54:57], v[142:145], v[182:185], v[54:57]
	v_mfma_f32_16x16x32_bf16 v[94:97], v[134:137], v[190:193], v[94:97]
	v_mfma_f32_16x16x32_bf16 v[46:49], v[142:145], v[190:193], v[46:49]
	s_setprio 0
	s_setprio 1
	v_mfma_f32_16x16x32_bf16 v[18:21], v[146:149], v[162:165], v[18:21]
	v_mfma_f32_16x16x32_bf16 v[10:13], v[154:157], v[162:165], v[10:13]
	v_mfma_f32_16x16x32_bf16 v[2:5], v[146:149], v[170:173], v[2:5]
	v_mfma_f32_16x16x32_bf16 v[6:9], v[154:157], v[170:173], v[6:9]
	v_mfma_f32_16x16x32_bf16 v[50:53], v[146:149], v[178:181], v[50:53]
	v_mfma_f32_16x16x32_bf16 v[42:45], v[154:157], v[178:181], v[42:45]
	v_mfma_f32_16x16x32_bf16 v[34:37], v[146:149], v[186:189], v[34:37]
	v_mfma_f32_16x16x32_bf16 v[38:41], v[154:157], v[186:189], v[38:41]
	v_mfma_f32_16x16x32_bf16 v[18:21], v[150:153], v[166:169], v[18:21]
	v_mfma_f32_16x16x32_bf16 v[10:13], v[158:161], v[166:169], v[10:13]
	v_mfma_f32_16x16x32_bf16 v[2:5], v[150:153], v[174:177], v[2:5]
	v_mfma_f32_16x16x32_bf16 v[6:9], v[158:161], v[174:177], v[6:9]
	v_mfma_f32_16x16x32_bf16 v[50:53], v[150:153], v[182:185], v[50:53]
	v_mfma_f32_16x16x32_bf16 v[42:45], v[158:161], v[182:185], v[42:45]
	v_mfma_f32_16x16x32_bf16 v[34:37], v[150:153], v[190:193], v[34:37]
	v_mfma_f32_16x16x32_bf16 v[38:41], v[158:161], v[190:193], v[38:41]
	s_barrier
	s_setprio 0
	s_add_i32 s22, s42, s49
	v_lshl_add_u64 v[206:207], v[206:207], 0, s[2:3]
	s_mov_b32 m0, s22
	ds_read_b128 v[162:165], v225 offset:49152
	ds_read_b128 v[166:169], v225 offset:50176
	ds_read_b128 v[170:173], v225 offset:51200
	ds_read_b128 v[174:177], v225 offset:52224
	ds_read_b128 v[178:181], v225 offset:53248
	ds_read_b128 v[182:185], v225 offset:54272
	ds_read_b128 v[186:189], v225 offset:55296
	ds_read_b128 v[190:193], v225 offset:56320
	global_load_lds_dwordx4 v[206:207], off
	v_lshl_add_u64 v[206:207], v[208:209], 0, s[2:3]
	s_add_i32 m0, s22, 0x2000
	s_add_i32 s22, s43, s49
	global_load_lds_dwordx4 v[206:207], off
	v_lshl_add_u64 v[206:207], v[220:221], 0, s[2:3]
	s_mov_b32 m0, s22
	s_nop 0
	global_load_lds_dwordx4 v[206:207], off
	v_lshl_add_u64 v[206:207], v[226:227], 0, s[2:3]
	s_add_i32 m0, s22, 0x2000
	s_nop 0
	global_load_lds_dwordx4 v[206:207], off
	v_lshl_add_u64 v[206:207], v[228:229], 0, s[2:3]
	s_mov_b32 m0, s61
	s_nop 0
	global_load_lds_dwordx4 v[206:207], off
	v_lshl_add_u64 v[206:207], v[230:231], 0, s[2:3]
	s_mov_b32 m0, s62
	s_nop 0
	global_load_lds_dwordx4 v[206:207], off
	s_waitcnt vmcnt(8)
	s_waitcnt lgkmcnt(0)
	s_setprio 1
	s_barrier
	v_mfma_f32_16x16x32_bf16 v[30:33], v[122:125], v[186:189], v[30:33]
	v_mfma_f32_16x16x32_bf16 v[90:93], v[122:125], v[162:165], v[90:93]
	v_mfma_f32_16x16x32_bf16 v[86:89], v[138:141], v[162:165], v[86:89]
	v_mfma_f32_16x16x32_bf16 v[130:133], v[122:125], v[170:173], v[130:133]
	v_mfma_f32_16x16x32_bf16 v[78:81], v[138:141], v[170:173], v[78:81]
	v_mfma_f32_16x16x32_bf16 v[126:129], v[122:125], v[178:181], v[126:129]
	v_mfma_f32_16x16x32_bf16 v[118:121], v[138:141], v[178:181], v[118:121]
	v_mfma_f32_16x16x32_bf16 v[122:125], v[134:137], v[190:193], v[30:33]
	v_mfma_f32_16x16x32_bf16 v[30:33], v[138:141], v[186:189], v[110:113]
	v_mfma_f32_16x16x32_bf16 v[90:93], v[134:137], v[166:169], v[90:93]
	v_mfma_f32_16x16x32_bf16 v[86:89], v[142:145], v[166:169], v[86:89]
	v_mfma_f32_16x16x32_bf16 v[130:133], v[134:137], v[174:177], v[130:133]
	v_mfma_f32_16x16x32_bf16 v[78:81], v[142:145], v[174:177], v[78:81]
	v_mfma_f32_16x16x32_bf16 v[126:129], v[134:137], v[182:185], v[126:129]
	v_mfma_f32_16x16x32_bf16 v[118:121], v[142:145], v[182:185], v[118:121]
	v_mfma_f32_16x16x32_bf16 v[110:113], v[142:145], v[190:193], v[30:33]
	s_setprio 0
	s_setprio 1
	v_mfma_f32_16x16x32_bf16 v[30:33], v[146:149], v[162:165], v[82:85]
	v_mfma_f32_16x16x32_bf16 v[82:85], v[150:153], v[166:169], v[30:33]
	v_mfma_f32_16x16x32_bf16 v[30:33], v[154:157], v[162:165], v[74:77]
	v_mfma_f32_16x16x32_bf16 v[74:77], v[158:161], v[166:169], v[30:33]
	v_mfma_f32_16x16x32_bf16 v[30:33], v[146:149], v[170:173], v[66:69]
	v_mfma_f32_16x16x32_bf16 v[66:69], v[150:153], v[174:177], v[30:33]
	v_mfma_f32_16x16x32_bf16 v[30:33], v[154:157], v[170:173], v[70:73]
	v_mfma_f32_16x16x32_bf16 v[70:73], v[158:161], v[174:177], v[30:33]
	v_mfma_f32_16x16x32_bf16 v[30:33], v[146:149], v[178:181], v[114:117]
	v_mfma_f32_16x16x32_bf16 v[114:117], v[150:153], v[182:185], v[30:33]
	v_mfma_f32_16x16x32_bf16 v[30:33], v[154:157], v[178:181], v[106:109]
	v_mfma_f32_16x16x32_bf16 v[106:109], v[158:161], v[182:185], v[30:33]
	v_mfma_f32_16x16x32_bf16 v[30:33], v[146:149], v[186:189], v[98:101]
	v_mfma_f32_16x16x32_bf16 v[98:101], v[150:153], v[190:193], v[30:33]
	v_mfma_f32_16x16x32_bf16 v[30:33], v[154:157], v[186:189], v[102:105]
	v_mfma_f32_16x16x32_bf16 v[102:105], v[158:161], v[190:193], v[30:33]
	s_barrier
	s_setprio 0
	s_add_u32 s38, s38, 0x100
	s_addc_u32 s39, s39, 0
	s_add_u32 s15, s15, 0x100
	s_addc_u32 s21, s21, 0
	s_cmp_ge_u32 s41, s56
	s_mov_b32 s22, s41
	s_cbranch_scc1 .Lpeel_done_1
.LBB0_883:
	s_add_i32 s41, s22, 2
	s_add_u32 s42, s38, 0xfff80080
	s_addc_u32 s23, s39, -1
	s_add_i32 s44, 0, 0x10000
	s_cmp_eq_u32 s63, s22
	s_cselect_b32 s23, s17, s23
	s_cselect_b32 s22, s16, s42
	v_add_u32_e32 v0, s44, v224
	s_cselect_b32 s43, s19, s21
	s_cselect_b32 s42, s18, s15
	s_add_i32 s45, 0, 0x14000
	ds_read_b128 v[30:33], v0
	ds_read_b128 v[134:137], v0 offset:1024
	ds_read_b128 v[138:141], v0 offset:2048
	ds_read_b128 v[142:145], v0 offset:3072
	v_add_u32_e32 v0, s45, v224
	ds_read_b128 v[146:149], v0
	ds_read_b128 v[150:153], v0 offset:1024
	ds_read_b128 v[154:157], v0 offset:2048
	ds_read_b128 v[158:161], v0 offset:3072
	v_lshl_add_u64 v[206:207], s[38:39], 0, v[202:203]
	s_add_i32 m0, s52, 0xc000
	ds_read_b128 v[162:165], v225
	ds_read_b128 v[166:169], v225 offset:1024
	ds_read_b128 v[170:173], v225 offset:2048
	ds_read_b128 v[174:177], v225 offset:3072
	ds_read_b128 v[178:181], v225 offset:4096
	ds_read_b128 v[182:185], v225 offset:5120
	ds_read_b128 v[186:189], v225 offset:6144
	ds_read_b128 v[190:193], v225 offset:7168
	global_load_lds_dwordx4 v[206:207], off
	v_lshl_add_u64 v[206:207], s[38:39], 0, v[204:205]
	s_add_i32 m0, s52, 0xe000
	s_nop 0
	global_load_lds_dwordx4 v[206:207], off
	s_waitcnt vmcnt(8)
	s_waitcnt lgkmcnt(0)
	s_setprio 1
	s_barrier
	v_mfma_f32_16x16x32_bf16 v[26:29], v[30:33], v[162:165], v[26:29]
	v_mfma_f32_16x16x32_bf16 v[22:25], v[138:141], v[162:165], v[22:25]
	v_mfma_f32_16x16x32_bf16 v[62:65], v[30:33], v[170:173], v[62:65]
	v_mfma_f32_16x16x32_bf16 v[14:17], v[138:141], v[170:173], v[14:17]
	v_mfma_f32_16x16x32_bf16 v[58:61], v[30:33], v[178:181], v[58:61]
	v_mfma_f32_16x16x32_bf16 v[54:57], v[138:141], v[178:181], v[54:57]
	v_mfma_f32_16x16x32_bf16 v[94:97], v[30:33], v[186:189], v[94:97]
	v_mfma_f32_16x16x32_bf16 v[46:49], v[138:141], v[186:189], v[46:49]
	v_mfma_f32_16x16x32_bf16 v[26:29], v[134:137], v[166:169], v[26:29]
	v_mfma_f32_16x16x32_bf16 v[22:25], v[142:145], v[166:169], v[22:25]
	v_mfma_f32_16x16x32_bf16 v[62:65], v[134:137], v[174:177], v[62:65]
	v_mfma_f32_16x16x32_bf16 v[14:17], v[142:145], v[174:177], v[14:17]
	v_mfma_f32_16x16x32_bf16 v[58:61], v[134:137], v[182:185], v[58:61]
	v_mfma_f32_16x16x32_bf16 v[54:57], v[142:145], v[182:185], v[54:57]
	v_mfma_f32_16x16x32_bf16 v[94:97], v[134:137], v[190:193], v[94:97]
	v_mfma_f32_16x16x32_bf16 v[46:49], v[142:145], v[190:193], v[46:49]
	s_setprio 0
	s_setprio 1
	v_mfma_f32_16x16x32_bf16 v[18:21], v[146:149], v[162:165], v[18:21]
	v_mfma_f32_16x16x32_bf16 v[10:13], v[154:157], v[162:165], v[10:13]
	v_mfma_f32_16x16x32_bf16 v[2:5], v[146:149], v[170:173], v[2:5]
	v_mfma_f32_16x16x32_bf16 v[6:9], v[154:157], v[170:173], v[6:9]
	v_mfma_f32_16x16x32_bf16 v[50:53], v[146:149], v[178:181], v[50:53]
	v_mfma_f32_16x16x32_bf16 v[42:45], v[154:157], v[178:181], v[42:45]
	v_mfma_f32_16x16x32_bf16 v[34:37], v[146:149], v[186:189], v[34:37]
	v_mfma_f32_16x16x32_bf16 v[38:41], v[154:157], v[186:189], v[38:41]
	v_mfma_f32_16x16x32_bf16 v[18:21], v[150:153], v[166:169], v[18:21]
	v_mfma_f32_16x16x32_bf16 v[10:13], v[158:161], v[166:169], v[10:13]
	v_mfma_f32_16x16x32_bf16 v[2:5], v[150:153], v[174:177], v[2:5]
	v_mfma_f32_16x16x32_bf16 v[6:9], v[158:161], v[174:177], v[6:9]
	v_mfma_f32_16x16x32_bf16 v[50:53], v[150:153], v[182:185], v[50:53]
	v_mfma_f32_16x16x32_bf16 v[42:45], v[158:161], v[182:185], v[42:45]
	v_mfma_f32_16x16x32_bf16 v[34:37], v[150:153], v[190:193], v[34:37]
	v_mfma_f32_16x16x32_bf16 v[38:41], v[158:161], v[190:193], v[38:41]
	s_barrier
	s_setprio 0
	s_add_i32 s44, s44, s49
	v_lshl_add_u64 v[206:207], s[42:43], 0, v[196:197]
	s_mov_b32 m0, s44
	ds_read_b128 v[162:165], v225 offset:16384
	ds_read_b128 v[166:169], v225 offset:17408
	ds_read_b128 v[170:173], v225 offset:18432
	ds_read_b128 v[174:177], v225 offset:19456
	ds_read_b128 v[178:181], v225 offset:20480
	ds_read_b128 v[182:185], v225 offset:21504
	ds_read_b128 v[186:189], v225 offset:22528
	ds_read_b128 v[190:193], v225 offset:23552
	global_load_lds_dwordx4 v[206:207], off
	s_add_i32 m0, s44, 0x2000
	v_lshl_add_u64 v[208:209], s[42:43], 0, v[200:201]
	s_add_u32 s42, s42, s50
	s_addc_u32 s43, s43, 0
	s_add_i32 s44, s45, s49
	global_load_lds_dwordx4 v[208:209], off
	v_lshl_add_u64 v[220:221], s[42:43], 0, v[196:197]
	s_mov_b32 m0, s44
	v_lshl_add_u64 v[226:227], s[42:43], 0, v[200:201]
	global_load_lds_dwordx4 v[220:221], off
	s_add_i32 m0, s44, 0x2000
	v_lshl_add_u64 v[228:229], s[22:23], 0, v[194:195]
	global_load_lds_dwordx4 v[226:227], off
	s_mov_b32 m0, s52
	v_lshl_add_u64 v[230:231], s[22:23], 0, v[198:199]
	global_load_lds_dwordx4 v[228:229], off
	s_mov_b32 m0, s53
	s_nop 0
	global_load_lds_dwordx4 v[230:231], off
	s_waitcnt vmcnt(8)
	s_waitcnt lgkmcnt(0)
	s_setprio 1
	s_barrier
	v_mfma_f32_16x16x32_bf16 v[90:93], v[30:33], v[162:165], v[90:93]
	v_mfma_f32_16x16x32_bf16 v[86:89], v[138:141], v[162:165], v[86:89]
	v_mfma_f32_16x16x32_bf16 v[130:133], v[30:33], v[170:173], v[130:133]
	v_mfma_f32_16x16x32_bf16 v[78:81], v[138:141], v[170:173], v[78:81]
	v_mfma_f32_16x16x32_bf16 v[126:129], v[30:33], v[178:181], v[126:129]
	v_mfma_f32_16x16x32_bf16 v[118:121], v[138:141], v[178:181], v[118:121]
	v_mfma_f32_16x16x32_bf16 v[110:113], v[138:141], v[186:189], v[110:113]
	v_mfma_f32_16x16x32_bf16 v[90:93], v[134:137], v[166:169], v[90:93]
	v_mfma_f32_16x16x32_bf16 v[86:89], v[142:145], v[166:169], v[86:89]
	v_mfma_f32_16x16x32_bf16 v[130:133], v[134:137], v[174:177], v[130:133]
	v_mfma_f32_16x16x32_bf16 v[78:81], v[142:145], v[174:177], v[78:81]
	v_mfma_f32_16x16x32_bf16 v[126:129], v[134:137], v[182:185], v[126:129]
	v_mfma_f32_16x16x32_bf16 v[118:121], v[142:145], v[182:185], v[118:121]
	v_mfma_f32_16x16x32_bf16 v[30:33], v[30:33], v[186:189], v[122:125]
	v_mfma_f32_16x16x32_bf16 v[110:113], v[142:145], v[190:193], v[110:113]
	v_mfma_f32_16x16x32_bf16 v[30:33], v[134:137], v[190:193], v[30:33]
	s_setprio 0
	s_setprio 1
	v_mfma_f32_16x16x32_bf16 v[82:85], v[146:149], v[162:165], v[82:85]
	v_mfma_f32_16x16x32_bf16 v[74:77], v[154:157], v[162:165], v[74:77]
	v_mfma_f32_16x16x32_bf16 v[66:69], v[146:149], v[170:173], v[66:69]
	v_mfma_f32_16x16x32_bf16 v[70:73], v[154:157], v[170:173], v[70:73]
	v_mfma_f32_16x16x32_bf16 v[114:117], v[146:149], v[178:181], v[114:117]
	v_mfma_f32_16x16x32_bf16 v[106:109], v[154:157], v[178:181], v[106:109]
	v_mfma_f32_16x16x32_bf16 v[98:101], v[146:149], v[186:189], v[98:101]
	v_mfma_f32_16x16x32_bf16 v[102:105], v[154:157], v[186:189], v[102:105]
	v_mfma_f32_16x16x32_bf16 v[82:85], v[150:153], v[166:169], v[82:85]
	v_mfma_f32_16x16x32_bf16 v[74:77], v[158:161], v[166:169], v[74:77]
	v_mfma_f32_16x16x32_bf16 v[66:69], v[150:153], v[174:177], v[66:69]
	v_mfma_f32_16x16x32_bf16 v[70:73], v[158:161], v[174:177], v[70:73]
	v_mfma_f32_16x16x32_bf16 v[114:117], v[150:153], v[182:185], v[114:117]
	v_mfma_f32_16x16x32_bf16 v[106:109], v[158:161], v[182:185], v[106:109]
	v_mfma_f32_16x16x32_bf16 v[98:101], v[150:153], v[190:193], v[98:101]
	v_mfma_f32_16x16x32_bf16 v[102:105], v[158:161], v[190:193], v[102:105]
	s_barrier
	s_setprio 0
	s_add_i32 s42, 0, 0x18000
	v_add_u32_e32 v0, s42, v224
	s_add_i32 s43, 0, 0x1c000
	ds_read_b128 v[122:125], v0
	ds_read_b128 v[134:137], v0 offset:1024
	ds_read_b128 v[138:141], v0 offset:2048
	ds_read_b128 v[142:145], v0 offset:3072
	v_add_u32_e32 v0, s43, v224
	ds_read_b128 v[146:149], v0
	ds_read_b128 v[150:153], v0 offset:1024
	ds_read_b128 v[154:157], v0 offset:2048
	ds_read_b128 v[158:161], v0 offset:3072
	s_add_u32 s22, s22, 0x80000
	s_addc_u32 s23, s23, 0
	s_mov_b32 m0, s54
	v_lshl_add_u64 v[232:233], s[22:23], 0, v[194:195]
	ds_read_b128 v[162:165], v225 offset:32768
	ds_read_b128 v[166:169], v225 offset:33792
	ds_read_b128 v[170:173], v225 offset:34816
	ds_read_b128 v[174:177], v225 offset:35840
	ds_read_b128 v[178:181], v225 offset:36864
	ds_read_b128 v[182:185], v225 offset:37888
	ds_read_b128 v[186:189], v225 offset:38912
	ds_read_b128 v[190:193], v225 offset:39936
	global_load_lds_dwordx4 v[232:233], off
	v_lshl_add_u64 v[232:233], s[22:23], 0, v[198:199]
	s_mov_b32 m0, s55
	s_nop 0
	global_load_lds_dwordx4 v[232:233], off
	s_waitcnt vmcnt(8)
	s_waitcnt lgkmcnt(0)
	s_setprio 1
	s_barrier
	v_mfma_f32_16x16x32_bf16 v[26:29], v[122:125], v[162:165], v[26:29]
	v_mfma_f32_16x16x32_bf16 v[22:25], v[138:141], v[162:165], v[22:25]
	v_mfma_f32_16x16x32_bf16 v[62:65], v[122:125], v[170:173], v[62:65]
	v_mfma_f32_16x16x32_bf16 v[14:17], v[138:141], v[170:173], v[14:17]
	v_mfma_f32_16x16x32_bf16 v[58:61], v[122:125], v[178:181], v[58:61]
	v_mfma_f32_16x16x32_bf16 v[54:57], v[138:141], v[178:181], v[54:57]
	v_mfma_f32_16x16x32_bf16 v[94:97], v[122:125], v[186:189], v[94:97]
	v_mfma_f32_16x16x32_bf16 v[46:49], v[138:141], v[186:189], v[46:49]
	v_mfma_f32_16x16x32_bf16 v[26:29], v[134:137], v[166:169], v[26:29]
	v_mfma_f32_16x16x32_bf16 v[22:25], v[142:145], v[166:169], v[22:25]
	v_mfma_f32_16x16x32_bf16 v[62:65], v[134:137], v[174:177], v[62:65]
	v_mfma_f32_16x16x32_bf16 v[14:17], v[142:145], v[174:177], v[14:17]
	v_mfma_f32_16x16x32_bf16 v[58:61], v[134:137], v[182:185], v[58:61]
	v_mfma_f32_16x16x32_bf16 v[54:57], v[142:145], v[182:185], v[54:57]
	v_mfma_f32_16x16x32_bf16 v[94:97], v[134:137], v[190:193], v[94:97]
	v_mfma_f32_16x16x32_bf16 v[46:49], v[142:145], v[190:193], v[46:49]
	s_setprio 0
	s_setprio 1
	v_mfma_f32_16x16x32_bf16 v[18:21], v[146:149], v[162:165], v[18:21]
	v_mfma_f32_16x16x32_bf16 v[10:13], v[154:157], v[162:165], v[10:13]
	v_mfma_f32_16x16x32_bf16 v[2:5], v[146:149], v[170:173], v[2:5]
	v_mfma_f32_16x16x32_bf16 v[6:9], v[154:157], v[170:173], v[6:9]
	v_mfma_f32_16x16x32_bf16 v[50:53], v[146:149], v[178:181], v[50:53]
	v_mfma_f32_16x16x32_bf16 v[42:45], v[154:157], v[178:181], v[42:45]
	v_mfma_f32_16x16x32_bf16 v[34:37], v[146:149], v[186:189], v[34:37]
	v_mfma_f32_16x16x32_bf16 v[38:41], v[154:157], v[186:189], v[38:41]
	v_mfma_f32_16x16x32_bf16 v[18:21], v[150:153], v[166:169], v[18:21]
	v_mfma_f32_16x16x32_bf16 v[10:13], v[158:161], v[166:169], v[10:13]
	v_mfma_f32_16x16x32_bf16 v[2:5], v[150:153], v[174:177], v[2:5]
	v_mfma_f32_16x16x32_bf16 v[6:9], v[158:161], v[174:177], v[6:9]
	v_mfma_f32_16x16x32_bf16 v[50:53], v[150:153], v[182:185], v[50:53]
	v_mfma_f32_16x16x32_bf16 v[42:45], v[158:161], v[182:185], v[42:45]
	v_mfma_f32_16x16x32_bf16 v[34:37], v[150:153], v[190:193], v[34:37]
	v_mfma_f32_16x16x32_bf16 v[38:41], v[158:161], v[190:193], v[38:41]
	s_barrier
	s_setprio 0
	s_add_i32 s22, s42, s49
	v_lshl_add_u64 v[206:207], v[206:207], 0, s[2:3]
	s_mov_b32 m0, s22
	ds_read_b128 v[162:165], v225 offset:49152
	ds_read_b128 v[166:169], v225 offset:50176
	ds_read_b128 v[170:173], v225 offset:51200
	ds_read_b128 v[174:177], v225 offset:52224
	ds_read_b128 v[178:181], v225 offset:53248
	ds_read_b128 v[182:185], v225 offset:54272
	ds_read_b128 v[186:189], v225 offset:55296
	ds_read_b128 v[190:193], v225 offset:56320
	global_load_lds_dwordx4 v[206:207], off
	v_lshl_add_u64 v[206:207], v[208:209], 0, s[2:3]
	s_add_i32 m0, s22, 0x2000
	s_add_i32 s22, s43, s49
	global_load_lds_dwordx4 v[206:207], off
	v_lshl_add_u64 v[206:207], v[220:221], 0, s[2:3]
	s_mov_b32 m0, s22
	s_nop 0
	global_load_lds_dwordx4 v[206:207], off
	v_lshl_add_u64 v[206:207], v[226:227], 0, s[2:3]
	s_add_i32 m0, s22, 0x2000
	s_nop 0
	global_load_lds_dwordx4 v[206:207], off
	v_lshl_add_u64 v[206:207], v[228:229], 0, s[2:3]
	s_mov_b32 m0, s61
	s_nop 0
	global_load_lds_dwordx4 v[206:207], off
	v_lshl_add_u64 v[206:207], v[230:231], 0, s[2:3]
	s_mov_b32 m0, s62
	s_nop 0
	global_load_lds_dwordx4 v[206:207], off
	s_waitcnt vmcnt(8)
	s_waitcnt lgkmcnt(0)
	s_setprio 1
	s_barrier
	v_mfma_f32_16x16x32_bf16 v[30:33], v[122:125], v[186:189], v[30:33]
	v_mfma_f32_16x16x32_bf16 v[90:93], v[122:125], v[162:165], v[90:93]
	v_mfma_f32_16x16x32_bf16 v[86:89], v[138:141], v[162:165], v[86:89]
	v_mfma_f32_16x16x32_bf16 v[130:133], v[122:125], v[170:173], v[130:133]
	v_mfma_f32_16x16x32_bf16 v[78:81], v[138:141], v[170:173], v[78:81]
	v_mfma_f32_16x16x32_bf16 v[126:129], v[122:125], v[178:181], v[126:129]
	v_mfma_f32_16x16x32_bf16 v[118:121], v[138:141], v[178:181], v[118:121]
	v_mfma_f32_16x16x32_bf16 v[122:125], v[134:137], v[190:193], v[30:33]
	v_mfma_f32_16x16x32_bf16 v[30:33], v[138:141], v[186:189], v[110:113]
	v_mfma_f32_16x16x32_bf16 v[90:93], v[134:137], v[166:169], v[90:93]
	v_mfma_f32_16x16x32_bf16 v[86:89], v[142:145], v[166:169], v[86:89]
	v_mfma_f32_16x16x32_bf16 v[130:133], v[134:137], v[174:177], v[130:133]
	v_mfma_f32_16x16x32_bf16 v[78:81], v[142:145], v[174:177], v[78:81]
	v_mfma_f32_16x16x32_bf16 v[126:129], v[134:137], v[182:185], v[126:129]
	v_mfma_f32_16x16x32_bf16 v[118:121], v[142:145], v[182:185], v[118:121]
	v_mfma_f32_16x16x32_bf16 v[110:113], v[142:145], v[190:193], v[30:33]
	s_setprio 0
	s_setprio 1
	v_mfma_f32_16x16x32_bf16 v[30:33], v[146:149], v[162:165], v[82:85]
	v_mfma_f32_16x16x32_bf16 v[82:85], v[150:153], v[166:169], v[30:33]
	v_mfma_f32_16x16x32_bf16 v[30:33], v[154:157], v[162:165], v[74:77]
	v_mfma_f32_16x16x32_bf16 v[74:77], v[158:161], v[166:169], v[30:33]
	v_mfma_f32_16x16x32_bf16 v[30:33], v[146:149], v[170:173], v[66:69]
	v_mfma_f32_16x16x32_bf16 v[66:69], v[150:153], v[174:177], v[30:33]
	v_mfma_f32_16x16x32_bf16 v[30:33], v[154:157], v[170:173], v[70:73]
	v_mfma_f32_16x16x32_bf16 v[70:73], v[158:161], v[174:177], v[30:33]
	v_mfma_f32_16x16x32_bf16 v[30:33], v[146:149], v[178:181], v[114:117]
	v_mfma_f32_16x16x32_bf16 v[114:117], v[150:153], v[182:185], v[30:33]
	v_mfma_f32_16x16x32_bf16 v[30:33], v[154:157], v[178:181], v[106:109]
	v_mfma_f32_16x16x32_bf16 v[106:109], v[158:161], v[182:185], v[30:33]
	v_mfma_f32_16x16x32_bf16 v[30:33], v[146:149], v[186:189], v[98:101]
	v_mfma_f32_16x16x32_bf16 v[98:101], v[150:153], v[190:193], v[30:33]
	v_mfma_f32_16x16x32_bf16 v[30:33], v[154:157], v[186:189], v[102:105]
	v_mfma_f32_16x16x32_bf16 v[102:105], v[158:161], v[190:193], v[30:33]
	s_barrier
	s_setprio 0
	s_add_u32 s38, s38, 0x100
	s_addc_u32 s39, s39, 0
	s_add_u32 s15, s15, 0x100
	s_addc_u32 s21, s21, 0
	s_cmp_ge_u32 s41, s56
	s_mov_b32 s22, s41
	s_cbranch_scc0 .LBB0_883

.LBB0_989:
	s_add_u32 s36, s38, 0x80080
	s_addc_u32 s37, s39, 0
	s_add_u32 s5, s22, 0x100
	s_addc_u32 s13, s23, 0
	s_mov_b32 s15, -2
	s_add_u32 s17, s36, 0xfff80080
	s_addc_u32 s22, s37, -1
	s_add_i32 s48, 0, 0x10000
	s_cmp_eq_u32 s15, 4
	s_cselect_b32 s39, s19, s22
	s_cselect_b32 s38, s18, s17
	s_cselect_b32 s23, s21, s13
	s_cselect_b32 s22, s20, s5
	s_add_i32 s17, 0, 0x14000
	v_add_u32_e32 v156, s48, v140
	v_add_u32_e32 v172, s17, v140
	ds_read_b128 v[144:147], v156
	ds_read_b128 v[148:151], v156 offset:1024
	ds_read_b128 v[152:155], v156 offset:2048
	ds_read_b128 v[156:159], v156 offset:3072
	ds_read_b128 v[160:163], v172
	ds_read_b128 v[164:167], v172 offset:1024
	ds_read_b128 v[168:171], v172 offset:2048
	ds_read_b128 v[172:175], v172 offset:3072
	v_lshl_add_u64 v[208:209], s[36:37], 0, v[136:137]
	s_add_i32 m0, s7, 0xc000
	ds_read_b128 v[176:179], v143
	ds_read_b128 v[180:183], v143 offset:1024
	ds_read_b128 v[184:187], v143 offset:2048
	ds_read_b128 v[188:191], v143 offset:3072
	ds_read_b128 v[192:195], v143 offset:4096
	ds_read_b128 v[196:199], v143 offset:5120
	ds_read_b128 v[200:203], v143 offset:6144
	ds_read_b128 v[204:207], v143 offset:7168
	global_load_lds_dwordx4 v[208:209], off
	v_lshl_add_u64 v[208:209], s[36:37], 0, v[138:139]
	s_add_i32 m0, s7, 0xe000
	s_nop 0
	global_load_lds_dwordx4 v[208:209], off
	s_waitcnt vmcnt(8)
	s_waitcnt lgkmcnt(0)
	s_setprio 1
	s_barrier
	v_mfma_f32_16x16x32_bf16 v[126:129], v[144:147], v[176:179], 0
	v_mfma_f32_16x16x32_bf16 v[122:125], v[152:155], v[176:179], 0
	v_mfma_f32_16x16x32_bf16 v[118:121], v[144:147], v[184:187], 0
	v_mfma_f32_16x16x32_bf16 v[114:117], v[152:155], v[184:187], 0
	v_mfma_f32_16x16x32_bf16 v[102:105], v[144:147], v[192:195], 0
	v_mfma_f32_16x16x32_bf16 v[98:101], v[152:155], v[192:195], 0
	v_mfma_f32_16x16x32_bf16 v[86:89], v[144:147], v[200:203], 0
	v_mfma_f32_16x16x32_bf16 v[82:85], v[152:155], v[200:203], 0
	v_mfma_f32_16x16x32_bf16 v[126:129], v[148:151], v[180:183], v[126:129]
	v_mfma_f32_16x16x32_bf16 v[122:125], v[156:159], v[180:183], v[122:125]
	v_mfma_f32_16x16x32_bf16 v[118:121], v[148:151], v[188:191], v[118:121]
	v_mfma_f32_16x16x32_bf16 v[114:117], v[156:159], v[188:191], v[114:117]
	v_mfma_f32_16x16x32_bf16 v[102:105], v[148:151], v[196:199], v[102:105]
	v_mfma_f32_16x16x32_bf16 v[98:101], v[156:159], v[196:199], v[98:101]
	v_mfma_f32_16x16x32_bf16 v[86:89], v[148:151], v[204:207], v[86:89]
	v_mfma_f32_16x16x32_bf16 v[82:85], v[156:159], v[204:207], v[82:85]
	s_setprio 0
	s_setprio 1
	v_mfma_f32_16x16x32_bf16 v[110:113], v[160:163], v[176:179], 0
	v_mfma_f32_16x16x32_bf16 v[106:109], v[168:171], v[176:179], 0
	v_mfma_f32_16x16x32_bf16 v[94:97], v[160:163], v[184:187], 0
	v_mfma_f32_16x16x32_bf16 v[90:93], v[168:171], v[184:187], 0
	v_mfma_f32_16x16x32_bf16 v[78:81], v[160:163], v[192:195], 0
	v_mfma_f32_16x16x32_bf16 v[74:77], v[168:171], v[192:195], 0
	v_mfma_f32_16x16x32_bf16 v[70:73], v[160:163], v[200:203], 0
	v_mfma_f32_16x16x32_bf16 v[66:69], v[168:171], v[200:203], 0
	v_mfma_f32_16x16x32_bf16 v[110:113], v[164:167], v[180:183], v[110:113]
	v_mfma_f32_16x16x32_bf16 v[106:109], v[172:175], v[180:183], v[106:109]
	v_mfma_f32_16x16x32_bf16 v[94:97], v[164:167], v[188:191], v[94:97]
	v_mfma_f32_16x16x32_bf16 v[90:93], v[172:175], v[188:191], v[90:93]
	v_mfma_f32_16x16x32_bf16 v[78:81], v[164:167], v[196:199], v[78:81]
	v_mfma_f32_16x16x32_bf16 v[74:77], v[172:175], v[196:199], v[74:77]
	v_mfma_f32_16x16x32_bf16 v[70:73], v[164:167], v[204:207], v[70:73]
	v_mfma_f32_16x16x32_bf16 v[66:69], v[172:175], v[204:207], v[66:69]
	s_barrier
	s_setprio 0
	s_add_i32 s48, s48, s40
	v_lshl_add_u64 v[208:209], s[22:23], 0, v[0:1]
	s_mov_b32 m0, s48
	ds_read_b128 v[176:179], v143 offset:16384
	ds_read_b128 v[180:183], v143 offset:17408
	ds_read_b128 v[184:187], v143 offset:18432
	ds_read_b128 v[188:191], v143 offset:19456
	ds_read_b128 v[192:195], v143 offset:20480
	ds_read_b128 v[196:199], v143 offset:21504
	ds_read_b128 v[200:203], v143 offset:22528
	ds_read_b128 v[204:207], v143 offset:23552
	global_load_lds_dwordx4 v[208:209], off
	s_add_i32 m0, s48, 0x2000
	s_add_u32 s48, s22, 0x80000
	v_lshl_add_u64 v[216:217], s[22:23], 0, v[130:131]
	s_addc_u32 s49, s23, 0
	s_add_i32 s17, s17, s40
	global_load_lds_dwordx4 v[216:217], off
	v_lshl_add_u64 v[220:221], s[48:49], 0, v[0:1]
	s_mov_b32 m0, s17
	v_lshl_add_u64 v[222:223], s[38:39], 0, v[132:133]
	global_load_lds_dwordx4 v[220:221], off
	v_lshl_add_u64 v[220:221], s[48:49], 0, v[130:131]
	s_add_i32 m0, s17, 0x2000
	s_nop 0
	global_load_lds_dwordx4 v[220:221], off
	v_lshl_add_u64 v[220:221], s[38:39], 0, v[134:135]
	s_mov_b32 m0, s7
	s_nop 0
	global_load_lds_dwordx4 v[220:221], off
	s_mov_b32 m0, s9
	s_nop 0
	global_load_lds_dwordx4 v[222:223], off
	s_waitcnt vmcnt(8)
	s_waitcnt lgkmcnt(0)
	s_setprio 1
	s_barrier
	v_mfma_f32_16x16x32_bf16 v[62:65], v[144:147], v[176:179], 0
	v_mfma_f32_16x16x32_bf16 v[58:61], v[152:155], v[176:179], 0
	v_mfma_f32_16x16x32_bf16 v[54:57], v[144:147], v[184:187], 0
	v_mfma_f32_16x16x32_bf16 v[50:53], v[152:155], v[184:187], 0
	v_mfma_f32_16x16x32_bf16 v[38:41], v[144:147], v[192:195], 0
	v_mfma_f32_16x16x32_bf16 v[34:37], v[152:155], v[192:195], 0
	v_mfma_f32_16x16x32_bf16 v[22:25], v[144:147], v[200:203], 0
	v_mfma_f32_16x16x32_bf16 v[18:21], v[152:155], v[200:203], 0
	v_mfma_f32_16x16x32_bf16 v[62:65], v[148:151], v[180:183], v[62:65]
	v_mfma_f32_16x16x32_bf16 v[58:61], v[156:159], v[180:183], v[58:61]
	v_mfma_f32_16x16x32_bf16 v[54:57], v[148:151], v[188:191], v[54:57]
	v_mfma_f32_16x16x32_bf16 v[50:53], v[156:159], v[188:191], v[50:53]
	v_mfma_f32_16x16x32_bf16 v[38:41], v[148:151], v[196:199], v[38:41]
	v_mfma_f32_16x16x32_bf16 v[34:37], v[156:159], v[196:199], v[34:37]
	v_mfma_f32_16x16x32_bf16 v[22:25], v[148:151], v[204:207], v[22:25]
	v_mfma_f32_16x16x32_bf16 v[18:21], v[156:159], v[204:207], v[18:21]
	s_setprio 0
	s_setprio 1
	v_mfma_f32_16x16x32_bf16 v[46:49], v[160:163], v[176:179], 0
	v_mfma_f32_16x16x32_bf16 v[42:45], v[168:171], v[176:179], 0
	v_mfma_f32_16x16x32_bf16 v[30:33], v[160:163], v[184:187], 0
	v_mfma_f32_16x16x32_bf16 v[26:29], v[168:171], v[184:187], 0
	v_mfma_f32_16x16x32_bf16 v[14:17], v[160:163], v[192:195], 0
	v_mfma_f32_16x16x32_bf16 v[10:13], v[168:171], v[192:195], 0
	v_mfma_f32_16x16x32_bf16 v[6:9], v[160:163], v[200:203], 0
	v_mfma_f32_16x16x32_bf16 v[2:5], v[168:171], v[200:203], 0
	v_mfma_f32_16x16x32_bf16 v[46:49], v[164:167], v[180:183], v[46:49]
	v_mfma_f32_16x16x32_bf16 v[42:45], v[172:175], v[180:183], v[42:45]
	v_mfma_f32_16x16x32_bf16 v[30:33], v[164:167], v[188:191], v[30:33]
	v_mfma_f32_16x16x32_bf16 v[26:29], v[172:175], v[188:191], v[26:29]
	v_mfma_f32_16x16x32_bf16 v[14:17], v[164:167], v[196:199], v[14:17]
	v_mfma_f32_16x16x32_bf16 v[10:13], v[172:175], v[196:199], v[10:13]
	v_mfma_f32_16x16x32_bf16 v[6:9], v[164:167], v[204:207], v[6:9]
	v_mfma_f32_16x16x32_bf16 v[2:5], v[172:175], v[204:207], v[2:5]
	s_barrier
	s_setprio 0
	s_add_i32 s17, 0, 0x18000
	s_add_i32 s48, 0, 0x1c000
	v_add_u32_e32 v156, s17, v140
	v_add_u32_e32 v172, s48, v140
	ds_read_b128 v[144:147], v156
	ds_read_b128 v[148:151], v156 offset:1024
	ds_read_b128 v[152:155], v156 offset:2048
	ds_read_b128 v[156:159], v156 offset:3072
	ds_read_b128 v[160:163], v172
	ds_read_b128 v[164:167], v172 offset:1024
	ds_read_b128 v[168:171], v172 offset:2048
	ds_read_b128 v[172:175], v172 offset:3072
	s_add_u32 s38, s38, 0x80000
	s_addc_u32 s39, s39, 0
	s_mov_b32 m0, s42
	v_lshl_add_u64 v[224:225], s[38:39], 0, v[134:135]
	ds_read_b128 v[176:179], v143 offset:32768
	ds_read_b128 v[180:183], v143 offset:33792
	ds_read_b128 v[184:187], v143 offset:34816
	ds_read_b128 v[188:191], v143 offset:35840
	ds_read_b128 v[192:195], v143 offset:36864
	ds_read_b128 v[196:199], v143 offset:37888
	ds_read_b128 v[200:203], v143 offset:38912
	ds_read_b128 v[204:207], v143 offset:39936
	global_load_lds_dwordx4 v[224:225], off
	v_lshl_add_u64 v[224:225], s[38:39], 0, v[132:133]
	s_mov_b32 m0, s43
	s_nop 0
	global_load_lds_dwordx4 v[224:225], off
	s_waitcnt vmcnt(8)
	s_waitcnt lgkmcnt(0)
	s_setprio 1
	s_barrier
	v_mfma_f32_16x16x32_bf16 v[126:129], v[144:147], v[176:179], v[126:129]
	v_mfma_f32_16x16x32_bf16 v[122:125], v[152:155], v[176:179], v[122:125]
	v_mfma_f32_16x16x32_bf16 v[118:121], v[144:147], v[184:187], v[118:121]
	v_mfma_f32_16x16x32_bf16 v[114:117], v[152:155], v[184:187], v[114:117]
	v_mfma_f32_16x16x32_bf16 v[102:105], v[144:147], v[192:195], v[102:105]
	v_mfma_f32_16x16x32_bf16 v[98:101], v[152:155], v[192:195], v[98:101]
	v_mfma_f32_16x16x32_bf16 v[86:89], v[144:147], v[200:203], v[86:89]
	v_mfma_f32_16x16x32_bf16 v[82:85], v[152:155], v[200:203], v[82:85]
	v_mfma_f32_16x16x32_bf16 v[126:129], v[148:151], v[180:183], v[126:129]
	v_mfma_f32_16x16x32_bf16 v[122:125], v[156:159], v[180:183], v[122:125]
	v_mfma_f32_16x16x32_bf16 v[118:121], v[148:151], v[188:191], v[118:121]
	v_mfma_f32_16x16x32_bf16 v[114:117], v[156:159], v[188:191], v[114:117]
	v_mfma_f32_16x16x32_bf16 v[102:105], v[148:151], v[196:199], v[102:105]
	v_mfma_f32_16x16x32_bf16 v[98:101], v[156:159], v[196:199], v[98:101]
	v_mfma_f32_16x16x32_bf16 v[86:89], v[148:151], v[204:207], v[86:89]
	v_mfma_f32_16x16x32_bf16 v[82:85], v[156:159], v[204:207], v[82:85]
	s_setprio 0
	s_setprio 1
	v_mfma_f32_16x16x32_bf16 v[110:113], v[160:163], v[176:179], v[110:113]
	v_mfma_f32_16x16x32_bf16 v[106:109], v[168:171], v[176:179], v[106:109]
	v_mfma_f32_16x16x32_bf16 v[94:97], v[160:163], v[184:187], v[94:97]
	v_mfma_f32_16x16x32_bf16 v[90:93], v[168:171], v[184:187], v[90:93]
	v_mfma_f32_16x16x32_bf16 v[78:81], v[160:163], v[192:195], v[78:81]
	v_mfma_f32_16x16x32_bf16 v[74:77], v[168:171], v[192:195], v[74:77]
	v_mfma_f32_16x16x32_bf16 v[70:73], v[160:163], v[200:203], v[70:73]
	v_mfma_f32_16x16x32_bf16 v[66:69], v[168:171], v[200:203], v[66:69]
	v_mfma_f32_16x16x32_bf16 v[110:113], v[164:167], v[180:183], v[110:113]
	v_mfma_f32_16x16x32_bf16 v[106:109], v[172:175], v[180:183], v[106:109]
	v_mfma_f32_16x16x32_bf16 v[94:97], v[164:167], v[188:191], v[94:97]
	v_mfma_f32_16x16x32_bf16 v[90:93], v[172:175], v[188:191], v[90:93]
	v_mfma_f32_16x16x32_bf16 v[78:81], v[164:167], v[196:199], v[78:81]
	v_mfma_f32_16x16x32_bf16 v[74:77], v[172:175], v[196:199], v[74:77]
	v_mfma_f32_16x16x32_bf16 v[70:73], v[164:167], v[204:207], v[70:73]
	v_mfma_f32_16x16x32_bf16 v[66:69], v[172:175], v[204:207], v[66:69]
	s_barrier
	s_setprio 0
	s_add_i32 s17, s17, s40
	v_lshl_add_u64 v[208:209], v[208:209], 0, s[2:3]
	s_mov_b32 m0, s17
	ds_read_b128 v[176:179], v143 offset:49152
	ds_read_b128 v[180:183], v143 offset:50176
	ds_read_b128 v[184:187], v143 offset:51200
	ds_read_b128 v[188:191], v143 offset:52224
	ds_read_b128 v[192:195], v143 offset:53248
	ds_read_b128 v[196:199], v143 offset:54272
	ds_read_b128 v[200:203], v143 offset:55296
	ds_read_b128 v[204:207], v143 offset:56320
	global_load_lds_dwordx4 v[208:209], off
	s_add_i32 m0, s17, 0x2000
	s_add_u32 s22, s22, 0x80080
	v_lshl_add_u64 v[208:209], v[216:217], 0, s[2:3]
	s_addc_u32 s23, s23, 0
	s_add_i32 s17, s48, s40
	global_load_lds_dwordx4 v[208:209], off
	v_lshl_add_u64 v[208:209], s[22:23], 0, v[0:1]
	s_mov_b32 m0, s17
	s_nop 0
	global_load_lds_dwordx4 v[208:209], off
	v_lshl_add_u64 v[208:209], s[22:23], 0, v[130:131]
	s_add_i32 m0, s17, 0x2000
	s_nop 0
	global_load_lds_dwordx4 v[208:209], off
	v_lshl_add_u64 v[208:209], v[220:221], 0, s[2:3]
	s_mov_b32 m0, s44
	s_nop 0
	global_load_lds_dwordx4 v[208:209], off
	v_lshl_add_u64 v[208:209], v[222:223], 0, s[2:3]
	s_mov_b32 m0, s45
	s_nop 0
	global_load_lds_dwordx4 v[208:209], off
	s_waitcnt vmcnt(8)
	s_waitcnt lgkmcnt(0)
	s_setprio 1
	s_barrier
	v_mfma_f32_16x16x32_bf16 v[62:65], v[144:147], v[176:179], v[62:65]
	v_mfma_f32_16x16x32_bf16 v[58:61], v[152:155], v[176:179], v[58:61]
	v_mfma_f32_16x16x32_bf16 v[54:57], v[144:147], v[184:187], v[54:57]
	v_mfma_f32_16x16x32_bf16 v[50:53], v[152:155], v[184:187], v[50:53]
	v_mfma_f32_16x16x32_bf16 v[38:41], v[144:147], v[192:195], v[38:41]
	v_mfma_f32_16x16x32_bf16 v[34:37], v[152:155], v[192:195], v[34:37]
	v_mfma_f32_16x16x32_bf16 v[22:25], v[144:147], v[200:203], v[22:25]
	v_mfma_f32_16x16x32_bf16 v[18:21], v[152:155], v[200:203], v[18:21]
	v_mfma_f32_16x16x32_bf16 v[62:65], v[148:151], v[180:183], v[62:65]
	v_mfma_f32_16x16x32_bf16 v[58:61], v[156:159], v[180:183], v[58:61]
	v_mfma_f32_16x16x32_bf16 v[54:57], v[148:151], v[188:191], v[54:57]
	v_mfma_f32_16x16x32_bf16 v[50:53], v[156:159], v[188:191], v[50:53]
	v_mfma_f32_16x16x32_bf16 v[38:41], v[148:151], v[196:199], v[38:41]
	v_mfma_f32_16x16x32_bf16 v[34:37], v[156:159], v[196:199], v[34:37]
	v_mfma_f32_16x16x32_bf16 v[22:25], v[148:151], v[204:207], v[22:25]
	v_mfma_f32_16x16x32_bf16 v[18:21], v[156:159], v[204:207], v[18:21]
	s_setprio 0
	s_setprio 1
	v_mfma_f32_16x16x32_bf16 v[46:49], v[160:163], v[176:179], v[46:49]
	v_mfma_f32_16x16x32_bf16 v[42:45], v[168:171], v[176:179], v[42:45]
	v_mfma_f32_16x16x32_bf16 v[30:33], v[160:163], v[184:187], v[30:33]
	v_mfma_f32_16x16x32_bf16 v[26:29], v[168:171], v[184:187], v[26:29]
	v_mfma_f32_16x16x32_bf16 v[14:17], v[160:163], v[192:195], v[14:17]
	v_mfma_f32_16x16x32_bf16 v[10:13], v[168:171], v[192:195], v[10:13]
	v_mfma_f32_16x16x32_bf16 v[6:9], v[160:163], v[200:203], v[6:9]
	v_mfma_f32_16x16x32_bf16 v[2:5], v[168:171], v[200:203], v[2:5]
	v_mfma_f32_16x16x32_bf16 v[46:49], v[164:167], v[180:183], v[46:49]
	v_mfma_f32_16x16x32_bf16 v[42:45], v[172:175], v[180:183], v[42:45]
	v_mfma_f32_16x16x32_bf16 v[30:33], v[164:167], v[188:191], v[30:33]
	v_mfma_f32_16x16x32_bf16 v[26:29], v[172:175], v[188:191], v[26:29]
	v_mfma_f32_16x16x32_bf16 v[14:17], v[164:167], v[196:199], v[14:17]
	v_mfma_f32_16x16x32_bf16 v[10:13], v[172:175], v[196:199], v[10:13]
	v_mfma_f32_16x16x32_bf16 v[6:9], v[164:167], v[204:207], v[6:9]
	v_mfma_f32_16x16x32_bf16 v[2:5], v[172:175], v[204:207], v[2:5]
	s_barrier
	s_setprio 0
	s_add_i32 s15, s15, 2
	s_add_u32 s36, s36, 0x100
	s_addc_u32 s37, s37, 0
	s_add_u32 s5, s5, 0x100
	s_addc_u32 s13, s13, 0
	s_cmp_gt_u32 s15, 5
	s_cbranch_scc1 .Lpeel_done_2
.LBB0_990:
	s_add_u32 s17, s36, 0xfff80080
	s_addc_u32 s22, s37, -1
	s_add_i32 s48, 0, 0x10000
	s_cmp_eq_u32 s15, 4
	s_cselect_b32 s39, s19, s22
	s_cselect_b32 s38, s18, s17
	s_cselect_b32 s23, s21, s13
	s_cselect_b32 s22, s20, s5
	s_add_i32 s17, 0, 0x14000
	v_add_u32_e32 v156, s48, v140
	v_add_u32_e32 v172, s17, v140
	ds_read_b128 v[144:147], v156
	ds_read_b128 v[148:151], v156 offset:1024
	ds_read_b128 v[152:155], v156 offset:2048
	ds_read_b128 v[156:159], v156 offset:3072
	ds_read_b128 v[160:163], v172
	ds_read_b128 v[164:167], v172 offset:1024
	ds_read_b128 v[168:171], v172 offset:2048
	ds_read_b128 v[172:175], v172 offset:3072
	v_lshl_add_u64 v[208:209], s[36:37], 0, v[136:137]
	s_add_i32 m0, s7, 0xc000
	ds_read_b128 v[176:179], v143
	ds_read_b128 v[180:183], v143 offset:1024
	ds_read_b128 v[184:187], v143 offset:2048
	ds_read_b128 v[188:191], v143 offset:3072
	ds_read_b128 v[192:195], v143 offset:4096
	ds_read_b128 v[196:199], v143 offset:5120
	ds_read_b128 v[200:203], v143 offset:6144
	ds_read_b128 v[204:207], v143 offset:7168
	global_load_lds_dwordx4 v[208:209], off
	v_lshl_add_u64 v[208:209], s[36:37], 0, v[138:139]
	s_add_i32 m0, s7, 0xe000
	s_nop 0
	global_load_lds_dwordx4 v[208:209], off
	s_waitcnt vmcnt(8)
	s_waitcnt lgkmcnt(0)
	s_setprio 1
	s_barrier
	v_mfma_f32_16x16x32_bf16 v[126:129], v[144:147], v[176:179], v[126:129]
	v_mfma_f32_16x16x32_bf16 v[122:125], v[152:155], v[176:179], v[122:125]
	v_mfma_f32_16x16x32_bf16 v[118:121], v[144:147], v[184:187], v[118:121]
	v_mfma_f32_16x16x32_bf16 v[114:117], v[152:155], v[184:187], v[114:117]
	v_mfma_f32_16x16x32_bf16 v[102:105], v[144:147], v[192:195], v[102:105]
	v_mfma_f32_16x16x32_bf16 v[98:101], v[152:155], v[192:195], v[98:101]
	v_mfma_f32_16x16x32_bf16 v[86:89], v[144:147], v[200:203], v[86:89]
	v_mfma_f32_16x16x32_bf16 v[82:85], v[152:155], v[200:203], v[82:85]
	v_mfma_f32_16x16x32_bf16 v[126:129], v[148:151], v[180:183], v[126:129]
	v_mfma_f32_16x16x32_bf16 v[122:125], v[156:159], v[180:183], v[122:125]
	v_mfma_f32_16x16x32_bf16 v[118:121], v[148:151], v[188:191], v[118:121]
	v_mfma_f32_16x16x32_bf16 v[114:117], v[156:159], v[188:191], v[114:117]
	v_mfma_f32_16x16x32_bf16 v[102:105], v[148:151], v[196:199], v[102:105]
	v_mfma_f32_16x16x32_bf16 v[98:101], v[156:159], v[196:199], v[98:101]
	v_mfma_f32_16x16x32_bf16 v[86:89], v[148:151], v[204:207], v[86:89]
	v_mfma_f32_16x16x32_bf16 v[82:85], v[156:159], v[204:207], v[82:85]
	s_setprio 0
	s_setprio 1
	v_mfma_f32_16x16x32_bf16 v[110:113], v[160:163], v[176:179], v[110:113]
	v_mfma_f32_16x16x32_bf16 v[106:109], v[168:171], v[176:179], v[106:109]
	v_mfma_f32_16x16x32_bf16 v[94:97], v[160:163], v[184:187], v[94:97]
	v_mfma_f32_16x16x32_bf16 v[90:93], v[168:171], v[184:187], v[90:93]
	v_mfma_f32_16x16x32_bf16 v[78:81], v[160:163], v[192:195], v[78:81]
	v_mfma_f32_16x16x32_bf16 v[74:77], v[168:171], v[192:195], v[74:77]
	v_mfma_f32_16x16x32_bf16 v[70:73], v[160:163], v[200:203], v[70:73]
	v_mfma_f32_16x16x32_bf16 v[66:69], v[168:171], v[200:203], v[66:69]
	v_mfma_f32_16x16x32_bf16 v[110:113], v[164:167], v[180:183], v[110:113]
	v_mfma_f32_16x16x32_bf16 v[106:109], v[172:175], v[180:183], v[106:109]
	v_mfma_f32_16x16x32_bf16 v[94:97], v[164:167], v[188:191], v[94:97]
	v_mfma_f32_16x16x32_bf16 v[90:93], v[172:175], v[188:191], v[90:93]
	v_mfma_f32_16x16x32_bf16 v[78:81], v[164:167], v[196:199], v[78:81]
	v_mfma_f32_16x16x32_bf16 v[74:77], v[172:175], v[196:199], v[74:77]
	v_mfma_f32_16x16x32_bf16 v[70:73], v[164:167], v[204:207], v[70:73]
	v_mfma_f32_16x16x32_bf16 v[66:69], v[172:175], v[204:207], v[66:69]
	s_barrier
	s_setprio 0
	s_add_i32 s48, s48, s40
	v_lshl_add_u64 v[208:209], s[22:23], 0, v[0:1]
	s_mov_b32 m0, s48
	ds_read_b128 v[176:179], v143 offset:16384
	ds_read_b128 v[180:183], v143 offset:17408
	ds_read_b128 v[184:187], v143 offset:18432
	ds_read_b128 v[188:191], v143 offset:19456
	ds_read_b128 v[192:195], v143 offset:20480
	ds_read_b128 v[196:199], v143 offset:21504
	ds_read_b128 v[200:203], v143 offset:22528
	ds_read_b128 v[204:207], v143 offset:23552
	global_load_lds_dwordx4 v[208:209], off
	s_add_i32 m0, s48, 0x2000
	s_add_u32 s48, s22, 0x80000
	v_lshl_add_u64 v[216:217], s[22:23], 0, v[130:131]
	s_addc_u32 s49, s23, 0
	s_add_i32 s17, s17, s40
	global_load_lds_dwordx4 v[216:217], off
	v_lshl_add_u64 v[220:221], s[48:49], 0, v[0:1]
	s_mov_b32 m0, s17
	v_lshl_add_u64 v[222:223], s[38:39], 0, v[132:133]
	global_load_lds_dwordx4 v[220:221], off
	v_lshl_add_u64 v[220:221], s[48:49], 0, v[130:131]
	s_add_i32 m0, s17, 0x2000
	s_nop 0
	global_load_lds_dwordx4 v[220:221], off
	v_lshl_add_u64 v[220:221], s[38:39], 0, v[134:135]
	s_mov_b32 m0, s7
	s_nop 0
	global_load_lds_dwordx4 v[220:221], off
	s_mov_b32 m0, s9
	s_nop 0
	global_load_lds_dwordx4 v[222:223], off
	s_waitcnt vmcnt(8)
	s_waitcnt lgkmcnt(0)
	s_setprio 1
	s_barrier
	v_mfma_f32_16x16x32_bf16 v[62:65], v[144:147], v[176:179], v[62:65]
	v_mfma_f32_16x16x32_bf16 v[58:61], v[152:155], v[176:179], v[58:61]
	v_mfma_f32_16x16x32_bf16 v[54:57], v[144:147], v[184:187], v[54:57]
	v_mfma_f32_16x16x32_bf16 v[50:53], v[152:155], v[184:187], v[50:53]
	v_mfma_f32_16x16x32_bf16 v[38:41], v[144:147], v[192:195], v[38:41]
	v_mfma_f32_16x16x32_bf16 v[34:37], v[152:155], v[192:195], v[34:37]
	v_mfma_f32_16x16x32_bf16 v[22:25], v[144:147], v[200:203], v[22:25]
	v_mfma_f32_16x16x32_bf16 v[18:21], v[152:155], v[200:203], v[18:21]
	v_mfma_f32_16x16x32_bf16 v[62:65], v[148:151], v[180:183], v[62:65]
	v_mfma_f32_16x16x32_bf16 v[58:61], v[156:159], v[180:183], v[58:61]
	v_mfma_f32_16x16x32_bf16 v[54:57], v[148:151], v[188:191], v[54:57]
	v_mfma_f32_16x16x32_bf16 v[50:53], v[156:159], v[188:191], v[50:53]
	v_mfma_f32_16x16x32_bf16 v[38:41], v[148:151], v[196:199], v[38:41]
	v_mfma_f32_16x16x32_bf16 v[34:37], v[156:159], v[196:199], v[34:37]
	v_mfma_f32_16x16x32_bf16 v[22:25], v[148:151], v[204:207], v[22:25]
	v_mfma_f32_16x16x32_bf16 v[18:21], v[156:159], v[204:207], v[18:21]
	s_setprio 0
	s_setprio 1
	v_mfma_f32_16x16x32_bf16 v[46:49], v[160:163], v[176:179], v[46:49]
	v_mfma_f32_16x16x32_bf16 v[42:45], v[168:171], v[176:179], v[42:45]
	v_mfma_f32_16x16x32_bf16 v[30:33], v[160:163], v[184:187], v[30:33]
	v_mfma_f32_16x16x32_bf16 v[26:29], v[168:171], v[184:187], v[26:29]
	v_mfma_f32_16x16x32_bf16 v[14:17], v[160:163], v[192:195], v[14:17]
	v_mfma_f32_16x16x32_bf16 v[10:13], v[168:171], v[192:195], v[10:13]
	v_mfma_f32_16x16x32_bf16 v[6:9], v[160:163], v[200:203], v[6:9]
	v_mfma_f32_16x16x32_bf16 v[2:5], v[168:171], v[200:203], v[2:5]
	v_mfma_f32_16x16x32_bf16 v[46:49], v[164:167], v[180:183], v[46:49]
	v_mfma_f32_16x16x32_bf16 v[42:45], v[172:175], v[180:183], v[42:45]
	v_mfma_f32_16x16x32_bf16 v[30:33], v[164:167], v[188:191], v[30:33]
	v_mfma_f32_16x16x32_bf16 v[26:29], v[172:175], v[188:191], v[26:29]
	v_mfma_f32_16x16x32_bf16 v[14:17], v[164:167], v[196:199], v[14:17]
	v_mfma_f32_16x16x32_bf16 v[10:13], v[172:175], v[196:199], v[10:13]
	v_mfma_f32_16x16x32_bf16 v[6:9], v[164:167], v[204:207], v[6:9]
	v_mfma_f32_16x16x32_bf16 v[2:5], v[172:175], v[204:207], v[2:5]
	s_barrier
	s_setprio 0
	s_add_i32 s17, 0, 0x18000
	s_add_i32 s48, 0, 0x1c000
	v_add_u32_e32 v156, s17, v140
	v_add_u32_e32 v172, s48, v140
	ds_read_b128 v[144:147], v156
	ds_read_b128 v[148:151], v156 offset:1024
	ds_read_b128 v[152:155], v156 offset:2048
	ds_read_b128 v[156:159], v156 offset:3072
	ds_read_b128 v[160:163], v172
	ds_read_b128 v[164:167], v172 offset:1024
	ds_read_b128 v[168:171], v172 offset:2048
	ds_read_b128 v[172:175], v172 offset:3072
	s_add_u32 s38, s38, 0x80000
	s_addc_u32 s39, s39, 0
	s_mov_b32 m0, s42
	v_lshl_add_u64 v[224:225], s[38:39], 0, v[134:135]
	ds_read_b128 v[176:179], v143 offset:32768
	ds_read_b128 v[180:183], v143 offset:33792
	ds_read_b128 v[184:187], v143 offset:34816
	ds_read_b128 v[188:191], v143 offset:35840
	ds_read_b128 v[192:195], v143 offset:36864
	ds_read_b128 v[196:199], v143 offset:37888
	ds_read_b128 v[200:203], v143 offset:38912
	ds_read_b128 v[204:207], v143 offset:39936
	global_load_lds_dwordx4 v[224:225], off
	v_lshl_add_u64 v[224:225], s[38:39], 0, v[132:133]
	s_mov_b32 m0, s43
	s_nop 0
	global_load_lds_dwordx4 v[224:225], off
	s_waitcnt vmcnt(8)
	s_waitcnt lgkmcnt(0)
	s_setprio 1
	s_barrier
	v_mfma_f32_16x16x32_bf16 v[126:129], v[144:147], v[176:179], v[126:129]
	v_mfma_f32_16x16x32_bf16 v[122:125], v[152:155], v[176:179], v[122:125]
	v_mfma_f32_16x16x32_bf16 v[118:121], v[144:147], v[184:187], v[118:121]
	v_mfma_f32_16x16x32_bf16 v[114:117], v[152:155], v[184:187], v[114:117]
	v_mfma_f32_16x16x32_bf16 v[102:105], v[144:147], v[192:195], v[102:105]
	v_mfma_f32_16x16x32_bf16 v[98:101], v[152:155], v[192:195], v[98:101]
	v_mfma_f32_16x16x32_bf16 v[86:89], v[144:147], v[200:203], v[86:89]
	v_mfma_f32_16x16x32_bf16 v[82:85], v[152:155], v[200:203], v[82:85]
	v_mfma_f32_16x16x32_bf16 v[126:129], v[148:151], v[180:183], v[126:129]
	v_mfma_f32_16x16x32_bf16 v[122:125], v[156:159], v[180:183], v[122:125]
	v_mfma_f32_16x16x32_bf16 v[118:121], v[148:151], v[188:191], v[118:121]
	v_mfma_f32_16x16x32_bf16 v[114:117], v[156:159], v[188:191], v[114:117]
	v_mfma_f32_16x16x32_bf16 v[102:105], v[148:151], v[196:199], v[102:105]
	v_mfma_f32_16x16x32_bf16 v[98:101], v[156:159], v[196:199], v[98:101]
	v_mfma_f32_16x16x32_bf16 v[86:89], v[148:151], v[204:207], v[86:89]
	v_mfma_f32_16x16x32_bf16 v[82:85], v[156:159], v[204:207], v[82:85]
	s_setprio 0
	s_setprio 1
	v_mfma_f32_16x16x32_bf16 v[110:113], v[160:163], v[176:179], v[110:113]
	v_mfma_f32_16x16x32_bf16 v[106:109], v[168:171], v[176:179], v[106:109]
	v_mfma_f32_16x16x32_bf16 v[94:97], v[160:163], v[184:187], v[94:97]
	v_mfma_f32_16x16x32_bf16 v[90:93], v[168:171], v[184:187], v[90:93]
	v_mfma_f32_16x16x32_bf16 v[78:81], v[160:163], v[192:195], v[78:81]
	v_mfma_f32_16x16x32_bf16 v[74:77], v[168:171], v[192:195], v[74:77]
	v_mfma_f32_16x16x32_bf16 v[70:73], v[160:163], v[200:203], v[70:73]
	v_mfma_f32_16x16x32_bf16 v[66:69], v[168:171], v[200:203], v[66:69]
	v_mfma_f32_16x16x32_bf16 v[110:113], v[164:167], v[180:183], v[110:113]
	v_mfma_f32_16x16x32_bf16 v[106:109], v[172:175], v[180:183], v[106:109]
	v_mfma_f32_16x16x32_bf16 v[94:97], v[164:167], v[188:191], v[94:97]
	v_mfma_f32_16x16x32_bf16 v[90:93], v[172:175], v[188:191], v[90:93]
	v_mfma_f32_16x16x32_bf16 v[78:81], v[164:167], v[196:199], v[78:81]
	v_mfma_f32_16x16x32_bf16 v[74:77], v[172:175], v[196:199], v[74:77]
	v_mfma_f32_16x16x32_bf16 v[70:73], v[164:167], v[204:207], v[70:73]
	v_mfma_f32_16x16x32_bf16 v[66:69], v[172:175], v[204:207], v[66:69]
	s_barrier
	s_setprio 0
	s_add_i32 s17, s17, s40
	v_lshl_add_u64 v[208:209], v[208:209], 0, s[2:3]
	s_mov_b32 m0, s17
	ds_read_b128 v[176:179], v143 offset:49152
	ds_read_b128 v[180:183], v143 offset:50176
	ds_read_b128 v[184:187], v143 offset:51200
	ds_read_b128 v[188:191], v143 offset:52224
	ds_read_b128 v[192:195], v143 offset:53248
	ds_read_b128 v[196:199], v143 offset:54272
	ds_read_b128 v[200:203], v143 offset:55296
	ds_read_b128 v[204:207], v143 offset:56320
	global_load_lds_dwordx4 v[208:209], off
	s_add_i32 m0, s17, 0x2000
	s_add_u32 s22, s22, 0x80080
	v_lshl_add_u64 v[208:209], v[216:217], 0, s[2:3]
	s_addc_u32 s23, s23, 0
	s_add_i32 s17, s48, s40
	global_load_lds_dwordx4 v[208:209], off
	v_lshl_add_u64 v[208:209], s[22:23], 0, v[0:1]
	s_mov_b32 m0, s17
	s_nop 0
	global_load_lds_dwordx4 v[208:209], off
	v_lshl_add_u64 v[208:209], s[22:23], 0, v[130:131]
	s_add_i32 m0, s17, 0x2000
	s_nop 0
	global_load_lds_dwordx4 v[208:209], off
	v_lshl_add_u64 v[208:209], v[220:221], 0, s[2:3]
	s_mov_b32 m0, s44
	s_nop 0
	global_load_lds_dwordx4 v[208:209], off
	v_lshl_add_u64 v[208:209], v[222:223], 0, s[2:3]
	s_mov_b32 m0, s45
	s_nop 0
	global_load_lds_dwordx4 v[208:209], off
	s_waitcnt vmcnt(8)
	s_waitcnt lgkmcnt(0)
	s_setprio 1
	s_barrier
	v_mfma_f32_16x16x32_bf16 v[62:65], v[144:147], v[176:179], v[62:65]
	v_mfma_f32_16x16x32_bf16 v[58:61], v[152:155], v[176:179], v[58:61]
	v_mfma_f32_16x16x32_bf16 v[54:57], v[144:147], v[184:187], v[54:57]
	v_mfma_f32_16x16x32_bf16 v[50:53], v[152:155], v[184:187], v[50:53]
	v_mfma_f32_16x16x32_bf16 v[38:41], v[144:147], v[192:195], v[38:41]
	v_mfma_f32_16x16x32_bf16 v[34:37], v[152:155], v[192:195], v[34:37]
	v_mfma_f32_16x16x32_bf16 v[22:25], v[144:147], v[200:203], v[22:25]
	v_mfma_f32_16x16x32_bf16 v[18:21], v[152:155], v[200:203], v[18:21]
	v_mfma_f32_16x16x32_bf16 v[62:65], v[148:151], v[180:183], v[62:65]
	v_mfma_f32_16x16x32_bf16 v[58:61], v[156:159], v[180:183], v[58:61]
	v_mfma_f32_16x16x32_bf16 v[54:57], v[148:151], v[188:191], v[54:57]
	v_mfma_f32_16x16x32_bf16 v[50:53], v[156:159], v[188:191], v[50:53]
	v_mfma_f32_16x16x32_bf16 v[38:41], v[148:151], v[196:199], v[38:41]
	v_mfma_f32_16x16x32_bf16 v[34:37], v[156:159], v[196:199], v[34:37]
	v_mfma_f32_16x16x32_bf16 v[22:25], v[148:151], v[204:207], v[22:25]
	v_mfma_f32_16x16x32_bf16 v[18:21], v[156:159], v[204:207], v[18:21]
	s_setprio 0
	s_setprio 1
	v_mfma_f32_16x16x32_bf16 v[46:49], v[160:163], v[176:179], v[46:49]
	v_mfma_f32_16x16x32_bf16 v[42:45], v[168:171], v[176:179], v[42:45]
	v_mfma_f32_16x16x32_bf16 v[30:33], v[160:163], v[184:187], v[30:33]
	v_mfma_f32_16x16x32_bf16 v[26:29], v[168:171], v[184:187], v[26:29]
	v_mfma_f32_16x16x32_bf16 v[14:17], v[160:163], v[192:195], v[14:17]
	v_mfma_f32_16x16x32_bf16 v[10:13], v[168:171], v[192:195], v[10:13]
	v_mfma_f32_16x16x32_bf16 v[6:9], v[160:163], v[200:203], v[6:9]
	v_mfma_f32_16x16x32_bf16 v[2:5], v[168:171], v[200:203], v[2:5]
	v_mfma_f32_16x16x32_bf16 v[46:49], v[164:167], v[180:183], v[46:49]
	v_mfma_f32_16x16x32_bf16 v[42:45], v[172:175], v[180:183], v[42:45]
	v_mfma_f32_16x16x32_bf16 v[30:33], v[164:167], v[188:191], v[30:33]
	v_mfma_f32_16x16x32_bf16 v[26:29], v[172:175], v[188:191], v[26:29]
	v_mfma_f32_16x16x32_bf16 v[14:17], v[164:167], v[196:199], v[14:17]
	v_mfma_f32_16x16x32_bf16 v[10:13], v[172:175], v[196:199], v[10:13]
	v_mfma_f32_16x16x32_bf16 v[6:9], v[164:167], v[204:207], v[6:9]
	v_mfma_f32_16x16x32_bf16 v[2:5], v[172:175], v[204:207], v[2:5]
	s_barrier
	s_setprio 0
	s_add_i32 s15, s15, 2
	s_add_u32 s36, s36, 0x100
	s_addc_u32 s37, s37, 0
	s_add_u32 s5, s5, 0x100
	s_addc_u32 s13, s13, 0
	s_cmp_gt_u32 s15, 5
	s_cbranch_scc0 .LBB0_990

.LBB0_1200:
	s_ashr_i32 s7, s6, 31
	s_lshl_b64 s[12:13], s[6:7], 18
	s_add_u32 s12, s78, s12
	v_readlane_b32 s7, v254, 37
	s_addc_u32 s13, s7, s13
	s_and_b64 s[22:23], s[22:23], exec
	s_cselect_b32 s7, s13, s21
	s_cselect_b32 s9, s12, s20
	s_add_u32 s18, s18, 0x80080
	s_addc_u32 s19, s19, 0
	s_add_u32 s15, s20, 0x100
	s_addc_u32 s36, s21, 0
	s_mov_b32 s37, -2
	s_add_u32 s20, s18, 0xfff80080
	s_addc_u32 s21, s19, -1
	s_add_i32 s47, 0, 0x10000
	s_cmp_eq_u32 s37, 4
	s_cselect_b32 s23, s11, s21
	s_cselect_b32 s22, s10, s20
	s_cselect_b32 s21, s7, s36
	s_cselect_b32 s20, s9, s15
	s_add_i32 s50, 0, 0x14000
	v_add_u32_e32 v142, s47, v171
	v_add_u32_e32 v168, s50, v171
	ds_read_b128 v[130:133], v142
	ds_read_b128 v[134:137], v142 offset:1024
	ds_read_b128 v[138:141], v142 offset:2048
	ds_read_b128 v[142:145], v142 offset:3072
	ds_read_b128 v[156:159], v168
	ds_read_b128 v[160:163], v168 offset:1024
	ds_read_b128 v[164:167], v168 offset:2048
	ds_read_b128 v[174:177], v168 offset:3072
	v_lshl_add_u64 v[168:169], s[18:19], 0, v[152:153]
	s_add_i32 m0, s17, 0xc000
	ds_read_b128 v[178:181], v173
	ds_read_b128 v[182:185], v173 offset:1024
	ds_read_b128 v[186:189], v173 offset:2048
	ds_read_b128 v[190:193], v173 offset:3072
	ds_read_b128 v[194:197], v173 offset:4096
	ds_read_b128 v[198:201], v173 offset:5120
	ds_read_b128 v[202:205], v173 offset:6144
	ds_read_b128 v[206:209], v173 offset:7168
	global_load_lds_dwordx4 v[168:169], off
	v_lshl_add_u64 v[168:169], s[18:19], 0, v[154:155]
	s_add_i32 m0, s17, 0xe000
	s_nop 0
	global_load_lds_dwordx4 v[168:169], off
	s_waitcnt vmcnt(8)
	s_waitcnt lgkmcnt(0)
	s_setprio 1
	s_barrier
	v_mfma_f32_16x16x32_bf16 v[126:129], v[130:133], v[178:181], 0
	v_mfma_f32_16x16x32_bf16 v[122:125], v[138:141], v[178:181], 0
	v_mfma_f32_16x16x32_bf16 v[118:121], v[130:133], v[186:189], 0
	v_mfma_f32_16x16x32_bf16 v[106:109], v[138:141], v[186:189], 0
	v_mfma_f32_16x16x32_bf16 v[98:101], v[130:133], v[194:197], 0
	v_mfma_f32_16x16x32_bf16 v[90:93], v[138:141], v[194:197], 0
	v_mfma_f32_16x16x32_bf16 v[82:85], v[130:133], v[202:205], 0
	v_mfma_f32_16x16x32_bf16 v[74:77], v[138:141], v[202:205], 0
	v_mfma_f32_16x16x32_bf16 v[126:129], v[134:137], v[182:185], v[126:129]
	v_mfma_f32_16x16x32_bf16 v[122:125], v[142:145], v[182:185], v[122:125]
	v_mfma_f32_16x16x32_bf16 v[118:121], v[134:137], v[190:193], v[118:121]
	v_mfma_f32_16x16x32_bf16 v[106:109], v[142:145], v[190:193], v[106:109]
	v_mfma_f32_16x16x32_bf16 v[98:101], v[134:137], v[198:201], v[98:101]
	v_mfma_f32_16x16x32_bf16 v[90:93], v[142:145], v[198:201], v[90:93]
	v_mfma_f32_16x16x32_bf16 v[82:85], v[134:137], v[206:209], v[82:85]
	v_mfma_f32_16x16x32_bf16 v[74:77], v[142:145], v[206:209], v[74:77]
	s_setprio 0
	s_setprio 1
	v_mfma_f32_16x16x32_bf16 v[114:117], v[156:159], v[178:181], 0
	v_mfma_f32_16x16x32_bf16 v[110:113], v[164:167], v[178:181], 0
	v_mfma_f32_16x16x32_bf16 v[102:105], v[156:159], v[186:189], 0
	v_mfma_f32_16x16x32_bf16 v[94:97], v[164:167], v[186:189], 0
	v_mfma_f32_16x16x32_bf16 v[86:89], v[156:159], v[194:197], 0
	v_mfma_f32_16x16x32_bf16 v[78:81], v[164:167], v[194:197], 0
	v_mfma_f32_16x16x32_bf16 v[70:73], v[156:159], v[202:205], 0
	v_mfma_f32_16x16x32_bf16 v[66:69], v[164:167], v[202:205], 0
	v_mfma_f32_16x16x32_bf16 v[114:117], v[160:163], v[182:185], v[114:117]
	v_mfma_f32_16x16x32_bf16 v[110:113], v[174:177], v[182:185], v[110:113]
	v_mfma_f32_16x16x32_bf16 v[102:105], v[160:163], v[190:193], v[102:105]
	v_mfma_f32_16x16x32_bf16 v[94:97], v[174:177], v[190:193], v[94:97]
	v_mfma_f32_16x16x32_bf16 v[86:89], v[160:163], v[198:201], v[86:89]
	v_mfma_f32_16x16x32_bf16 v[78:81], v[174:177], v[198:201], v[78:81]
	v_mfma_f32_16x16x32_bf16 v[70:73], v[160:163], v[206:209], v[70:73]
	v_mfma_f32_16x16x32_bf16 v[66:69], v[174:177], v[206:209], v[66:69]
	s_barrier
	s_setprio 0
	s_add_i32 s47, s47, s38
	v_lshl_add_u64 v[168:169], s[20:21], 0, v[0:1]
	s_mov_b32 m0, s47
	ds_read_b128 v[178:181], v173 offset:16384
	ds_read_b128 v[182:185], v173 offset:17408
	ds_read_b128 v[186:189], v173 offset:18432
	ds_read_b128 v[190:193], v173 offset:19456
	ds_read_b128 v[194:197], v173 offset:20480
	ds_read_b128 v[198:201], v173 offset:21504
	ds_read_b128 v[202:205], v173 offset:22528
	ds_read_b128 v[206:209], v173 offset:23552
	global_load_lds_dwordx4 v[168:169], off
	s_add_i32 m0, s47, 0x2000
	s_add_u32 s48, s20, 0x20000
	v_lshl_add_u64 v[216:217], s[20:21], 0, v[146:147]
	s_addc_u32 s49, s21, 0
	s_add_i32 s47, s50, s38
	global_load_lds_dwordx4 v[216:217], off
	v_lshl_add_u64 v[220:221], s[48:49], 0, v[0:1]
	s_mov_b32 m0, s47
	v_lshl_add_u64 v[222:223], s[22:23], 0, v[148:149]
	global_load_lds_dwordx4 v[220:221], off
	v_lshl_add_u64 v[220:221], s[48:49], 0, v[146:147]
	s_add_i32 m0, s47, 0x2000
	s_nop 0
	global_load_lds_dwordx4 v[220:221], off
	v_lshl_add_u64 v[220:221], s[22:23], 0, v[150:151]
	s_mov_b32 m0, s17
	s_nop 0
	global_load_lds_dwordx4 v[220:221], off
	s_mov_b32 m0, s40
	s_nop 0
	global_load_lds_dwordx4 v[222:223], off
	s_waitcnt vmcnt(8)
	s_waitcnt lgkmcnt(0)
	s_setprio 1
	s_barrier
	v_mfma_f32_16x16x32_bf16 v[62:65], v[130:133], v[178:181], 0
	v_mfma_f32_16x16x32_bf16 v[58:61], v[138:141], v[178:181], 0
	v_mfma_f32_16x16x32_bf16 v[50:53], v[130:133], v[186:189], 0
	v_mfma_f32_16x16x32_bf16 v[42:45], v[138:141], v[186:189], 0
	v_mfma_f32_16x16x32_bf16 v[34:37], v[130:133], v[194:197], 0
	v_mfma_f32_16x16x32_bf16 v[26:29], v[138:141], v[194:197], 0
	v_mfma_f32_16x16x32_bf16 v[18:21], v[130:133], v[202:205], 0
	v_mfma_f32_16x16x32_bf16 v[10:13], v[138:141], v[202:205], 0
	v_mfma_f32_16x16x32_bf16 v[62:65], v[134:137], v[182:185], v[62:65]
	v_mfma_f32_16x16x32_bf16 v[58:61], v[142:145], v[182:185], v[58:61]
	v_mfma_f32_16x16x32_bf16 v[50:53], v[134:137], v[190:193], v[50:53]
	v_mfma_f32_16x16x32_bf16 v[42:45], v[142:145], v[190:193], v[42:45]
	v_mfma_f32_16x16x32_bf16 v[34:37], v[134:137], v[198:201], v[34:37]
	v_mfma_f32_16x16x32_bf16 v[26:29], v[142:145], v[198:201], v[26:29]
	v_mfma_f32_16x16x32_bf16 v[18:21], v[134:137], v[206:209], v[18:21]
	v_mfma_f32_16x16x32_bf16 v[10:13], v[142:145], v[206:209], v[10:13]
	s_setprio 0
	s_setprio 1
	v_mfma_f32_16x16x32_bf16 v[54:57], v[156:159], v[178:181], 0
	v_mfma_f32_16x16x32_bf16 v[46:49], v[164:167], v[178:181], 0
	v_mfma_f32_16x16x32_bf16 v[38:41], v[156:159], v[186:189], 0
	v_mfma_f32_16x16x32_bf16 v[30:33], v[164:167], v[186:189], 0
	v_mfma_f32_16x16x32_bf16 v[22:25], v[156:159], v[194:197], 0
	v_mfma_f32_16x16x32_bf16 v[14:17], v[164:167], v[194:197], 0
	v_mfma_f32_16x16x32_bf16 v[6:9], v[156:159], v[202:205], 0
	v_mfma_f32_16x16x32_bf16 v[2:5], v[164:167], v[202:205], 0
	v_mfma_f32_16x16x32_bf16 v[54:57], v[160:163], v[182:185], v[54:57]
	v_mfma_f32_16x16x32_bf16 v[46:49], v[174:177], v[182:185], v[46:49]
	v_mfma_f32_16x16x32_bf16 v[38:41], v[160:163], v[190:193], v[38:41]
	v_mfma_f32_16x16x32_bf16 v[30:33], v[174:177], v[190:193], v[30:33]
	v_mfma_f32_16x16x32_bf16 v[22:25], v[160:163], v[198:201], v[22:25]
	v_mfma_f32_16x16x32_bf16 v[14:17], v[174:177], v[198:201], v[14:17]
	v_mfma_f32_16x16x32_bf16 v[6:9], v[160:163], v[206:209], v[6:9]
	v_mfma_f32_16x16x32_bf16 v[2:5], v[174:177], v[206:209], v[2:5]
	s_barrier
	s_setprio 0
	s_add_i32 s47, 0, 0x18000
	s_add_i32 s48, 0, 0x1c000
	v_add_u32_e32 v142, s47, v171
	v_add_u32_e32 v174, s48, v171
	ds_read_b128 v[130:133], v142
	ds_read_b128 v[134:137], v142 offset:1024
	ds_read_b128 v[138:141], v142 offset:2048
	ds_read_b128 v[142:145], v142 offset:3072
	ds_read_b128 v[156:159], v174
	ds_read_b128 v[160:163], v174 offset:1024
	ds_read_b128 v[164:167], v174 offset:2048
	ds_read_b128 v[174:177], v174 offset:3072
	s_add_u32 s22, s22, 0x80000
	s_addc_u32 s23, s23, 0
	s_mov_b32 m0, s41
	v_lshl_add_u64 v[224:225], s[22:23], 0, v[150:151]
	ds_read_b128 v[178:181], v173 offset:32768
	ds_read_b128 v[182:185], v173 offset:33792
	ds_read_b128 v[186:189], v173 offset:34816
	ds_read_b128 v[190:193], v173 offset:35840
	ds_read_b128 v[194:197], v173 offset:36864
	ds_read_b128 v[198:201], v173 offset:37888
	ds_read_b128 v[202:205], v173 offset:38912
	ds_read_b128 v[206:209], v173 offset:39936
	global_load_lds_dwordx4 v[224:225], off
	v_lshl_add_u64 v[224:225], s[22:23], 0, v[148:149]
	s_mov_b32 m0, s42
	s_nop 0
	global_load_lds_dwordx4 v[224:225], off
	s_waitcnt vmcnt(8)
	s_waitcnt lgkmcnt(0)
	s_setprio 1
	s_barrier
	v_mfma_f32_16x16x32_bf16 v[126:129], v[130:133], v[178:181], v[126:129]
	v_mfma_f32_16x16x32_bf16 v[122:125], v[138:141], v[178:181], v[122:125]
	v_mfma_f32_16x16x32_bf16 v[118:121], v[130:133], v[186:189], v[118:121]
	v_mfma_f32_16x16x32_bf16 v[106:109], v[138:141], v[186:189], v[106:109]
	v_mfma_f32_16x16x32_bf16 v[98:101], v[130:133], v[194:197], v[98:101]
	v_mfma_f32_16x16x32_bf16 v[90:93], v[138:141], v[194:197], v[90:93]
	v_mfma_f32_16x16x32_bf16 v[82:85], v[130:133], v[202:205], v[82:85]
	v_mfma_f32_16x16x32_bf16 v[74:77], v[138:141], v[202:205], v[74:77]
	v_mfma_f32_16x16x32_bf16 v[126:129], v[134:137], v[182:185], v[126:129]
	v_mfma_f32_16x16x32_bf16 v[122:125], v[142:145], v[182:185], v[122:125]
	v_mfma_f32_16x16x32_bf16 v[118:121], v[134:137], v[190:193], v[118:121]
	v_mfma_f32_16x16x32_bf16 v[106:109], v[142:145], v[190:193], v[106:109]
	v_mfma_f32_16x16x32_bf16 v[98:101], v[134:137], v[198:201], v[98:101]
	v_mfma_f32_16x16x32_bf16 v[90:93], v[142:145], v[198:201], v[90:93]
	v_mfma_f32_16x16x32_bf16 v[82:85], v[134:137], v[206:209], v[82:85]
	v_mfma_f32_16x16x32_bf16 v[74:77], v[142:145], v[206:209], v[74:77]
	s_setprio 0
	s_setprio 1
	v_mfma_f32_16x16x32_bf16 v[114:117], v[156:159], v[178:181], v[114:117]
	v_mfma_f32_16x16x32_bf16 v[110:113], v[164:167], v[178:181], v[110:113]
	v_mfma_f32_16x16x32_bf16 v[102:105], v[156:159], v[186:189], v[102:105]
	v_mfma_f32_16x16x32_bf16 v[94:97], v[164:167], v[186:189], v[94:97]
	v_mfma_f32_16x16x32_bf16 v[86:89], v[156:159], v[194:197], v[86:89]
	v_mfma_f32_16x16x32_bf16 v[78:81], v[164:167], v[194:197], v[78:81]
	v_mfma_f32_16x16x32_bf16 v[70:73], v[156:159], v[202:205], v[70:73]
	v_mfma_f32_16x16x32_bf16 v[66:69], v[164:167], v[202:205], v[66:69]
	v_mfma_f32_16x16x32_bf16 v[114:117], v[160:163], v[182:185], v[114:117]
	v_mfma_f32_16x16x32_bf16 v[110:113], v[174:177], v[182:185], v[110:113]
	v_mfma_f32_16x16x32_bf16 v[102:105], v[160:163], v[190:193], v[102:105]
	v_mfma_f32_16x16x32_bf16 v[94:97], v[174:177], v[190:193], v[94:97]
	v_mfma_f32_16x16x32_bf16 v[86:89], v[160:163], v[198:201], v[86:89]
	v_mfma_f32_16x16x32_bf16 v[78:81], v[174:177], v[198:201], v[78:81]
	v_mfma_f32_16x16x32_bf16 v[70:73], v[160:163], v[206:209], v[70:73]
	v_mfma_f32_16x16x32_bf16 v[66:69], v[174:177], v[206:209], v[66:69]
	s_barrier
	s_setprio 0
	s_add_i32 s22, s47, s38
	v_lshl_add_u64 v[168:169], v[168:169], 0, s[2:3]
	s_mov_b32 m0, s22
	ds_read_b128 v[178:181], v173 offset:49152
	ds_read_b128 v[182:185], v173 offset:50176
	ds_read_b128 v[186:189], v173 offset:51200
	ds_read_b128 v[190:193], v173 offset:52224
	ds_read_b128 v[194:197], v173 offset:53248
	ds_read_b128 v[198:201], v173 offset:54272
	ds_read_b128 v[202:205], v173 offset:55296
	ds_read_b128 v[206:209], v173 offset:56320
	global_load_lds_dwordx4 v[168:169], off
	s_add_i32 m0, s22, 0x2000
	s_add_u32 s20, s20, 0x20080
	v_lshl_add_u64 v[168:169], v[216:217], 0, s[2:3]
	s_addc_u32 s21, s21, 0
	s_add_i32 s22, s48, s38
	global_load_lds_dwordx4 v[168:169], off
	v_lshl_add_u64 v[168:169], s[20:21], 0, v[0:1]
	s_mov_b32 m0, s22
	s_nop 0
	global_load_lds_dwordx4 v[168:169], off
	v_lshl_add_u64 v[168:169], s[20:21], 0, v[146:147]
	s_add_i32 m0, s22, 0x2000
	s_nop 0
	global_load_lds_dwordx4 v[168:169], off
	v_lshl_add_u64 v[168:169], v[220:221], 0, s[2:3]
	s_mov_b32 m0, s43
	s_nop 0
	global_load_lds_dwordx4 v[168:169], off
	v_lshl_add_u64 v[168:169], v[222:223], 0, s[2:3]
	s_mov_b32 m0, s44
	s_nop 0
	global_load_lds_dwordx4 v[168:169], off
	s_waitcnt vmcnt(8)
	s_waitcnt lgkmcnt(0)
	s_setprio 1
	s_barrier
	v_mfma_f32_16x16x32_bf16 v[62:65], v[130:133], v[178:181], v[62:65]
	v_mfma_f32_16x16x32_bf16 v[58:61], v[138:141], v[178:181], v[58:61]
	v_mfma_f32_16x16x32_bf16 v[50:53], v[130:133], v[186:189], v[50:53]
	v_mfma_f32_16x16x32_bf16 v[42:45], v[138:141], v[186:189], v[42:45]
	v_mfma_f32_16x16x32_bf16 v[34:37], v[130:133], v[194:197], v[34:37]
	v_mfma_f32_16x16x32_bf16 v[26:29], v[138:141], v[194:197], v[26:29]
	v_mfma_f32_16x16x32_bf16 v[18:21], v[130:133], v[202:205], v[18:21]
	v_mfma_f32_16x16x32_bf16 v[10:13], v[138:141], v[202:205], v[10:13]
	v_mfma_f32_16x16x32_bf16 v[62:65], v[134:137], v[182:185], v[62:65]
	v_mfma_f32_16x16x32_bf16 v[58:61], v[142:145], v[182:185], v[58:61]
	v_mfma_f32_16x16x32_bf16 v[50:53], v[134:137], v[190:193], v[50:53]
	v_mfma_f32_16x16x32_bf16 v[42:45], v[142:145], v[190:193], v[42:45]
	v_mfma_f32_16x16x32_bf16 v[34:37], v[134:137], v[198:201], v[34:37]
	v_mfma_f32_16x16x32_bf16 v[26:29], v[142:145], v[198:201], v[26:29]
	v_mfma_f32_16x16x32_bf16 v[18:21], v[134:137], v[206:209], v[18:21]
	v_mfma_f32_16x16x32_bf16 v[10:13], v[142:145], v[206:209], v[10:13]
	s_setprio 0
	s_setprio 1
	v_mfma_f32_16x16x32_bf16 v[54:57], v[156:159], v[178:181], v[54:57]
	v_mfma_f32_16x16x32_bf16 v[46:49], v[164:167], v[178:181], v[46:49]
	v_mfma_f32_16x16x32_bf16 v[38:41], v[156:159], v[186:189], v[38:41]
	v_mfma_f32_16x16x32_bf16 v[30:33], v[164:167], v[186:189], v[30:33]
	v_mfma_f32_16x16x32_bf16 v[22:25], v[156:159], v[194:197], v[22:25]
	v_mfma_f32_16x16x32_bf16 v[14:17], v[164:167], v[194:197], v[14:17]
	v_mfma_f32_16x16x32_bf16 v[6:9], v[156:159], v[202:205], v[6:9]
	v_mfma_f32_16x16x32_bf16 v[2:5], v[164:167], v[202:205], v[2:5]
	v_mfma_f32_16x16x32_bf16 v[54:57], v[160:163], v[182:185], v[54:57]
	v_mfma_f32_16x16x32_bf16 v[46:49], v[174:177], v[182:185], v[46:49]
	v_mfma_f32_16x16x32_bf16 v[38:41], v[160:163], v[190:193], v[38:41]
	v_mfma_f32_16x16x32_bf16 v[30:33], v[174:177], v[190:193], v[30:33]
	v_mfma_f32_16x16x32_bf16 v[22:25], v[160:163], v[198:201], v[22:25]
	v_mfma_f32_16x16x32_bf16 v[14:17], v[174:177], v[198:201], v[14:17]
	v_mfma_f32_16x16x32_bf16 v[6:9], v[160:163], v[206:209], v[6:9]
	v_mfma_f32_16x16x32_bf16 v[2:5], v[174:177], v[206:209], v[2:5]
	s_barrier
	s_setprio 0
	s_add_i32 s37, s37, 2
	s_add_u32 s18, s18, 0x100
	s_addc_u32 s19, s19, 0
	s_add_u32 s15, s15, 0x100
	s_addc_u32 s36, s36, 0
	s_cmp_gt_u32 s37, 5
	s_cbranch_scc1 .Lpeel_done_3
.LBB0_1201:
	s_add_u32 s20, s18, 0xfff80080
	s_addc_u32 s21, s19, -1
	s_add_i32 s47, 0, 0x10000
	s_cmp_eq_u32 s37, 4
	s_cselect_b32 s23, s11, s21
	s_cselect_b32 s22, s10, s20
	s_cselect_b32 s21, s7, s36
	s_cselect_b32 s20, s9, s15
	s_add_i32 s50, 0, 0x14000
	v_add_u32_e32 v142, s47, v171
	v_add_u32_e32 v168, s50, v171
	ds_read_b128 v[130:133], v142
	ds_read_b128 v[134:137], v142 offset:1024
	ds_read_b128 v[138:141], v142 offset:2048
	ds_read_b128 v[142:145], v142 offset:3072
	ds_read_b128 v[156:159], v168
	ds_read_b128 v[160:163], v168 offset:1024
	ds_read_b128 v[164:167], v168 offset:2048
	ds_read_b128 v[174:177], v168 offset:3072
	v_lshl_add_u64 v[168:169], s[18:19], 0, v[152:153]
	s_add_i32 m0, s17, 0xc000
	ds_read_b128 v[178:181], v173
	ds_read_b128 v[182:185], v173 offset:1024
	ds_read_b128 v[186:189], v173 offset:2048
	ds_read_b128 v[190:193], v173 offset:3072
	ds_read_b128 v[194:197], v173 offset:4096
	ds_read_b128 v[198:201], v173 offset:5120
	ds_read_b128 v[202:205], v173 offset:6144
	ds_read_b128 v[206:209], v173 offset:7168
	global_load_lds_dwordx4 v[168:169], off
	v_lshl_add_u64 v[168:169], s[18:19], 0, v[154:155]
	s_add_i32 m0, s17, 0xe000
	s_nop 0
	global_load_lds_dwordx4 v[168:169], off
	s_waitcnt vmcnt(8)
	s_waitcnt lgkmcnt(0)
	s_setprio 1
	s_barrier
	v_mfma_f32_16x16x32_bf16 v[126:129], v[130:133], v[178:181], v[126:129]
	v_mfma_f32_16x16x32_bf16 v[122:125], v[138:141], v[178:181], v[122:125]
	v_mfma_f32_16x16x32_bf16 v[118:121], v[130:133], v[186:189], v[118:121]
	v_mfma_f32_16x16x32_bf16 v[106:109], v[138:141], v[186:189], v[106:109]
	v_mfma_f32_16x16x32_bf16 v[98:101], v[130:133], v[194:197], v[98:101]
	v_mfma_f32_16x16x32_bf16 v[90:93], v[138:141], v[194:197], v[90:93]
	v_mfma_f32_16x16x32_bf16 v[82:85], v[130:133], v[202:205], v[82:85]
	v_mfma_f32_16x16x32_bf16 v[74:77], v[138:141], v[202:205], v[74:77]
	v_mfma_f32_16x16x32_bf16 v[126:129], v[134:137], v[182:185], v[126:129]
	v_mfma_f32_16x16x32_bf16 v[122:125], v[142:145], v[182:185], v[122:125]
	v_mfma_f32_16x16x32_bf16 v[118:121], v[134:137], v[190:193], v[118:121]
	v_mfma_f32_16x16x32_bf16 v[106:109], v[142:145], v[190:193], v[106:109]
	v_mfma_f32_16x16x32_bf16 v[98:101], v[134:137], v[198:201], v[98:101]
	v_mfma_f32_16x16x32_bf16 v[90:93], v[142:145], v[198:201], v[90:93]
	v_mfma_f32_16x16x32_bf16 v[82:85], v[134:137], v[206:209], v[82:85]
	v_mfma_f32_16x16x32_bf16 v[74:77], v[142:145], v[206:209], v[74:77]
	s_setprio 0
	s_setprio 1
	v_mfma_f32_16x16x32_bf16 v[114:117], v[156:159], v[178:181], v[114:117]
	v_mfma_f32_16x16x32_bf16 v[110:113], v[164:167], v[178:181], v[110:113]
	v_mfma_f32_16x16x32_bf16 v[102:105], v[156:159], v[186:189], v[102:105]
	v_mfma_f32_16x16x32_bf16 v[94:97], v[164:167], v[186:189], v[94:97]
	v_mfma_f32_16x16x32_bf16 v[86:89], v[156:159], v[194:197], v[86:89]
	v_mfma_f32_16x16x32_bf16 v[78:81], v[164:167], v[194:197], v[78:81]
	v_mfma_f32_16x16x32_bf16 v[70:73], v[156:159], v[202:205], v[70:73]
	v_mfma_f32_16x16x32_bf16 v[66:69], v[164:167], v[202:205], v[66:69]
	v_mfma_f32_16x16x32_bf16 v[114:117], v[160:163], v[182:185], v[114:117]
	v_mfma_f32_16x16x32_bf16 v[110:113], v[174:177], v[182:185], v[110:113]
	v_mfma_f32_16x16x32_bf16 v[102:105], v[160:163], v[190:193], v[102:105]
	v_mfma_f32_16x16x32_bf16 v[94:97], v[174:177], v[190:193], v[94:97]
	v_mfma_f32_16x16x32_bf16 v[86:89], v[160:163], v[198:201], v[86:89]
	v_mfma_f32_16x16x32_bf16 v[78:81], v[174:177], v[198:201], v[78:81]
	v_mfma_f32_16x16x32_bf16 v[70:73], v[160:163], v[206:209], v[70:73]
	v_mfma_f32_16x16x32_bf16 v[66:69], v[174:177], v[206:209], v[66:69]
	s_barrier
	s_setprio 0
	s_add_i32 s47, s47, s38
	v_lshl_add_u64 v[168:169], s[20:21], 0, v[0:1]
	s_mov_b32 m0, s47
	ds_read_b128 v[178:181], v173 offset:16384
	ds_read_b128 v[182:185], v173 offset:17408
	ds_read_b128 v[186:189], v173 offset:18432
	ds_read_b128 v[190:193], v173 offset:19456
	ds_read_b128 v[194:197], v173 offset:20480
	ds_read_b128 v[198:201], v173 offset:21504
	ds_read_b128 v[202:205], v173 offset:22528
	ds_read_b128 v[206:209], v173 offset:23552
	global_load_lds_dwordx4 v[168:169], off
	s_add_i32 m0, s47, 0x2000
	s_add_u32 s48, s20, 0x20000
	v_lshl_add_u64 v[216:217], s[20:21], 0, v[146:147]
	s_addc_u32 s49, s21, 0
	s_add_i32 s47, s50, s38
	global_load_lds_dwordx4 v[216:217], off
	v_lshl_add_u64 v[220:221], s[48:49], 0, v[0:1]
	s_mov_b32 m0, s47
	v_lshl_add_u64 v[222:223], s[22:23], 0, v[148:149]
	global_load_lds_dwordx4 v[220:221], off
	v_lshl_add_u64 v[220:221], s[48:49], 0, v[146:147]
	s_add_i32 m0, s47, 0x2000
	s_nop 0
	global_load_lds_dwordx4 v[220:221], off
	v_lshl_add_u64 v[220:221], s[22:23], 0, v[150:151]
	s_mov_b32 m0, s17
	s_nop 0
	global_load_lds_dwordx4 v[220:221], off
	s_mov_b32 m0, s40
	s_nop 0
	global_load_lds_dwordx4 v[222:223], off
	s_waitcnt vmcnt(8)
	s_waitcnt lgkmcnt(0)
	s_setprio 1
	s_barrier
	v_mfma_f32_16x16x32_bf16 v[62:65], v[130:133], v[178:181], v[62:65]
	v_mfma_f32_16x16x32_bf16 v[58:61], v[138:141], v[178:181], v[58:61]
	v_mfma_f32_16x16x32_bf16 v[50:53], v[130:133], v[186:189], v[50:53]
	v_mfma_f32_16x16x32_bf16 v[42:45], v[138:141], v[186:189], v[42:45]
	v_mfma_f32_16x16x32_bf16 v[34:37], v[130:133], v[194:197], v[34:37]
	v_mfma_f32_16x16x32_bf16 v[26:29], v[138:141], v[194:197], v[26:29]
	v_mfma_f32_16x16x32_bf16 v[18:21], v[130:133], v[202:205], v[18:21]
	v_mfma_f32_16x16x32_bf16 v[10:13], v[138:141], v[202:205], v[10:13]
	v_mfma_f32_16x16x32_bf16 v[62:65], v[134:137], v[182:185], v[62:65]
	v_mfma_f32_16x16x32_bf16 v[58:61], v[142:145], v[182:185], v[58:61]
	v_mfma_f32_16x16x32_bf16 v[50:53], v[134:137], v[190:193], v[50:53]
	v_mfma_f32_16x16x32_bf16 v[42:45], v[142:145], v[190:193], v[42:45]
	v_mfma_f32_16x16x32_bf16 v[34:37], v[134:137], v[198:201], v[34:37]
	v_mfma_f32_16x16x32_bf16 v[26:29], v[142:145], v[198:201], v[26:29]
	v_mfma_f32_16x16x32_bf16 v[18:21], v[134:137], v[206:209], v[18:21]
	v_mfma_f32_16x16x32_bf16 v[10:13], v[142:145], v[206:209], v[10:13]
	s_setprio 0
	s_setprio 1
	v_mfma_f32_16x16x32_bf16 v[54:57], v[156:159], v[178:181], v[54:57]
	v_mfma_f32_16x16x32_bf16 v[46:49], v[164:167], v[178:181], v[46:49]
	v_mfma_f32_16x16x32_bf16 v[38:41], v[156:159], v[186:189], v[38:41]
	v_mfma_f32_16x16x32_bf16 v[30:33], v[164:167], v[186:189], v[30:33]
	v_mfma_f32_16x16x32_bf16 v[22:25], v[156:159], v[194:197], v[22:25]
	v_mfma_f32_16x16x32_bf16 v[14:17], v[164:167], v[194:197], v[14:17]
	v_mfma_f32_16x16x32_bf16 v[6:9], v[156:159], v[202:205], v[6:9]
	v_mfma_f32_16x16x32_bf16 v[2:5], v[164:167], v[202:205], v[2:5]
	v_mfma_f32_16x16x32_bf16 v[54:57], v[160:163], v[182:185], v[54:57]
	v_mfma_f32_16x16x32_bf16 v[46:49], v[174:177], v[182:185], v[46:49]
	v_mfma_f32_16x16x32_bf16 v[38:41], v[160:163], v[190:193], v[38:41]
	v_mfma_f32_16x16x32_bf16 v[30:33], v[174:177], v[190:193], v[30:33]
	v_mfma_f32_16x16x32_bf16 v[22:25], v[160:163], v[198:201], v[22:25]
	v_mfma_f32_16x16x32_bf16 v[14:17], v[174:177], v[198:201], v[14:17]
	v_mfma_f32_16x16x32_bf16 v[6:9], v[160:163], v[206:209], v[6:9]
	v_mfma_f32_16x16x32_bf16 v[2:5], v[174:177], v[206:209], v[2:5]
	s_barrier
	s_setprio 0
	s_add_i32 s47, 0, 0x18000
	s_add_i32 s48, 0, 0x1c000
	v_add_u32_e32 v142, s47, v171
	v_add_u32_e32 v174, s48, v171
	ds_read_b128 v[130:133], v142
	ds_read_b128 v[134:137], v142 offset:1024
	ds_read_b128 v[138:141], v142 offset:2048
	ds_read_b128 v[142:145], v142 offset:3072
	ds_read_b128 v[156:159], v174
	ds_read_b128 v[160:163], v174 offset:1024
	ds_read_b128 v[164:167], v174 offset:2048
	ds_read_b128 v[174:177], v174 offset:3072
	s_add_u32 s22, s22, 0x80000
	s_addc_u32 s23, s23, 0
	s_mov_b32 m0, s41
	v_lshl_add_u64 v[224:225], s[22:23], 0, v[150:151]
	ds_read_b128 v[178:181], v173 offset:32768
	ds_read_b128 v[182:185], v173 offset:33792
	ds_read_b128 v[186:189], v173 offset:34816
	ds_read_b128 v[190:193], v173 offset:35840
	ds_read_b128 v[194:197], v173 offset:36864
	ds_read_b128 v[198:201], v173 offset:37888
	ds_read_b128 v[202:205], v173 offset:38912
	ds_read_b128 v[206:209], v173 offset:39936
	global_load_lds_dwordx4 v[224:225], off
	v_lshl_add_u64 v[224:225], s[22:23], 0, v[148:149]
	s_mov_b32 m0, s42
	s_nop 0
	global_load_lds_dwordx4 v[224:225], off
	s_waitcnt vmcnt(8)
	s_waitcnt lgkmcnt(0)
	s_setprio 1
	s_barrier
	v_mfma_f32_16x16x32_bf16 v[126:129], v[130:133], v[178:181], v[126:129]
	v_mfma_f32_16x16x32_bf16 v[122:125], v[138:141], v[178:181], v[122:125]
	v_mfma_f32_16x16x32_bf16 v[118:121], v[130:133], v[186:189], v[118:121]
	v_mfma_f32_16x16x32_bf16 v[106:109], v[138:141], v[186:189], v[106:109]
	v_mfma_f32_16x16x32_bf16 v[98:101], v[130:133], v[194:197], v[98:101]
	v_mfma_f32_16x16x32_bf16 v[90:93], v[138:141], v[194:197], v[90:93]
	v_mfma_f32_16x16x32_bf16 v[82:85], v[130:133], v[202:205], v[82:85]
	v_mfma_f32_16x16x32_bf16 v[74:77], v[138:141], v[202:205], v[74:77]
	v_mfma_f32_16x16x32_bf16 v[126:129], v[134:137], v[182:185], v[126:129]
	v_mfma_f32_16x16x32_bf16 v[122:125], v[142:145], v[182:185], v[122:125]
	v_mfma_f32_16x16x32_bf16 v[118:121], v[134:137], v[190:193], v[118:121]
	v_mfma_f32_16x16x32_bf16 v[106:109], v[142:145], v[190:193], v[106:109]
	v_mfma_f32_16x16x32_bf16 v[98:101], v[134:137], v[198:201], v[98:101]
	v_mfma_f32_16x16x32_bf16 v[90:93], v[142:145], v[198:201], v[90:93]
	v_mfma_f32_16x16x32_bf16 v[82:85], v[134:137], v[206:209], v[82:85]
	v_mfma_f32_16x16x32_bf16 v[74:77], v[142:145], v[206:209], v[74:77]
	s_setprio 0
	s_setprio 1
	v_mfma_f32_16x16x32_bf16 v[114:117], v[156:159], v[178:181], v[114:117]
	v_mfma_f32_16x16x32_bf16 v[110:113], v[164:167], v[178:181], v[110:113]
	v_mfma_f32_16x16x32_bf16 v[102:105], v[156:159], v[186:189], v[102:105]
	v_mfma_f32_16x16x32_bf16 v[94:97], v[164:167], v[186:189], v[94:97]
	v_mfma_f32_16x16x32_bf16 v[86:89], v[156:159], v[194:197], v[86:89]
	v_mfma_f32_16x16x32_bf16 v[78:81], v[164:167], v[194:197], v[78:81]
	v_mfma_f32_16x16x32_bf16 v[70:73], v[156:159], v[202:205], v[70:73]
	v_mfma_f32_16x16x32_bf16 v[66:69], v[164:167], v[202:205], v[66:69]
	v_mfma_f32_16x16x32_bf16 v[114:117], v[160:163], v[182:185], v[114:117]
	v_mfma_f32_16x16x32_bf16 v[110:113], v[174:177], v[182:185], v[110:113]
	v_mfma_f32_16x16x32_bf16 v[102:105], v[160:163], v[190:193], v[102:105]
	v_mfma_f32_16x16x32_bf16 v[94:97], v[174:177], v[190:193], v[94:97]
	v_mfma_f32_16x16x32_bf16 v[86:89], v[160:163], v[198:201], v[86:89]
	v_mfma_f32_16x16x32_bf16 v[78:81], v[174:177], v[198:201], v[78:81]
	v_mfma_f32_16x16x32_bf16 v[70:73], v[160:163], v[206:209], v[70:73]
	v_mfma_f32_16x16x32_bf16 v[66:69], v[174:177], v[206:209], v[66:69]
	s_barrier
	s_setprio 0
	s_add_i32 s22, s47, s38
	v_lshl_add_u64 v[168:169], v[168:169], 0, s[2:3]
	s_mov_b32 m0, s22
	ds_read_b128 v[178:181], v173 offset:49152
	ds_read_b128 v[182:185], v173 offset:50176
	ds_read_b128 v[186:189], v173 offset:51200
	ds_read_b128 v[190:193], v173 offset:52224
	ds_read_b128 v[194:197], v173 offset:53248
	ds_read_b128 v[198:201], v173 offset:54272
	ds_read_b128 v[202:205], v173 offset:55296
	ds_read_b128 v[206:209], v173 offset:56320
	global_load_lds_dwordx4 v[168:169], off
	s_add_i32 m0, s22, 0x2000
	s_add_u32 s20, s20, 0x20080
	v_lshl_add_u64 v[168:169], v[216:217], 0, s[2:3]
	s_addc_u32 s21, s21, 0
	s_add_i32 s22, s48, s38
	global_load_lds_dwordx4 v[168:169], off
	v_lshl_add_u64 v[168:169], s[20:21], 0, v[0:1]
	s_mov_b32 m0, s22
	s_nop 0
	global_load_lds_dwordx4 v[168:169], off
	v_lshl_add_u64 v[168:169], s[20:21], 0, v[146:147]
	s_add_i32 m0, s22, 0x2000
	s_nop 0
	global_load_lds_dwordx4 v[168:169], off
	v_lshl_add_u64 v[168:169], v[220:221], 0, s[2:3]
	s_mov_b32 m0, s43
	s_nop 0
	global_load_lds_dwordx4 v[168:169], off
	v_lshl_add_u64 v[168:169], v[222:223], 0, s[2:3]
	s_mov_b32 m0, s44
	s_nop 0
	global_load_lds_dwordx4 v[168:169], off
	s_waitcnt vmcnt(8)
	s_waitcnt lgkmcnt(0)
	s_setprio 1
	s_barrier
	v_mfma_f32_16x16x32_bf16 v[62:65], v[130:133], v[178:181], v[62:65]
	v_mfma_f32_16x16x32_bf16 v[58:61], v[138:141], v[178:181], v[58:61]
	v_mfma_f32_16x16x32_bf16 v[50:53], v[130:133], v[186:189], v[50:53]
	v_mfma_f32_16x16x32_bf16 v[42:45], v[138:141], v[186:189], v[42:45]
	v_mfma_f32_16x16x32_bf16 v[34:37], v[130:133], v[194:197], v[34:37]
	v_mfma_f32_16x16x32_bf16 v[26:29], v[138:141], v[194:197], v[26:29]
	v_mfma_f32_16x16x32_bf16 v[18:21], v[130:133], v[202:205], v[18:21]
	v_mfma_f32_16x16x32_bf16 v[10:13], v[138:141], v[202:205], v[10:13]
	v_mfma_f32_16x16x32_bf16 v[62:65], v[134:137], v[182:185], v[62:65]
	v_mfma_f32_16x16x32_bf16 v[58:61], v[142:145], v[182:185], v[58:61]
	v_mfma_f32_16x16x32_bf16 v[50:53], v[134:137], v[190:193], v[50:53]
	v_mfma_f32_16x16x32_bf16 v[42:45], v[142:145], v[190:193], v[42:45]
	v_mfma_f32_16x16x32_bf16 v[34:37], v[134:137], v[198:201], v[34:37]
	v_mfma_f32_16x16x32_bf16 v[26:29], v[142:145], v[198:201], v[26:29]
	v_mfma_f32_16x16x32_bf16 v[18:21], v[134:137], v[206:209], v[18:21]
	v_mfma_f32_16x16x32_bf16 v[10:13], v[142:145], v[206:209], v[10:13]
	s_setprio 0
	s_setprio 1
	v_mfma_f32_16x16x32_bf16 v[54:57], v[156:159], v[178:181], v[54:57]
	v_mfma_f32_16x16x32_bf16 v[46:49], v[164:167], v[178:181], v[46:49]
	v_mfma_f32_16x16x32_bf16 v[38:41], v[156:159], v[186:189], v[38:41]
	v_mfma_f32_16x16x32_bf16 v[30:33], v[164:167], v[186:189], v[30:33]
	v_mfma_f32_16x16x32_bf16 v[22:25], v[156:159], v[194:197], v[22:25]
	v_mfma_f32_16x16x32_bf16 v[14:17], v[164:167], v[194:197], v[14:17]
	v_mfma_f32_16x16x32_bf16 v[6:9], v[156:159], v[202:205], v[6:9]
	v_mfma_f32_16x16x32_bf16 v[2:5], v[164:167], v[202:205], v[2:5]
	v_mfma_f32_16x16x32_bf16 v[54:57], v[160:163], v[182:185], v[54:57]
	v_mfma_f32_16x16x32_bf16 v[46:49], v[174:177], v[182:185], v[46:49]
	v_mfma_f32_16x16x32_bf16 v[38:41], v[160:163], v[190:193], v[38:41]
	v_mfma_f32_16x16x32_bf16 v[30:33], v[174:177], v[190:193], v[30:33]
	v_mfma_f32_16x16x32_bf16 v[22:25], v[160:163], v[198:201], v[22:25]
	v_mfma_f32_16x16x32_bf16 v[14:17], v[174:177], v[198:201], v[14:17]
	v_mfma_f32_16x16x32_bf16 v[6:9], v[160:163], v[206:209], v[6:9]
	v_mfma_f32_16x16x32_bf16 v[2:5], v[174:177], v[206:209], v[2:5]
	s_barrier
	s_setprio 0
	s_add_i32 s37, s37, 2
	s_add_u32 s18, s18, 0x100
	s_addc_u32 s19, s19, 0
	s_add_u32 s15, s15, 0x100
	s_addc_u32 s36, s36, 0
	s_cmp_gt_u32 s37, 5
	s_cbranch_scc0 .LBB0_1201

.LBB0_1564:
	s_ashr_i32 s9, s8, 31
	s_lshl_b64 s[10:11], s[8:9], 20
	v_readlane_b32 s12, v253, 25
	v_readlane_b32 s13, v253, 26
	s_add_u32 s10, s12, s10
	s_addc_u32 s11, s13, s11
	s_and_b64 s[12:13], s[34:35], exec
	s_cselect_b32 s9, s11, s19
	s_cselect_b32 s15, s10, s18
	s_ashr_i32 s7, s6, 31
	s_lshl_b64 s[12:13], s[6:7], 20
	s_add_u32 s12, s37, s12
	s_addc_u32 s13, s38, s13
	s_and_b64 s[22:23], s[34:35], exec
	s_cselect_b32 s7, s13, s21
	s_cselect_b32 s50, s12, s20
	s_add_u32 s18, s18, 0x80080
	s_addc_u32 s19, s19, 0
	s_add_u32 s51, s20, 0x100
	s_addc_u32 s52, s21, 0
	s_mov_b32 s53, -2
	s_add_u32 s20, s18, 0xfff80080
	s_addc_u32 s21, s19, -1
	s_add_i32 s54, 0, 0x10000
	s_cmp_eq_u32 s53, 28
	s_cselect_b32 s23, s9, s21
	s_cselect_b32 s22, s15, s20
	v_add_u32_e32 v158, s54, v160
	s_cselect_b32 s21, s7, s52
	s_cselect_b32 s20, s50, s51
	s_add_i32 s56, 0, 0x14000
	ds_read_b128 v[164:167], v158
	ds_read_b128 v[168:171], v158 offset:1024
	ds_read_b128 v[172:175], v158 offset:2048
	ds_read_b128 v[176:179], v158 offset:3072
	v_add_u32_e32 v158, s56, v160
	ds_read_b128 v[180:183], v158
	ds_read_b128 v[184:187], v158 offset:1024
	ds_read_b128 v[188:191], v158 offset:2048
	ds_read_b128 v[192:195], v158 offset:3072
	v_lshl_add_u64 v[158:159], s[18:19], 0, v[154:155]
	s_add_i32 m0, s17, 0xc000
	ds_read_b128 v[196:199], v162
	ds_read_b128 v[200:203], v162 offset:1024
	ds_read_b128 v[204:207], v162 offset:2048
	ds_read_b128 v[220:223], v162 offset:3072
	ds_read_b128 v[224:227], v162 offset:4096
	ds_read_b128 v[228:231], v162 offset:5120
	ds_read_b128 v[232:235], v162 offset:6144
	ds_read_b128 v[236:239], v162 offset:7168
	global_load_lds_dwordx4 v[158:159], off
	v_lshl_add_u64 v[158:159], s[18:19], 0, v[156:157]
	s_add_i32 m0, s17, 0xe000
	s_nop 0
	global_load_lds_dwordx4 v[158:159], off
	s_waitcnt vmcnt(8)
	s_waitcnt lgkmcnt(0)
	s_setprio 1
	s_barrier
	v_mfma_f32_16x16x32_bf16 v[122:125], v[164:167], v[196:199], 0
	v_mfma_f32_16x16x32_bf16 v[114:117], v[172:175], v[196:199], 0
	v_mfma_f32_16x16x32_bf16 v[106:109], v[164:167], v[204:207], 0
	v_mfma_f32_16x16x32_bf16 v[98:101], v[172:175], v[204:207], 0
	v_mfma_f32_16x16x32_bf16 v[90:93], v[164:167], v[224:227], 0
	v_mfma_f32_16x16x32_bf16 v[82:85], v[172:175], v[224:227], 0
	v_mfma_f32_16x16x32_bf16 v[74:77], v[164:167], v[232:235], 0
	v_mfma_f32_16x16x32_bf16 v[66:69], v[172:175], v[232:235], 0
	v_mfma_f32_16x16x32_bf16 v[122:125], v[168:171], v[200:203], v[122:125]
	v_mfma_f32_16x16x32_bf16 v[114:117], v[176:179], v[200:203], v[114:117]
	v_mfma_f32_16x16x32_bf16 v[106:109], v[168:171], v[220:223], v[106:109]
	v_mfma_f32_16x16x32_bf16 v[98:101], v[176:179], v[220:223], v[98:101]
	v_mfma_f32_16x16x32_bf16 v[90:93], v[168:171], v[228:231], v[90:93]
	v_mfma_f32_16x16x32_bf16 v[82:85], v[176:179], v[228:231], v[82:85]
	v_mfma_f32_16x16x32_bf16 v[74:77], v[168:171], v[236:239], v[74:77]
	v_mfma_f32_16x16x32_bf16 v[66:69], v[176:179], v[236:239], v[66:69]
	s_setprio 0
	s_setprio 1
	v_mfma_f32_16x16x32_bf16 v[126:129], v[180:183], v[196:199], 0
	v_mfma_f32_16x16x32_bf16 v[118:121], v[188:191], v[196:199], 0
	v_mfma_f32_16x16x32_bf16 v[110:113], v[180:183], v[204:207], 0
	v_mfma_f32_16x16x32_bf16 v[102:105], v[188:191], v[204:207], 0
	v_mfma_f32_16x16x32_bf16 v[94:97], v[180:183], v[224:227], 0
	v_mfma_f32_16x16x32_bf16 v[86:89], v[188:191], v[224:227], 0
	v_mfma_f32_16x16x32_bf16 v[78:81], v[180:183], v[232:235], 0
	v_mfma_f32_16x16x32_bf16 v[70:73], v[188:191], v[232:235], 0
	v_mfma_f32_16x16x32_bf16 v[126:129], v[184:187], v[200:203], v[126:129]
	v_mfma_f32_16x16x32_bf16 v[118:121], v[192:195], v[200:203], v[118:121]
	v_mfma_f32_16x16x32_bf16 v[110:113], v[184:187], v[220:223], v[110:113]
	v_mfma_f32_16x16x32_bf16 v[102:105], v[192:195], v[220:223], v[102:105]
	v_mfma_f32_16x16x32_bf16 v[94:97], v[184:187], v[228:231], v[94:97]
	v_mfma_f32_16x16x32_bf16 v[86:89], v[192:195], v[228:231], v[86:89]
	v_mfma_f32_16x16x32_bf16 v[78:81], v[184:187], v[236:239], v[78:81]
	v_mfma_f32_16x16x32_bf16 v[70:73], v[192:195], v[236:239], v[70:73]
	s_barrier
	s_setprio 0
	s_add_i32 s54, s54, s41
	v_lshl_add_u64 v[158:159], s[20:21], 0, v[0:1]
	s_mov_b32 m0, s54
	ds_read_b128 v[196:199], v162 offset:16384
	ds_read_b128 v[200:203], v162 offset:17408
	ds_read_b128 v[204:207], v162 offset:18432
	ds_read_b128 v[220:223], v162 offset:19456
	ds_read_b128 v[224:227], v162 offset:20480
	ds_read_b128 v[228:231], v162 offset:21504
	ds_read_b128 v[232:235], v162 offset:22528
	ds_read_b128 v[236:239], v162 offset:23552
	global_load_lds_dwordx4 v[158:159], off
	s_add_i32 m0, s54, 0x2000
	s_add_u32 s54, s20, 0x80000
	v_lshl_add_u64 v[208:209], s[20:21], 0, v[130:131]
	s_addc_u32 s55, s21, 0
	s_add_i32 s56, s56, s41
	global_load_lds_dwordx4 v[208:209], off
	v_lshl_add_u64 v[216:217], s[54:55], 0, v[0:1]
	s_mov_b32 m0, s56
	v_lshl_add_u64 v[244:245], s[22:23], 0, v[132:133]
	global_load_lds_dwordx4 v[216:217], off
	v_lshl_add_u64 v[216:217], s[54:55], 0, v[130:131]
	s_add_i32 m0, s56, 0x2000
	s_nop 0
	global_load_lds_dwordx4 v[216:217], off
	v_lshl_add_u64 v[216:217], s[22:23], 0, v[134:135]
	s_mov_b32 m0, s17
	s_nop 0
	global_load_lds_dwordx4 v[216:217], off
	s_mov_b32 m0, s43
	s_nop 0
	global_load_lds_dwordx4 v[244:245], off
	s_waitcnt vmcnt(8)
	s_waitcnt lgkmcnt(0)
	s_setprio 1
	s_barrier
	v_mfma_f32_16x16x32_bf16 v[58:61], v[164:167], v[196:199], 0
	v_mfma_f32_16x16x32_bf16 v[50:53], v[172:175], v[196:199], 0
	v_mfma_f32_16x16x32_bf16 v[42:45], v[164:167], v[204:207], 0
	v_mfma_f32_16x16x32_bf16 v[34:37], v[172:175], v[204:207], 0
	v_mfma_f32_16x16x32_bf16 v[26:29], v[164:167], v[224:227], 0
	v_mfma_f32_16x16x32_bf16 v[18:21], v[172:175], v[224:227], 0
	v_mfma_f32_16x16x32_bf16 v[10:13], v[164:167], v[232:235], 0
	v_mfma_f32_16x16x32_bf16 v[2:5], v[172:175], v[232:235], 0
	v_mfma_f32_16x16x32_bf16 v[58:61], v[168:171], v[200:203], v[58:61]
	v_mfma_f32_16x16x32_bf16 v[50:53], v[176:179], v[200:203], v[50:53]
	v_mfma_f32_16x16x32_bf16 v[42:45], v[168:171], v[220:223], v[42:45]
	v_mfma_f32_16x16x32_bf16 v[34:37], v[176:179], v[220:223], v[34:37]
	v_mfma_f32_16x16x32_bf16 v[26:29], v[168:171], v[228:231], v[26:29]
	v_mfma_f32_16x16x32_bf16 v[18:21], v[176:179], v[228:231], v[18:21]
	v_mfma_f32_16x16x32_bf16 v[10:13], v[168:171], v[236:239], v[10:13]
	v_mfma_f32_16x16x32_bf16 v[2:5], v[176:179], v[236:239], v[2:5]
	s_setprio 0
	s_setprio 1
	v_mfma_f32_16x16x32_bf16 v[62:65], v[180:183], v[196:199], 0
	v_mfma_f32_16x16x32_bf16 v[54:57], v[188:191], v[196:199], 0
	v_mfma_f32_16x16x32_bf16 v[46:49], v[180:183], v[204:207], 0
	v_mfma_f32_16x16x32_bf16 v[38:41], v[188:191], v[204:207], 0
	v_mfma_f32_16x16x32_bf16 v[30:33], v[180:183], v[224:227], 0
	v_mfma_f32_16x16x32_bf16 v[22:25], v[188:191], v[224:227], 0
	v_mfma_f32_16x16x32_bf16 v[14:17], v[180:183], v[232:235], 0
	v_mfma_f32_16x16x32_bf16 v[6:9], v[188:191], v[232:235], 0
	v_mfma_f32_16x16x32_bf16 v[62:65], v[184:187], v[200:203], v[62:65]
	v_mfma_f32_16x16x32_bf16 v[54:57], v[192:195], v[200:203], v[54:57]
	v_mfma_f32_16x16x32_bf16 v[46:49], v[184:187], v[220:223], v[46:49]
	v_mfma_f32_16x16x32_bf16 v[38:41], v[192:195], v[220:223], v[38:41]
	v_mfma_f32_16x16x32_bf16 v[30:33], v[184:187], v[228:231], v[30:33]
	v_mfma_f32_16x16x32_bf16 v[22:25], v[192:195], v[228:231], v[22:25]
	v_mfma_f32_16x16x32_bf16 v[14:17], v[184:187], v[236:239], v[14:17]
	v_mfma_f32_16x16x32_bf16 v[6:9], v[192:195], v[236:239], v[6:9]
	s_barrier
	s_setprio 0
	s_add_i32 s54, 0, 0x18000
	v_add_u32_e32 v163, s54, v160
	s_add_i32 s55, 0, 0x1c000
	ds_read_b128 v[164:167], v163
	ds_read_b128 v[168:171], v163 offset:1024
	ds_read_b128 v[172:175], v163 offset:2048
	ds_read_b128 v[176:179], v163 offset:3072
	v_add_u32_e32 v163, s55, v160
	ds_read_b128 v[180:183], v163
	ds_read_b128 v[184:187], v163 offset:1024
	ds_read_b128 v[188:191], v163 offset:2048
	ds_read_b128 v[192:195], v163 offset:3072
	s_add_u32 s22, s22, 0x80000
	s_addc_u32 s23, s23, 0
	s_mov_b32 m0, s44
	v_lshl_add_u64 v[246:247], s[22:23], 0, v[134:135]
	ds_read_b128 v[196:199], v162 offset:32768
	ds_read_b128 v[200:203], v162 offset:33792
	ds_read_b128 v[204:207], v162 offset:34816
	ds_read_b128 v[220:223], v162 offset:35840
	ds_read_b128 v[224:227], v162 offset:36864
	ds_read_b128 v[228:231], v162 offset:37888
	ds_read_b128 v[232:235], v162 offset:38912
	ds_read_b128 v[236:239], v162 offset:39936
	global_load_lds_dwordx4 v[246:247], off
	v_lshl_add_u64 v[246:247], s[22:23], 0, v[132:133]
	s_mov_b32 m0, s45
	s_nop 0
	global_load_lds_dwordx4 v[246:247], off
	s_waitcnt vmcnt(8)
	s_waitcnt lgkmcnt(0)
	s_setprio 1
	s_barrier
	v_mfma_f32_16x16x32_bf16 v[122:125], v[164:167], v[196:199], v[122:125]
	v_mfma_f32_16x16x32_bf16 v[114:117], v[172:175], v[196:199], v[114:117]
	v_mfma_f32_16x16x32_bf16 v[106:109], v[164:167], v[204:207], v[106:109]
	v_mfma_f32_16x16x32_bf16 v[98:101], v[172:175], v[204:207], v[98:101]
	v_mfma_f32_16x16x32_bf16 v[90:93], v[164:167], v[224:227], v[90:93]
	v_mfma_f32_16x16x32_bf16 v[82:85], v[172:175], v[224:227], v[82:85]
	v_mfma_f32_16x16x32_bf16 v[74:77], v[164:167], v[232:235], v[74:77]
	v_mfma_f32_16x16x32_bf16 v[66:69], v[172:175], v[232:235], v[66:69]
	v_mfma_f32_16x16x32_bf16 v[122:125], v[168:171], v[200:203], v[122:125]
	v_mfma_f32_16x16x32_bf16 v[114:117], v[176:179], v[200:203], v[114:117]
	v_mfma_f32_16x16x32_bf16 v[106:109], v[168:171], v[220:223], v[106:109]
	v_mfma_f32_16x16x32_bf16 v[98:101], v[176:179], v[220:223], v[98:101]
	v_mfma_f32_16x16x32_bf16 v[90:93], v[168:171], v[228:231], v[90:93]
	v_mfma_f32_16x16x32_bf16 v[82:85], v[176:179], v[228:231], v[82:85]
	v_mfma_f32_16x16x32_bf16 v[74:77], v[168:171], v[236:239], v[74:77]
	v_mfma_f32_16x16x32_bf16 v[66:69], v[176:179], v[236:239], v[66:69]
	s_setprio 0
	s_setprio 1
	v_mfma_f32_16x16x32_bf16 v[126:129], v[180:183], v[196:199], v[126:129]
	v_mfma_f32_16x16x32_bf16 v[118:121], v[188:191], v[196:199], v[118:121]
	v_mfma_f32_16x16x32_bf16 v[110:113], v[180:183], v[204:207], v[110:113]
	v_mfma_f32_16x16x32_bf16 v[102:105], v[188:191], v[204:207], v[102:105]
	v_mfma_f32_16x16x32_bf16 v[94:97], v[180:183], v[224:227], v[94:97]
	v_mfma_f32_16x16x32_bf16 v[86:89], v[188:191], v[224:227], v[86:89]
	v_mfma_f32_16x16x32_bf16 v[78:81], v[180:183], v[232:235], v[78:81]
	v_mfma_f32_16x16x32_bf16 v[70:73], v[188:191], v[232:235], v[70:73]
	v_mfma_f32_16x16x32_bf16 v[126:129], v[184:187], v[200:203], v[126:129]
	v_mfma_f32_16x16x32_bf16 v[118:121], v[192:195], v[200:203], v[118:121]
	v_mfma_f32_16x16x32_bf16 v[110:113], v[184:187], v[220:223], v[110:113]
	v_mfma_f32_16x16x32_bf16 v[102:105], v[192:195], v[220:223], v[102:105]
	v_mfma_f32_16x16x32_bf16 v[94:97], v[184:187], v[228:231], v[94:97]
	v_mfma_f32_16x16x32_bf16 v[86:89], v[192:195], v[228:231], v[86:89]
	v_mfma_f32_16x16x32_bf16 v[78:81], v[184:187], v[236:239], v[78:81]
	v_mfma_f32_16x16x32_bf16 v[70:73], v[192:195], v[236:239], v[70:73]
	s_barrier
	s_setprio 0
	s_add_i32 s22, s54, s41
	v_lshl_add_u64 v[158:159], v[158:159], 0, s[2:3]
	s_mov_b32 m0, s22
	ds_read_b128 v[196:199], v162 offset:49152
	ds_read_b128 v[200:203], v162 offset:50176
	ds_read_b128 v[204:207], v162 offset:51200
	ds_read_b128 v[220:223], v162 offset:52224
	ds_read_b128 v[224:227], v162 offset:53248
	ds_read_b128 v[228:231], v162 offset:54272
	ds_read_b128 v[232:235], v162 offset:55296
	ds_read_b128 v[236:239], v162 offset:56320
	global_load_lds_dwordx4 v[158:159], off
	s_add_i32 m0, s22, 0x2000
	s_add_u32 s20, s20, 0x80080
	v_lshl_add_u64 v[158:159], v[208:209], 0, s[2:3]
	s_addc_u32 s21, s21, 0
	s_add_i32 s22, s55, s41
	global_load_lds_dwordx4 v[158:159], off
	v_lshl_add_u64 v[158:159], s[20:21], 0, v[0:1]
	s_mov_b32 m0, s22
	s_nop 0
	global_load_lds_dwordx4 v[158:159], off
	v_lshl_add_u64 v[158:159], s[20:21], 0, v[130:131]
	s_add_i32 m0, s22, 0x2000
	s_nop 0
	global_load_lds_dwordx4 v[158:159], off
	v_lshl_add_u64 v[158:159], v[216:217], 0, s[2:3]
	s_mov_b32 m0, s46
	s_nop 0
	global_load_lds_dwordx4 v[158:159], off
	v_lshl_add_u64 v[158:159], v[244:245], 0, s[2:3]
	s_mov_b32 m0, s47
	s_nop 0
	global_load_lds_dwordx4 v[158:159], off
	s_waitcnt vmcnt(8)
	s_waitcnt lgkmcnt(0)
	s_setprio 1
	s_barrier
	v_mfma_f32_16x16x32_bf16 v[58:61], v[164:167], v[196:199], v[58:61]
	v_mfma_f32_16x16x32_bf16 v[50:53], v[172:175], v[196:199], v[50:53]
	v_mfma_f32_16x16x32_bf16 v[42:45], v[164:167], v[204:207], v[42:45]
	v_mfma_f32_16x16x32_bf16 v[34:37], v[172:175], v[204:207], v[34:37]
	v_mfma_f32_16x16x32_bf16 v[26:29], v[164:167], v[224:227], v[26:29]
	v_mfma_f32_16x16x32_bf16 v[18:21], v[172:175], v[224:227], v[18:21]
	v_mfma_f32_16x16x32_bf16 v[10:13], v[164:167], v[232:235], v[10:13]
	v_mfma_f32_16x16x32_bf16 v[2:5], v[172:175], v[232:235], v[2:5]
	v_mfma_f32_16x16x32_bf16 v[58:61], v[168:171], v[200:203], v[58:61]
	v_mfma_f32_16x16x32_bf16 v[50:53], v[176:179], v[200:203], v[50:53]
	v_mfma_f32_16x16x32_bf16 v[42:45], v[168:171], v[220:223], v[42:45]
	v_mfma_f32_16x16x32_bf16 v[34:37], v[176:179], v[220:223], v[34:37]
	v_mfma_f32_16x16x32_bf16 v[26:29], v[168:171], v[228:231], v[26:29]
	v_mfma_f32_16x16x32_bf16 v[18:21], v[176:179], v[228:231], v[18:21]
	v_mfma_f32_16x16x32_bf16 v[10:13], v[168:171], v[236:239], v[10:13]
	v_mfma_f32_16x16x32_bf16 v[2:5], v[176:179], v[236:239], v[2:5]
	s_setprio 0
	s_setprio 1
	v_mfma_f32_16x16x32_bf16 v[62:65], v[180:183], v[196:199], v[62:65]
	v_mfma_f32_16x16x32_bf16 v[54:57], v[188:191], v[196:199], v[54:57]
	v_mfma_f32_16x16x32_bf16 v[46:49], v[180:183], v[204:207], v[46:49]
	v_mfma_f32_16x16x32_bf16 v[38:41], v[188:191], v[204:207], v[38:41]
	v_mfma_f32_16x16x32_bf16 v[30:33], v[180:183], v[224:227], v[30:33]
	v_mfma_f32_16x16x32_bf16 v[22:25], v[188:191], v[224:227], v[22:25]
	v_mfma_f32_16x16x32_bf16 v[14:17], v[180:183], v[232:235], v[14:17]
	v_mfma_f32_16x16x32_bf16 v[6:9], v[188:191], v[232:235], v[6:9]
	v_mfma_f32_16x16x32_bf16 v[62:65], v[184:187], v[200:203], v[62:65]
	v_mfma_f32_16x16x32_bf16 v[54:57], v[192:195], v[200:203], v[54:57]
	v_mfma_f32_16x16x32_bf16 v[46:49], v[184:187], v[220:223], v[46:49]
	v_mfma_f32_16x16x32_bf16 v[38:41], v[192:195], v[220:223], v[38:41]
	v_mfma_f32_16x16x32_bf16 v[30:33], v[184:187], v[228:231], v[30:33]
	v_mfma_f32_16x16x32_bf16 v[22:25], v[192:195], v[228:231], v[22:25]
	v_mfma_f32_16x16x32_bf16 v[14:17], v[184:187], v[236:239], v[14:17]
	v_mfma_f32_16x16x32_bf16 v[6:9], v[192:195], v[236:239], v[6:9]
	s_barrier
	s_setprio 0
	s_add_i32 s53, s53, 2
	s_add_u32 s18, s18, 0x100
	s_addc_u32 s19, s19, 0
	s_add_u32 s51, s51, 0x100
	s_addc_u32 s52, s52, 0
	s_cmp_gt_u32 s53, 29
	s_cbranch_scc1 .Lpeel_done_4
.LBB0_1565:
	s_add_u32 s20, s18, 0xfff80080
	s_addc_u32 s21, s19, -1
	s_cmp_eq_u32 s53, 28
	s_cselect_b32 s23, s9, s21
	s_cselect_b32 s22, s15, s20
	s_cselect_b32 s21, s7, s52
	s_cselect_b32 s20, s50, s51
	s_add_i32 s54, 0, 0x10000
	s_add_i32 s56, 0, 0x14000
	v_add_u32_e32 v158, 0x10000, v160
	ds_read_b128 v[164:167], v158
	ds_read_b128 v[168:171], v158 offset:1024
	ds_read_b128 v[172:175], v158 offset:2048
	ds_read_b128 v[176:179], v158 offset:3072
	ds_read_b128 v[180:183], v158 offset:16384
	ds_read_b128 v[184:187], v158 offset:17408
	ds_read_b128 v[188:191], v158 offset:18432
	ds_read_b128 v[192:195], v158 offset:19456
	s_add_i32 m0, s17, 0xc000
	ds_read_b128 v[196:199], v162
	ds_read_b128 v[200:203], v162 offset:1024
	ds_read_b128 v[204:207], v162 offset:2048
	ds_read_b128 v[220:223], v162 offset:3072
	ds_read_b128 v[224:227], v162 offset:4096
	ds_read_b128 v[228:231], v162 offset:5120
	ds_read_b128 v[232:235], v162 offset:6144
	ds_read_b128 v[236:239], v162 offset:7168
	global_load_lds_dwordx4 v154, s[18:19]
	s_add_i32 m0, s17, 0xe000
	s_nop 0
	global_load_lds_dwordx4 v156, s[18:19]
	s_waitcnt vmcnt(8)
	s_waitcnt lgkmcnt(0)
	s_setprio 1
	s_barrier
	v_mfma_f32_16x16x32_bf16 v[122:125], v[164:167], v[196:199], v[122:125]
	v_mfma_f32_16x16x32_bf16 v[114:117], v[172:175], v[196:199], v[114:117]
	v_mfma_f32_16x16x32_bf16 v[106:109], v[164:167], v[204:207], v[106:109]
	v_mfma_f32_16x16x32_bf16 v[98:101], v[172:175], v[204:207], v[98:101]
	v_mfma_f32_16x16x32_bf16 v[90:93], v[164:167], v[224:227], v[90:93]
	v_mfma_f32_16x16x32_bf16 v[82:85], v[172:175], v[224:227], v[82:85]
	v_mfma_f32_16x16x32_bf16 v[74:77], v[164:167], v[232:235], v[74:77]
	v_mfma_f32_16x16x32_bf16 v[66:69], v[172:175], v[232:235], v[66:69]
	v_mfma_f32_16x16x32_bf16 v[122:125], v[168:171], v[200:203], v[122:125]
	v_mfma_f32_16x16x32_bf16 v[114:117], v[176:179], v[200:203], v[114:117]
	v_mfma_f32_16x16x32_bf16 v[106:109], v[168:171], v[220:223], v[106:109]
	v_mfma_f32_16x16x32_bf16 v[98:101], v[176:179], v[220:223], v[98:101]
	v_mfma_f32_16x16x32_bf16 v[90:93], v[168:171], v[228:231], v[90:93]
	v_mfma_f32_16x16x32_bf16 v[82:85], v[176:179], v[228:231], v[82:85]
	v_mfma_f32_16x16x32_bf16 v[74:77], v[168:171], v[236:239], v[74:77]
	v_mfma_f32_16x16x32_bf16 v[66:69], v[176:179], v[236:239], v[66:69]
	s_setprio 0
	s_setprio 1
	v_mfma_f32_16x16x32_bf16 v[126:129], v[180:183], v[196:199], v[126:129]
	v_mfma_f32_16x16x32_bf16 v[118:121], v[188:191], v[196:199], v[118:121]
	v_mfma_f32_16x16x32_bf16 v[110:113], v[180:183], v[204:207], v[110:113]
	v_mfma_f32_16x16x32_bf16 v[102:105], v[188:191], v[204:207], v[102:105]
	v_mfma_f32_16x16x32_bf16 v[94:97], v[180:183], v[224:227], v[94:97]
	v_mfma_f32_16x16x32_bf16 v[86:89], v[188:191], v[224:227], v[86:89]
	v_mfma_f32_16x16x32_bf16 v[78:81], v[180:183], v[232:235], v[78:81]
	v_mfma_f32_16x16x32_bf16 v[70:73], v[188:191], v[232:235], v[70:73]
	v_mfma_f32_16x16x32_bf16 v[126:129], v[184:187], v[200:203], v[126:129]
	v_mfma_f32_16x16x32_bf16 v[118:121], v[192:195], v[200:203], v[118:121]
	v_mfma_f32_16x16x32_bf16 v[110:113], v[184:187], v[220:223], v[110:113]
	v_mfma_f32_16x16x32_bf16 v[102:105], v[192:195], v[220:223], v[102:105]
	v_mfma_f32_16x16x32_bf16 v[94:97], v[184:187], v[228:231], v[94:97]
	v_mfma_f32_16x16x32_bf16 v[86:89], v[192:195], v[228:231], v[86:89]
	v_mfma_f32_16x16x32_bf16 v[78:81], v[184:187], v[236:239], v[78:81]
	v_mfma_f32_16x16x32_bf16 v[70:73], v[192:195], v[236:239], v[70:73]
	s_barrier
	s_setprio 0
	s_add_i32 s54, s54, s41
	s_mov_b32 m0, s54
	ds_read_b128 v[196:199], v162 offset:16384
	ds_read_b128 v[200:203], v162 offset:17408
	ds_read_b128 v[204:207], v162 offset:18432
	ds_read_b128 v[220:223], v162 offset:19456
	ds_read_b128 v[224:227], v162 offset:20480
	ds_read_b128 v[228:231], v162 offset:21504
	ds_read_b128 v[232:235], v162 offset:22528
	ds_read_b128 v[236:239], v162 offset:23552
	global_load_lds_dwordx4 v0, s[20:21]
	s_add_i32 m0, s54, 0x2000
	s_add_u32 s54, s20, 0x80000
	s_addc_u32 s55, s21, 0
	s_add_i32 s56, s56, s41
	global_load_lds_dwordx4 v130, s[20:21]
	s_mov_b32 m0, s56
	s_nop 0
	global_load_lds_dwordx4 v0, s[54:55]
	s_add_i32 m0, s56, 0x2000
	s_nop 0
	global_load_lds_dwordx4 v130, s[54:55]
	s_mov_b32 m0, s17
	s_nop 0
	global_load_lds_dwordx4 v134, s[22:23]
	s_mov_b32 m0, s43
	s_nop 0
	global_load_lds_dwordx4 v132, s[22:23]
	s_waitcnt vmcnt(8)
	s_waitcnt lgkmcnt(0)
	s_setprio 1
	s_barrier
	v_mfma_f32_16x16x32_bf16 v[58:61], v[164:167], v[196:199], v[58:61]
	v_mfma_f32_16x16x32_bf16 v[50:53], v[172:175], v[196:199], v[50:53]
	v_mfma_f32_16x16x32_bf16 v[42:45], v[164:167], v[204:207], v[42:45]
	v_mfma_f32_16x16x32_bf16 v[34:37], v[172:175], v[204:207], v[34:37]
	v_mfma_f32_16x16x32_bf16 v[26:29], v[164:167], v[224:227], v[26:29]
	v_mfma_f32_16x16x32_bf16 v[18:21], v[172:175], v[224:227], v[18:21]
	v_mfma_f32_16x16x32_bf16 v[10:13], v[164:167], v[232:235], v[10:13]
	v_mfma_f32_16x16x32_bf16 v[2:5], v[172:175], v[232:235], v[2:5]
	v_mfma_f32_16x16x32_bf16 v[58:61], v[168:171], v[200:203], v[58:61]
	v_mfma_f32_16x16x32_bf16 v[50:53], v[176:179], v[200:203], v[50:53]
	v_mfma_f32_16x16x32_bf16 v[42:45], v[168:171], v[220:223], v[42:45]
	v_mfma_f32_16x16x32_bf16 v[34:37], v[176:179], v[220:223], v[34:37]
	v_mfma_f32_16x16x32_bf16 v[26:29], v[168:171], v[228:231], v[26:29]
	v_mfma_f32_16x16x32_bf16 v[18:21], v[176:179], v[228:231], v[18:21]
	v_mfma_f32_16x16x32_bf16 v[10:13], v[168:171], v[236:239], v[10:13]
	v_mfma_f32_16x16x32_bf16 v[2:5], v[176:179], v[236:239], v[2:5]
	s_setprio 0
	s_setprio 1
	v_mfma_f32_16x16x32_bf16 v[62:65], v[180:183], v[196:199], v[62:65]
	v_mfma_f32_16x16x32_bf16 v[54:57], v[188:191], v[196:199], v[54:57]
	v_mfma_f32_16x16x32_bf16 v[46:49], v[180:183], v[204:207], v[46:49]
	v_mfma_f32_16x16x32_bf16 v[38:41], v[188:191], v[204:207], v[38:41]
	v_mfma_f32_16x16x32_bf16 v[30:33], v[180:183], v[224:227], v[30:33]
	v_mfma_f32_16x16x32_bf16 v[22:25], v[188:191], v[224:227], v[22:25]
	v_mfma_f32_16x16x32_bf16 v[14:17], v[180:183], v[232:235], v[14:17]
	v_mfma_f32_16x16x32_bf16 v[6:9], v[188:191], v[232:235], v[6:9]
	v_mfma_f32_16x16x32_bf16 v[62:65], v[184:187], v[200:203], v[62:65]
	v_mfma_f32_16x16x32_bf16 v[54:57], v[192:195], v[200:203], v[54:57]
	v_mfma_f32_16x16x32_bf16 v[46:49], v[184:187], v[220:223], v[46:49]
	v_mfma_f32_16x16x32_bf16 v[38:41], v[192:195], v[220:223], v[38:41]
	v_mfma_f32_16x16x32_bf16 v[30:33], v[184:187], v[228:231], v[30:33]
	v_mfma_f32_16x16x32_bf16 v[22:25], v[192:195], v[228:231], v[22:25]
	v_mfma_f32_16x16x32_bf16 v[14:17], v[184:187], v[236:239], v[14:17]
	v_mfma_f32_16x16x32_bf16 v[6:9], v[192:195], v[236:239], v[6:9]
	s_barrier
	s_setprio 0
	ds_read_b128 v[164:167], v158 offset:32768
	ds_read_b128 v[168:171], v158 offset:33792
	ds_read_b128 v[172:175], v158 offset:34816
	ds_read_b128 v[176:179], v158 offset:35840
	ds_read_b128 v[180:183], v158 offset:49152
	ds_read_b128 v[184:187], v158 offset:50176
	ds_read_b128 v[188:191], v158 offset:51200
	ds_read_b128 v[192:195], v158 offset:52224
	s_add_i32 s54, 0, 0x18000
	s_add_i32 s55, 0, 0x1c000
	s_add_u32 s22, s22, 0x80000
	s_addc_u32 s23, s23, 0
	s_mov_b32 m0, s44
	ds_read_b128 v[196:199], v162 offset:32768
	ds_read_b128 v[200:203], v162 offset:33792
	ds_read_b128 v[204:207], v162 offset:34816
	ds_read_b128 v[220:223], v162 offset:35840
	ds_read_b128 v[224:227], v162 offset:36864
	ds_read_b128 v[228:231], v162 offset:37888
	ds_read_b128 v[232:235], v162 offset:38912
	ds_read_b128 v[236:239], v162 offset:39936
	global_load_lds_dwordx4 v134, s[22:23]
	s_mov_b32 m0, s45
	s_nop 0
	global_load_lds_dwordx4 v132, s[22:23]
	s_waitcnt vmcnt(8)
	s_waitcnt lgkmcnt(0)
	s_setprio 1
	s_barrier
	v_mfma_f32_16x16x32_bf16 v[122:125], v[164:167], v[196:199], v[122:125]
	v_mfma_f32_16x16x32_bf16 v[114:117], v[172:175], v[196:199], v[114:117]
	v_mfma_f32_16x16x32_bf16 v[106:109], v[164:167], v[204:207], v[106:109]
	v_mfma_f32_16x16x32_bf16 v[98:101], v[172:175], v[204:207], v[98:101]
	v_mfma_f32_16x16x32_bf16 v[90:93], v[164:167], v[224:227], v[90:93]
	v_mfma_f32_16x16x32_bf16 v[82:85], v[172:175], v[224:227], v[82:85]
	v_mfma_f32_16x16x32_bf16 v[74:77], v[164:167], v[232:235], v[74:77]
	v_mfma_f32_16x16x32_bf16 v[66:69], v[172:175], v[232:235], v[66:69]
	v_mfma_f32_16x16x32_bf16 v[122:125], v[168:171], v[200:203], v[122:125]
	v_mfma_f32_16x16x32_bf16 v[114:117], v[176:179], v[200:203], v[114:117]
	v_mfma_f32_16x16x32_bf16 v[106:109], v[168:171], v[220:223], v[106:109]
	v_mfma_f32_16x16x32_bf16 v[98:101], v[176:179], v[220:223], v[98:101]
	v_mfma_f32_16x16x32_bf16 v[90:93], v[168:171], v[228:231], v[90:93]
	v_mfma_f32_16x16x32_bf16 v[82:85], v[176:179], v[228:231], v[82:85]
	v_mfma_f32_16x16x32_bf16 v[74:77], v[168:171], v[236:239], v[74:77]
	v_mfma_f32_16x16x32_bf16 v[66:69], v[176:179], v[236:239], v[66:69]
	s_setprio 0
	s_setprio 1
	v_mfma_f32_16x16x32_bf16 v[126:129], v[180:183], v[196:199], v[126:129]
	v_mfma_f32_16x16x32_bf16 v[118:121], v[188:191], v[196:199], v[118:121]
	v_mfma_f32_16x16x32_bf16 v[110:113], v[180:183], v[204:207], v[110:113]
	v_mfma_f32_16x16x32_bf16 v[102:105], v[188:191], v[204:207], v[102:105]
	v_mfma_f32_16x16x32_bf16 v[94:97], v[180:183], v[224:227], v[94:97]
	v_mfma_f32_16x16x32_bf16 v[86:89], v[188:191], v[224:227], v[86:89]
	v_mfma_f32_16x16x32_bf16 v[78:81], v[180:183], v[232:235], v[78:81]
	v_mfma_f32_16x16x32_bf16 v[70:73], v[188:191], v[232:235], v[70:73]
	v_mfma_f32_16x16x32_bf16 v[126:129], v[184:187], v[200:203], v[126:129]
	v_mfma_f32_16x16x32_bf16 v[118:121], v[192:195], v[200:203], v[118:121]
	v_mfma_f32_16x16x32_bf16 v[110:113], v[184:187], v[220:223], v[110:113]
	v_mfma_f32_16x16x32_bf16 v[102:105], v[192:195], v[220:223], v[102:105]
	v_mfma_f32_16x16x32_bf16 v[94:97], v[184:187], v[228:231], v[94:97]
	v_mfma_f32_16x16x32_bf16 v[86:89], v[192:195], v[228:231], v[86:89]
	v_mfma_f32_16x16x32_bf16 v[78:81], v[184:187], v[236:239], v[78:81]
	v_mfma_f32_16x16x32_bf16 v[70:73], v[192:195], v[236:239], v[70:73]
	s_barrier
	s_setprio 0
	s_add_u32 vcc_lo, s22, 0xfff80080
	s_addc_u32 vcc_hi, s23, -1
	s_add_i32 s22, s54, s41
	s_add_i32 s56, s55, s41
	s_add_u32 s54, s20, 0x80
	s_addc_u32 s55, s21, 0
	s_add_u32 s20, s20, 0x80080
	s_addc_u32 s21, s21, 0
	s_mov_b32 m0, s22
	ds_read_b128 v[196:199], v162 offset:49152
	ds_read_b128 v[200:203], v162 offset:50176
	ds_read_b128 v[204:207], v162 offset:51200
	ds_read_b128 v[220:223], v162 offset:52224
	ds_read_b128 v[224:227], v162 offset:53248
	ds_read_b128 v[228:231], v162 offset:54272
	ds_read_b128 v[232:235], v162 offset:55296
	ds_read_b128 v[236:239], v162 offset:56320
	global_load_lds_dwordx4 v0, s[54:55]
	s_add_i32 m0, s22, 0x2000
	s_nop 0
	global_load_lds_dwordx4 v130, s[54:55]
	s_mov_b32 m0, s56
	s_nop 0
	global_load_lds_dwordx4 v0, s[20:21]
	s_add_i32 m0, s56, 0x2000
	s_nop 0
	global_load_lds_dwordx4 v130, s[20:21]
	s_mov_b32 m0, s46
	s_nop 0
	global_load_lds_dwordx4 v134, vcc
	s_mov_b32 m0, s47
	s_nop 0
	global_load_lds_dwordx4 v132, vcc
	s_waitcnt vmcnt(8)
	s_waitcnt lgkmcnt(0)
	s_setprio 1
	s_barrier
	v_mfma_f32_16x16x32_bf16 v[58:61], v[164:167], v[196:199], v[58:61]
	v_mfma_f32_16x16x32_bf16 v[50:53], v[172:175], v[196:199], v[50:53]
	v_mfma_f32_16x16x32_bf16 v[42:45], v[164:167], v[204:207], v[42:45]
	v_mfma_f32_16x16x32_bf16 v[34:37], v[172:175], v[204:207], v[34:37]
	v_mfma_f32_16x16x32_bf16 v[26:29], v[164:167], v[224:227], v[26:29]
	v_mfma_f32_16x16x32_bf16 v[18:21], v[172:175], v[224:227], v[18:21]
	v_mfma_f32_16x16x32_bf16 v[10:13], v[164:167], v[232:235], v[10:13]
	v_mfma_f32_16x16x32_bf16 v[2:5], v[172:175], v[232:235], v[2:5]
	v_mfma_f32_16x16x32_bf16 v[58:61], v[168:171], v[200:203], v[58:61]
	v_mfma_f32_16x16x32_bf16 v[50:53], v[176:179], v[200:203], v[50:53]
	v_mfma_f32_16x16x32_bf16 v[42:45], v[168:171], v[220:223], v[42:45]
	v_mfma_f32_16x16x32_bf16 v[34:37], v[176:179], v[220:223], v[34:37]
	v_mfma_f32_16x16x32_bf16 v[26:29], v[168:171], v[228:231], v[26:29]
	v_mfma_f32_16x16x32_bf16 v[18:21], v[176:179], v[228:231], v[18:21]
	v_mfma_f32_16x16x32_bf16 v[10:13], v[168:171], v[236:239], v[10:13]
	v_mfma_f32_16x16x32_bf16 v[2:5], v[176:179], v[236:239], v[2:5]
	s_setprio 0
	s_setprio 1
	v_mfma_f32_16x16x32_bf16 v[62:65], v[180:183], v[196:199], v[62:65]
	v_mfma_f32_16x16x32_bf16 v[54:57], v[188:191], v[196:199], v[54:57]
	v_mfma_f32_16x16x32_bf16 v[46:49], v[180:183], v[204:207], v[46:49]
	v_mfma_f32_16x16x32_bf16 v[38:41], v[188:191], v[204:207], v[38:41]
	v_mfma_f32_16x16x32_bf16 v[30:33], v[180:183], v[224:227], v[30:33]
	v_mfma_f32_16x16x32_bf16 v[22:25], v[188:191], v[224:227], v[22:25]
	v_mfma_f32_16x16x32_bf16 v[14:17], v[180:183], v[232:235], v[14:17]
	v_mfma_f32_16x16x32_bf16 v[6:9], v[188:191], v[232:235], v[6:9]
	v_mfma_f32_16x16x32_bf16 v[62:65], v[184:187], v[200:203], v[62:65]
	v_mfma_f32_16x16x32_bf16 v[54:57], v[192:195], v[200:203], v[54:57]
	v_mfma_f32_16x16x32_bf16 v[46:49], v[184:187], v[220:223], v[46:49]
	v_mfma_f32_16x16x32_bf16 v[38:41], v[192:195], v[220:223], v[38:41]
	v_mfma_f32_16x16x32_bf16 v[30:33], v[184:187], v[228:231], v[30:33]
	v_mfma_f32_16x16x32_bf16 v[22:25], v[192:195], v[228:231], v[22:25]
	v_mfma_f32_16x16x32_bf16 v[14:17], v[184:187], v[236:239], v[14:17]
	v_mfma_f32_16x16x32_bf16 v[6:9], v[192:195], v[236:239], v[6:9]
	s_barrier
	s_setprio 0
	s_add_i32 s53, s53, 2
	s_add_u32 s18, s18, 0x100
	s_addc_u32 s19, s19, 0
	s_add_u32 s51, s51, 0x100
	s_addc_u32 s52, s52, 0
	s_cmp_gt_u32 s53, 29
	s_cbranch_scc0 .LBB0_1565

.LBB0_1843:
	s_add_u32 s11, s14, 0x100
	s_addc_u32 s36, s15, 0
	s_add_u32 s12, s12, 0xc000
	s_addc_u32 s13, s13, 0
	s_mov_b32 s37, -2
	s_add_u32 s14, s12, 0x4000
	s_addc_u32 s15, s13, 0
	s_cmpk_eq_i32 s37, 0x54
	s_cselect_b32 s18, s6, s14
	s_cselect_b32 s19, s7, s15
	s_cselect_b32 s16, s8, s11
	s_cselect_b32 s17, s9, s36
	s_add_u32 s14, s18, 0x8000
	s_addc_u32 s15, s19, 0
	s_add_i32 s38, 0, 0x10000
	v_add_u32_e32 v0, s38, v246
	s_add_i32 s40, 0, 0x14000
	ds_read_b128 v[130:133], v0
	ds_read_b128 v[134:137], v0 offset:1024
	ds_read_b128 v[138:141], v0 offset:2048
	ds_read_b128 v[142:145], v0 offset:3072
	v_add_u32_e32 v0, s40, v246
	ds_read_b128 v[146:149], v0
	ds_read_b128 v[150:153], v0 offset:1024
	ds_read_b128 v[154:157], v0 offset:2048
	ds_read_b128 v[158:161], v0 offset:3072
	v_lshl_add_u64 v[194:195], s[12:13], 0, v[228:229]
	s_add_i32 m0, s47, 0xc000
	ds_read_b128 v[162:165], v247
	ds_read_b128 v[166:169], v247 offset:1024
	ds_read_b128 v[170:173], v247 offset:2048
	ds_read_b128 v[174:177], v247 offset:3072
	ds_read_b128 v[178:181], v247 offset:4096
	ds_read_b128 v[182:185], v247 offset:5120
	ds_read_b128 v[186:189], v247 offset:6144
	ds_read_b128 v[190:193], v247 offset:7168
	global_load_lds_dwordx4 v[194:195], off
	v_lshl_add_u64 v[194:195], s[12:13], 0, v[230:231]
	s_add_i32 m0, s47, 0xe000
	s_nop 0
	global_load_lds_dwordx4 v[194:195], off
	s_waitcnt vmcnt(8)
	s_waitcnt lgkmcnt(0)
	s_setprio 1
	s_barrier
	v_mfma_f32_16x16x32_bf16 v[126:129], v[130:133], v[162:165], 0
	v_mfma_f32_16x16x32_bf16 v[122:125], v[138:141], v[162:165], 0
	v_mfma_f32_16x16x32_bf16 v[114:117], v[130:133], v[170:173], 0
	v_mfma_f32_16x16x32_bf16 v[106:109], v[138:141], v[170:173], 0
	v_mfma_f32_16x16x32_bf16 v[94:97], v[130:133], v[178:181], 0
	v_mfma_f32_16x16x32_bf16 v[90:93], v[138:141], v[178:181], 0
	v_mfma_f32_16x16x32_bf16 v[86:89], v[130:133], v[186:189], 0
	v_mfma_f32_16x16x32_bf16 v[82:85], v[138:141], v[186:189], 0
	v_mfma_f32_16x16x32_bf16 v[126:129], v[134:137], v[166:169], v[126:129]
	v_mfma_f32_16x16x32_bf16 v[122:125], v[142:145], v[166:169], v[122:125]
	v_mfma_f32_16x16x32_bf16 v[114:117], v[134:137], v[174:177], v[114:117]
	v_mfma_f32_16x16x32_bf16 v[106:109], v[142:145], v[174:177], v[106:109]
	v_mfma_f32_16x16x32_bf16 v[94:97], v[134:137], v[182:185], v[94:97]
	v_mfma_f32_16x16x32_bf16 v[90:93], v[142:145], v[182:185], v[90:93]
	v_mfma_f32_16x16x32_bf16 v[86:89], v[134:137], v[190:193], v[86:89]
	v_mfma_f32_16x16x32_bf16 v[82:85], v[142:145], v[190:193], v[82:85]
	s_setprio 0
	s_setprio 1
	v_mfma_f32_16x16x32_bf16 v[118:121], v[146:149], v[162:165], 0
	v_mfma_f32_16x16x32_bf16 v[110:113], v[154:157], v[162:165], 0
	v_mfma_f32_16x16x32_bf16 v[102:105], v[146:149], v[170:173], 0
	v_mfma_f32_16x16x32_bf16 v[98:101], v[154:157], v[170:173], 0
	v_mfma_f32_16x16x32_bf16 v[78:81], v[146:149], v[178:181], 0
	v_mfma_f32_16x16x32_bf16 v[74:77], v[154:157], v[178:181], 0
	v_mfma_f32_16x16x32_bf16 v[70:73], v[146:149], v[186:189], 0
	v_mfma_f32_16x16x32_bf16 v[66:69], v[154:157], v[186:189], 0
	v_mfma_f32_16x16x32_bf16 v[118:121], v[150:153], v[166:169], v[118:121]
	v_mfma_f32_16x16x32_bf16 v[110:113], v[158:161], v[166:169], v[110:113]
	v_mfma_f32_16x16x32_bf16 v[102:105], v[150:153], v[174:177], v[102:105]
	v_mfma_f32_16x16x32_bf16 v[98:101], v[158:161], v[174:177], v[98:101]
	v_mfma_f32_16x16x32_bf16 v[78:81], v[150:153], v[182:185], v[78:81]
	v_mfma_f32_16x16x32_bf16 v[74:77], v[158:161], v[182:185], v[74:77]
	v_mfma_f32_16x16x32_bf16 v[70:73], v[150:153], v[190:193], v[70:73]
	v_mfma_f32_16x16x32_bf16 v[66:69], v[158:161], v[190:193], v[66:69]
	s_barrier
	s_setprio 0
	s_add_i32 s38, s38, s46
	v_lshl_add_u64 v[194:195], s[16:17], 0, v[222:223]
	s_mov_b32 m0, s38
	ds_read_b128 v[162:165], v247 offset:16384
	ds_read_b128 v[166:169], v247 offset:17408
	ds_read_b128 v[170:173], v247 offset:18432
	ds_read_b128 v[174:177], v247 offset:19456
	ds_read_b128 v[178:181], v247 offset:20480
	ds_read_b128 v[182:185], v247 offset:21504
	ds_read_b128 v[186:189], v247 offset:22528
	ds_read_b128 v[190:193], v247 offset:23552
	global_load_lds_dwordx4 v[194:195], off
	s_add_i32 m0, s38, 0x2000
	s_add_u32 s38, s16, 0x164000
	v_lshl_add_u64 v[196:197], s[16:17], 0, v[226:227]
	s_addc_u32 s39, s17, 0
	s_add_i32 s40, s40, s46
	global_load_lds_dwordx4 v[196:197], off
	v_lshl_add_u64 v[198:199], s[38:39], 0, v[222:223]
	s_mov_b32 m0, s40
	s_nop 0
	global_load_lds_dwordx4 v[198:199], off
	v_lshl_add_u64 v[198:199], s[38:39], 0, v[226:227]
	s_add_i32 m0, s40, 0x2000
	s_nop 0
	global_load_lds_dwordx4 v[198:199], off
	v_lshl_add_u64 v[198:199], s[18:19], 0, v[220:221]
	s_mov_b32 m0, s47
	s_nop 0
	global_load_lds_dwordx4 v[198:199], off
	v_lshl_add_u64 v[198:199], s[18:19], 0, v[224:225]
	s_mov_b32 m0, s74
	s_nop 0
	global_load_lds_dwordx4 v[198:199], off
	s_waitcnt vmcnt(8)
	s_waitcnt lgkmcnt(0)
	s_setprio 1
	s_barrier
	v_mfma_f32_16x16x32_bf16 v[62:65], v[130:133], v[162:165], 0
	v_mfma_f32_16x16x32_bf16 v[58:61], v[138:141], v[162:165], 0
	v_mfma_f32_16x16x32_bf16 v[54:57], v[130:133], v[170:173], 0
	v_mfma_f32_16x16x32_bf16 v[50:53], v[138:141], v[170:173], 0
	v_mfma_f32_16x16x32_bf16 v[30:33], v[130:133], v[178:181], 0
	v_mfma_f32_16x16x32_bf16 v[26:29], v[138:141], v[178:181], 0
	v_mfma_f32_16x16x32_bf16 v[22:25], v[130:133], v[186:189], 0
	v_mfma_f32_16x16x32_bf16 v[18:21], v[138:141], v[186:189], 0
	v_mfma_f32_16x16x32_bf16 v[62:65], v[134:137], v[166:169], v[62:65]
	v_mfma_f32_16x16x32_bf16 v[58:61], v[142:145], v[166:169], v[58:61]
	v_mfma_f32_16x16x32_bf16 v[54:57], v[134:137], v[174:177], v[54:57]
	v_mfma_f32_16x16x32_bf16 v[50:53], v[142:145], v[174:177], v[50:53]
	v_mfma_f32_16x16x32_bf16 v[30:33], v[134:137], v[182:185], v[30:33]
	v_mfma_f32_16x16x32_bf16 v[26:29], v[142:145], v[182:185], v[26:29]
	v_mfma_f32_16x16x32_bf16 v[22:25], v[134:137], v[190:193], v[22:25]
	v_mfma_f32_16x16x32_bf16 v[18:21], v[142:145], v[190:193], v[18:21]
	s_setprio 0
	s_setprio 1
	v_mfma_f32_16x16x32_bf16 v[46:49], v[146:149], v[162:165], 0
	v_mfma_f32_16x16x32_bf16 v[42:45], v[154:157], v[162:165], 0
	v_mfma_f32_16x16x32_bf16 v[38:41], v[146:149], v[170:173], 0
	v_mfma_f32_16x16x32_bf16 v[34:37], v[154:157], v[170:173], 0
	v_mfma_f32_16x16x32_bf16 v[14:17], v[146:149], v[178:181], 0
	v_mfma_f32_16x16x32_bf16 v[10:13], v[154:157], v[178:181], 0
	v_mfma_f32_16x16x32_bf16 v[6:9], v[146:149], v[186:189], 0
	v_mfma_f32_16x16x32_bf16 v[2:5], v[154:157], v[186:189], 0
	v_mfma_f32_16x16x32_bf16 v[46:49], v[150:153], v[166:169], v[46:49]
	v_mfma_f32_16x16x32_bf16 v[42:45], v[158:161], v[166:169], v[42:45]
	v_mfma_f32_16x16x32_bf16 v[38:41], v[150:153], v[174:177], v[38:41]
	v_mfma_f32_16x16x32_bf16 v[34:37], v[158:161], v[174:177], v[34:37]
	v_mfma_f32_16x16x32_bf16 v[14:17], v[150:153], v[182:185], v[14:17]
	v_mfma_f32_16x16x32_bf16 v[10:13], v[158:161], v[182:185], v[10:13]
	v_mfma_f32_16x16x32_bf16 v[6:9], v[150:153], v[190:193], v[6:9]
	v_mfma_f32_16x16x32_bf16 v[2:5], v[158:161], v[190:193], v[2:5]
	s_barrier
	s_setprio 0
	s_add_i32 s38, 0, 0x18000
	v_add_u32_e32 v0, s38, v246
	s_add_i32 s39, 0, 0x1c000
	ds_read_b128 v[130:133], v0
	ds_read_b128 v[134:137], v0 offset:1024
	ds_read_b128 v[138:141], v0 offset:2048
	ds_read_b128 v[142:145], v0 offset:3072
	v_add_u32_e32 v0, s39, v246
	ds_read_b128 v[146:149], v0
	ds_read_b128 v[150:153], v0 offset:1024
	ds_read_b128 v[154:157], v0 offset:2048
	ds_read_b128 v[158:161], v0 offset:3072
	s_add_u32 s18, s18, 0x4000
	s_addc_u32 s19, s19, 0
	s_mov_b32 m0, s75
	v_lshl_add_u64 v[198:199], s[18:19], 0, v[220:221]
	ds_read_b128 v[162:165], v247 offset:32768
	ds_read_b128 v[166:169], v247 offset:33792
	ds_read_b128 v[170:173], v247 offset:34816
	ds_read_b128 v[174:177], v247 offset:35840
	ds_read_b128 v[178:181], v247 offset:36864
	ds_read_b128 v[182:185], v247 offset:37888
	ds_read_b128 v[186:189], v247 offset:38912
	ds_read_b128 v[190:193], v247 offset:39936
	global_load_lds_dwordx4 v[198:199], off
	v_lshl_add_u64 v[198:199], s[18:19], 0, v[224:225]
	s_mov_b32 m0, s86
	s_nop 0
	global_load_lds_dwordx4 v[198:199], off
	s_waitcnt vmcnt(8)
	s_waitcnt lgkmcnt(0)
	s_setprio 1
	s_barrier
	v_mfma_f32_16x16x32_bf16 v[126:129], v[130:133], v[162:165], v[126:129]
	v_mfma_f32_16x16x32_bf16 v[122:125], v[138:141], v[162:165], v[122:125]
	v_mfma_f32_16x16x32_bf16 v[114:117], v[130:133], v[170:173], v[114:117]
	v_mfma_f32_16x16x32_bf16 v[106:109], v[138:141], v[170:173], v[106:109]
	v_mfma_f32_16x16x32_bf16 v[94:97], v[130:133], v[178:181], v[94:97]
	v_mfma_f32_16x16x32_bf16 v[90:93], v[138:141], v[178:181], v[90:93]
	v_mfma_f32_16x16x32_bf16 v[86:89], v[130:133], v[186:189], v[86:89]
	v_mfma_f32_16x16x32_bf16 v[82:85], v[138:141], v[186:189], v[82:85]
	v_mfma_f32_16x16x32_bf16 v[126:129], v[134:137], v[166:169], v[126:129]
	v_mfma_f32_16x16x32_bf16 v[122:125], v[142:145], v[166:169], v[122:125]
	v_mfma_f32_16x16x32_bf16 v[114:117], v[134:137], v[174:177], v[114:117]
	v_mfma_f32_16x16x32_bf16 v[106:109], v[142:145], v[174:177], v[106:109]
	v_mfma_f32_16x16x32_bf16 v[94:97], v[134:137], v[182:185], v[94:97]
	v_mfma_f32_16x16x32_bf16 v[90:93], v[142:145], v[182:185], v[90:93]
	v_mfma_f32_16x16x32_bf16 v[86:89], v[134:137], v[190:193], v[86:89]
	v_mfma_f32_16x16x32_bf16 v[82:85], v[142:145], v[190:193], v[82:85]
	s_setprio 0
	s_setprio 1
	v_mfma_f32_16x16x32_bf16 v[118:121], v[146:149], v[162:165], v[118:121]
	v_mfma_f32_16x16x32_bf16 v[110:113], v[154:157], v[162:165], v[110:113]
	v_mfma_f32_16x16x32_bf16 v[102:105], v[146:149], v[170:173], v[102:105]
	v_mfma_f32_16x16x32_bf16 v[98:101], v[154:157], v[170:173], v[98:101]
	v_mfma_f32_16x16x32_bf16 v[78:81], v[146:149], v[178:181], v[78:81]
	v_mfma_f32_16x16x32_bf16 v[74:77], v[154:157], v[178:181], v[74:77]
	v_mfma_f32_16x16x32_bf16 v[70:73], v[146:149], v[186:189], v[70:73]
	v_mfma_f32_16x16x32_bf16 v[66:69], v[154:157], v[186:189], v[66:69]
	v_mfma_f32_16x16x32_bf16 v[118:121], v[150:153], v[166:169], v[118:121]
	v_mfma_f32_16x16x32_bf16 v[110:113], v[158:161], v[166:169], v[110:113]
	v_mfma_f32_16x16x32_bf16 v[102:105], v[150:153], v[174:177], v[102:105]
	v_mfma_f32_16x16x32_bf16 v[98:101], v[158:161], v[174:177], v[98:101]
	v_mfma_f32_16x16x32_bf16 v[78:81], v[150:153], v[182:185], v[78:81]
	v_mfma_f32_16x16x32_bf16 v[74:77], v[158:161], v[182:185], v[74:77]
	v_mfma_f32_16x16x32_bf16 v[70:73], v[150:153], v[190:193], v[70:73]
	v_mfma_f32_16x16x32_bf16 v[66:69], v[158:161], v[190:193], v[66:69]
	s_barrier
	s_setprio 0
	s_add_i32 s18, s38, s46
	v_lshl_add_u64 v[194:195], v[194:195], 0, s[2:3]
	s_mov_b32 m0, s18
	ds_read_b128 v[162:165], v247 offset:49152
	ds_read_b128 v[166:169], v247 offset:50176
	ds_read_b128 v[170:173], v247 offset:51200
	ds_read_b128 v[174:177], v247 offset:52224
	ds_read_b128 v[178:181], v247 offset:53248
	ds_read_b128 v[182:185], v247 offset:54272
	ds_read_b128 v[186:189], v247 offset:55296
	ds_read_b128 v[190:193], v247 offset:56320
	global_load_lds_dwordx4 v[194:195], off
	s_add_i32 m0, s18, 0x2000
	s_add_u32 s16, s16, 0x164080
	v_lshl_add_u64 v[194:195], v[196:197], 0, s[2:3]
	s_addc_u32 s17, s17, 0
	s_add_i32 s18, s39, s46
	global_load_lds_dwordx4 v[194:195], off
	v_lshl_add_u64 v[194:195], s[16:17], 0, v[222:223]
	s_mov_b32 m0, s18
	s_nop 0
	global_load_lds_dwordx4 v[194:195], off
	v_lshl_add_u64 v[194:195], s[16:17], 0, v[226:227]
	s_add_i32 m0, s18, 0x2000
	s_nop 0
	global_load_lds_dwordx4 v[194:195], off
	v_lshl_add_u64 v[194:195], s[14:15], 0, v[220:221]
	s_mov_b32 m0, s50
	s_nop 0
	global_load_lds_dwordx4 v[194:195], off
	v_lshl_add_u64 v[194:195], s[14:15], 0, v[224:225]
	s_mov_b32 m0, s51
	s_nop 0
	global_load_lds_dwordx4 v[194:195], off
	s_waitcnt vmcnt(8)
	s_waitcnt lgkmcnt(0)
	s_setprio 1
	s_barrier
	v_mfma_f32_16x16x32_bf16 v[62:65], v[130:133], v[162:165], v[62:65]
	v_mfma_f32_16x16x32_bf16 v[58:61], v[138:141], v[162:165], v[58:61]
	v_mfma_f32_16x16x32_bf16 v[54:57], v[130:133], v[170:173], v[54:57]
	v_mfma_f32_16x16x32_bf16 v[50:53], v[138:141], v[170:173], v[50:53]
	v_mfma_f32_16x16x32_bf16 v[30:33], v[130:133], v[178:181], v[30:33]
	v_mfma_f32_16x16x32_bf16 v[26:29], v[138:141], v[178:181], v[26:29]
	v_mfma_f32_16x16x32_bf16 v[22:25], v[130:133], v[186:189], v[22:25]
	v_mfma_f32_16x16x32_bf16 v[18:21], v[138:141], v[186:189], v[18:21]
	v_mfma_f32_16x16x32_bf16 v[62:65], v[134:137], v[166:169], v[62:65]
	v_mfma_f32_16x16x32_bf16 v[58:61], v[142:145], v[166:169], v[58:61]
	v_mfma_f32_16x16x32_bf16 v[54:57], v[134:137], v[174:177], v[54:57]
	v_mfma_f32_16x16x32_bf16 v[50:53], v[142:145], v[174:177], v[50:53]
	v_mfma_f32_16x16x32_bf16 v[30:33], v[134:137], v[182:185], v[30:33]
	v_mfma_f32_16x16x32_bf16 v[26:29], v[142:145], v[182:185], v[26:29]
	v_mfma_f32_16x16x32_bf16 v[22:25], v[134:137], v[190:193], v[22:25]
	v_mfma_f32_16x16x32_bf16 v[18:21], v[142:145], v[190:193], v[18:21]
	s_setprio 0
	s_setprio 1
	v_mfma_f32_16x16x32_bf16 v[46:49], v[146:149], v[162:165], v[46:49]
	v_mfma_f32_16x16x32_bf16 v[42:45], v[154:157], v[162:165], v[42:45]
	v_mfma_f32_16x16x32_bf16 v[38:41], v[146:149], v[170:173], v[38:41]
	v_mfma_f32_16x16x32_bf16 v[34:37], v[154:157], v[170:173], v[34:37]
	v_mfma_f32_16x16x32_bf16 v[14:17], v[146:149], v[178:181], v[14:17]
	v_mfma_f32_16x16x32_bf16 v[10:13], v[154:157], v[178:181], v[10:13]
	v_mfma_f32_16x16x32_bf16 v[6:9], v[146:149], v[186:189], v[6:9]
	v_mfma_f32_16x16x32_bf16 v[2:5], v[154:157], v[186:189], v[2:5]
	v_mfma_f32_16x16x32_bf16 v[46:49], v[150:153], v[166:169], v[46:49]
	v_mfma_f32_16x16x32_bf16 v[42:45], v[158:161], v[166:169], v[42:45]
	v_mfma_f32_16x16x32_bf16 v[38:41], v[150:153], v[174:177], v[38:41]
	v_mfma_f32_16x16x32_bf16 v[34:37], v[158:161], v[174:177], v[34:37]
	v_mfma_f32_16x16x32_bf16 v[14:17], v[150:153], v[182:185], v[14:17]
	v_mfma_f32_16x16x32_bf16 v[10:13], v[158:161], v[182:185], v[10:13]
	v_mfma_f32_16x16x32_bf16 v[6:9], v[150:153], v[190:193], v[6:9]
	v_mfma_f32_16x16x32_bf16 v[2:5], v[158:161], v[190:193], v[2:5]
	s_barrier
	s_setprio 0
	s_add_i32 s37, s37, 2
	s_add_u32 s11, s11, 0x100
	s_addc_u32 s36, s36, 0
	s_add_u32 s12, s12, 0x10000
	s_addc_u32 s13, s13, 0
	s_cmpk_gt_u32 s37, 0x55
	s_cbranch_scc1 .Lpeel_done_5
.LBB0_1844:
	s_add_u32 s14, s12, 0x4000
	s_addc_u32 s15, s13, 0
	s_cmpk_eq_i32 s37, 0x54
	s_cselect_b32 s18, s6, s14
	s_cselect_b32 s19, s7, s15
	s_cselect_b32 s16, s8, s11
	s_cselect_b32 s17, s9, s36
	s_add_u32 s14, s18, 0x8000
	s_addc_u32 s15, s19, 0
	s_add_i32 s38, 0, 0x10000
	v_add_u32_e32 v0, s38, v246
	s_add_i32 s40, 0, 0x14000
	ds_read_b128 v[130:133], v0
	ds_read_b128 v[134:137], v0 offset:1024
	ds_read_b128 v[138:141], v0 offset:2048
	ds_read_b128 v[142:145], v0 offset:3072
	v_add_u32_e32 v0, s40, v246
	ds_read_b128 v[146:149], v0
	ds_read_b128 v[150:153], v0 offset:1024
	ds_read_b128 v[154:157], v0 offset:2048
	ds_read_b128 v[158:161], v0 offset:3072
	v_lshl_add_u64 v[194:195], s[12:13], 0, v[228:229]
	s_add_i32 m0, s47, 0xc000
	ds_read_b128 v[162:165], v247
	ds_read_b128 v[166:169], v247 offset:1024
	ds_read_b128 v[170:173], v247 offset:2048
	ds_read_b128 v[174:177], v247 offset:3072
	ds_read_b128 v[178:181], v247 offset:4096
	ds_read_b128 v[182:185], v247 offset:5120
	ds_read_b128 v[186:189], v247 offset:6144
	ds_read_b128 v[190:193], v247 offset:7168
	global_load_lds_dwordx4 v[194:195], off
	v_lshl_add_u64 v[194:195], s[12:13], 0, v[230:231]
	s_add_i32 m0, s47, 0xe000
	s_nop 0
	global_load_lds_dwordx4 v[194:195], off
	s_waitcnt vmcnt(8)
	s_waitcnt lgkmcnt(0)
	s_setprio 1
	s_barrier
	v_mfma_f32_16x16x32_bf16 v[126:129], v[130:133], v[162:165], v[126:129]
	v_mfma_f32_16x16x32_bf16 v[122:125], v[138:141], v[162:165], v[122:125]
	v_mfma_f32_16x16x32_bf16 v[114:117], v[130:133], v[170:173], v[114:117]
	v_mfma_f32_16x16x32_bf16 v[106:109], v[138:141], v[170:173], v[106:109]
	v_mfma_f32_16x16x32_bf16 v[94:97], v[130:133], v[178:181], v[94:97]
	v_mfma_f32_16x16x32_bf16 v[90:93], v[138:141], v[178:181], v[90:93]
	v_mfma_f32_16x16x32_bf16 v[86:89], v[130:133], v[186:189], v[86:89]
	v_mfma_f32_16x16x32_bf16 v[82:85], v[138:141], v[186:189], v[82:85]
	v_mfma_f32_16x16x32_bf16 v[126:129], v[134:137], v[166:169], v[126:129]
	v_mfma_f32_16x16x32_bf16 v[122:125], v[142:145], v[166:169], v[122:125]
	v_mfma_f32_16x16x32_bf16 v[114:117], v[134:137], v[174:177], v[114:117]
	v_mfma_f32_16x16x32_bf16 v[106:109], v[142:145], v[174:177], v[106:109]
	v_mfma_f32_16x16x32_bf16 v[94:97], v[134:137], v[182:185], v[94:97]
	v_mfma_f32_16x16x32_bf16 v[90:93], v[142:145], v[182:185], v[90:93]
	v_mfma_f32_16x16x32_bf16 v[86:89], v[134:137], v[190:193], v[86:89]
	v_mfma_f32_16x16x32_bf16 v[82:85], v[142:145], v[190:193], v[82:85]
	s_setprio 0
	s_setprio 1
	v_mfma_f32_16x16x32_bf16 v[118:121], v[146:149], v[162:165], v[118:121]
	v_mfma_f32_16x16x32_bf16 v[110:113], v[154:157], v[162:165], v[110:113]
	v_mfma_f32_16x16x32_bf16 v[102:105], v[146:149], v[170:173], v[102:105]
	v_mfma_f32_16x16x32_bf16 v[98:101], v[154:157], v[170:173], v[98:101]
	v_mfma_f32_16x16x32_bf16 v[78:81], v[146:149], v[178:181], v[78:81]
	v_mfma_f32_16x16x32_bf16 v[74:77], v[154:157], v[178:181], v[74:77]
	v_mfma_f32_16x16x32_bf16 v[70:73], v[146:149], v[186:189], v[70:73]
	v_mfma_f32_16x16x32_bf16 v[66:69], v[154:157], v[186:189], v[66:69]
	v_mfma_f32_16x16x32_bf16 v[118:121], v[150:153], v[166:169], v[118:121]
	v_mfma_f32_16x16x32_bf16 v[110:113], v[158:161], v[166:169], v[110:113]
	v_mfma_f32_16x16x32_bf16 v[102:105], v[150:153], v[174:177], v[102:105]
	v_mfma_f32_16x16x32_bf16 v[98:101], v[158:161], v[174:177], v[98:101]
	v_mfma_f32_16x16x32_bf16 v[78:81], v[150:153], v[182:185], v[78:81]
	v_mfma_f32_16x16x32_bf16 v[74:77], v[158:161], v[182:185], v[74:77]
	v_mfma_f32_16x16x32_bf16 v[70:73], v[150:153], v[190:193], v[70:73]
	v_mfma_f32_16x16x32_bf16 v[66:69], v[158:161], v[190:193], v[66:69]
	s_barrier
	s_setprio 0
	s_add_i32 s38, s38, s46
	v_lshl_add_u64 v[194:195], s[16:17], 0, v[222:223]
	s_mov_b32 m0, s38
	ds_read_b128 v[162:165], v247 offset:16384
	ds_read_b128 v[166:169], v247 offset:17408
	ds_read_b128 v[170:173], v247 offset:18432
	ds_read_b128 v[174:177], v247 offset:19456
	ds_read_b128 v[178:181], v247 offset:20480
	ds_read_b128 v[182:185], v247 offset:21504
	ds_read_b128 v[186:189], v247 offset:22528
	ds_read_b128 v[190:193], v247 offset:23552
	global_load_lds_dwordx4 v[194:195], off
	s_add_i32 m0, s38, 0x2000
	s_add_u32 s38, s16, 0x164000
	v_lshl_add_u64 v[196:197], s[16:17], 0, v[226:227]
	s_addc_u32 s39, s17, 0
	s_add_i32 s40, s40, s46
	global_load_lds_dwordx4 v[196:197], off
	v_lshl_add_u64 v[198:199], s[38:39], 0, v[222:223]
	s_mov_b32 m0, s40
	s_nop 0
	global_load_lds_dwordx4 v[198:199], off
	v_lshl_add_u64 v[198:199], s[38:39], 0, v[226:227]
	s_add_i32 m0, s40, 0x2000
	s_nop 0
	global_load_lds_dwordx4 v[198:199], off
	v_lshl_add_u64 v[198:199], s[18:19], 0, v[220:221]
	s_mov_b32 m0, s47
	s_nop 0
	global_load_lds_dwordx4 v[198:199], off
	v_lshl_add_u64 v[198:199], s[18:19], 0, v[224:225]
	s_mov_b32 m0, s74
	s_nop 0
	global_load_lds_dwordx4 v[198:199], off
	s_waitcnt vmcnt(8)
	s_waitcnt lgkmcnt(0)
	s_setprio 1
	s_barrier
	v_mfma_f32_16x16x32_bf16 v[62:65], v[130:133], v[162:165], v[62:65]
	v_mfma_f32_16x16x32_bf16 v[58:61], v[138:141], v[162:165], v[58:61]
	v_mfma_f32_16x16x32_bf16 v[54:57], v[130:133], v[170:173], v[54:57]
	v_mfma_f32_16x16x32_bf16 v[50:53], v[138:141], v[170:173], v[50:53]
	v_mfma_f32_16x16x32_bf16 v[30:33], v[130:133], v[178:181], v[30:33]
	v_mfma_f32_16x16x32_bf16 v[26:29], v[138:141], v[178:181], v[26:29]
	v_mfma_f32_16x16x32_bf16 v[22:25], v[130:133], v[186:189], v[22:25]
	v_mfma_f32_16x16x32_bf16 v[18:21], v[138:141], v[186:189], v[18:21]
	v_mfma_f32_16x16x32_bf16 v[62:65], v[134:137], v[166:169], v[62:65]
	v_mfma_f32_16x16x32_bf16 v[58:61], v[142:145], v[166:169], v[58:61]
	v_mfma_f32_16x16x32_bf16 v[54:57], v[134:137], v[174:177], v[54:57]
	v_mfma_f32_16x16x32_bf16 v[50:53], v[142:145], v[174:177], v[50:53]
	v_mfma_f32_16x16x32_bf16 v[30:33], v[134:137], v[182:185], v[30:33]
	v_mfma_f32_16x16x32_bf16 v[26:29], v[142:145], v[182:185], v[26:29]
	v_mfma_f32_16x16x32_bf16 v[22:25], v[134:137], v[190:193], v[22:25]
	v_mfma_f32_16x16x32_bf16 v[18:21], v[142:145], v[190:193], v[18:21]
	s_setprio 0
	s_setprio 1
	v_mfma_f32_16x16x32_bf16 v[46:49], v[146:149], v[162:165], v[46:49]
	v_mfma_f32_16x16x32_bf16 v[42:45], v[154:157], v[162:165], v[42:45]
	v_mfma_f32_16x16x32_bf16 v[38:41], v[146:149], v[170:173], v[38:41]
	v_mfma_f32_16x16x32_bf16 v[34:37], v[154:157], v[170:173], v[34:37]
	v_mfma_f32_16x16x32_bf16 v[14:17], v[146:149], v[178:181], v[14:17]
	v_mfma_f32_16x16x32_bf16 v[10:13], v[154:157], v[178:181], v[10:13]
	v_mfma_f32_16x16x32_bf16 v[6:9], v[146:149], v[186:189], v[6:9]
	v_mfma_f32_16x16x32_bf16 v[2:5], v[154:157], v[186:189], v[2:5]
	v_mfma_f32_16x16x32_bf16 v[46:49], v[150:153], v[166:169], v[46:49]
	v_mfma_f32_16x16x32_bf16 v[42:45], v[158:161], v[166:169], v[42:45]
	v_mfma_f32_16x16x32_bf16 v[38:41], v[150:153], v[174:177], v[38:41]
	v_mfma_f32_16x16x32_bf16 v[34:37], v[158:161], v[174:177], v[34:37]
	v_mfma_f32_16x16x32_bf16 v[14:17], v[150:153], v[182:185], v[14:17]
	v_mfma_f32_16x16x32_bf16 v[10:13], v[158:161], v[182:185], v[10:13]
	v_mfma_f32_16x16x32_bf16 v[6:9], v[150:153], v[190:193], v[6:9]
	v_mfma_f32_16x16x32_bf16 v[2:5], v[158:161], v[190:193], v[2:5]
	s_barrier
	s_setprio 0
	s_add_i32 s38, 0, 0x18000
	v_add_u32_e32 v0, s38, v246
	s_add_i32 s39, 0, 0x1c000
	ds_read_b128 v[130:133], v0
	ds_read_b128 v[134:137], v0 offset:1024
	ds_read_b128 v[138:141], v0 offset:2048
	ds_read_b128 v[142:145], v0 offset:3072
	v_add_u32_e32 v0, s39, v246
	ds_read_b128 v[146:149], v0
	ds_read_b128 v[150:153], v0 offset:1024
	ds_read_b128 v[154:157], v0 offset:2048
	ds_read_b128 v[158:161], v0 offset:3072
	s_add_u32 s18, s18, 0x4000
	s_addc_u32 s19, s19, 0
	s_mov_b32 m0, s75
	v_lshl_add_u64 v[198:199], s[18:19], 0, v[220:221]
	ds_read_b128 v[162:165], v247 offset:32768
	ds_read_b128 v[166:169], v247 offset:33792
	ds_read_b128 v[170:173], v247 offset:34816
	ds_read_b128 v[174:177], v247 offset:35840
	ds_read_b128 v[178:181], v247 offset:36864
	ds_read_b128 v[182:185], v247 offset:37888
	ds_read_b128 v[186:189], v247 offset:38912
	ds_read_b128 v[190:193], v247 offset:39936
	global_load_lds_dwordx4 v[198:199], off
	v_lshl_add_u64 v[198:199], s[18:19], 0, v[224:225]
	s_mov_b32 m0, s86
	s_nop 0
	global_load_lds_dwordx4 v[198:199], off
	s_waitcnt vmcnt(8)
	s_waitcnt lgkmcnt(0)
	s_setprio 1
	s_barrier
	v_mfma_f32_16x16x32_bf16 v[126:129], v[130:133], v[162:165], v[126:129]
	v_mfma_f32_16x16x32_bf16 v[122:125], v[138:141], v[162:165], v[122:125]
	v_mfma_f32_16x16x32_bf16 v[114:117], v[130:133], v[170:173], v[114:117]
	v_mfma_f32_16x16x32_bf16 v[106:109], v[138:141], v[170:173], v[106:109]
	v_mfma_f32_16x16x32_bf16 v[94:97], v[130:133], v[178:181], v[94:97]
	v_mfma_f32_16x16x32_bf16 v[90:93], v[138:141], v[178:181], v[90:93]
	v_mfma_f32_16x16x32_bf16 v[86:89], v[130:133], v[186:189], v[86:89]
	v_mfma_f32_16x16x32_bf16 v[82:85], v[138:141], v[186:189], v[82:85]
	v_mfma_f32_16x16x32_bf16 v[126:129], v[134:137], v[166:169], v[126:129]
	v_mfma_f32_16x16x32_bf16 v[122:125], v[142:145], v[166:169], v[122:125]
	v_mfma_f32_16x16x32_bf16 v[114:117], v[134:137], v[174:177], v[114:117]
	v_mfma_f32_16x16x32_bf16 v[106:109], v[142:145], v[174:177], v[106:109]
	v_mfma_f32_16x16x32_bf16 v[94:97], v[134:137], v[182:185], v[94:97]
	v_mfma_f32_16x16x32_bf16 v[90:93], v[142:145], v[182:185], v[90:93]
	v_mfma_f32_16x16x32_bf16 v[86:89], v[134:137], v[190:193], v[86:89]
	v_mfma_f32_16x16x32_bf16 v[82:85], v[142:145], v[190:193], v[82:85]
	s_setprio 0
	s_setprio 1
	v_mfma_f32_16x16x32_bf16 v[118:121], v[146:149], v[162:165], v[118:121]
	v_mfma_f32_16x16x32_bf16 v[110:113], v[154:157], v[162:165], v[110:113]
	v_mfma_f32_16x16x32_bf16 v[102:105], v[146:149], v[170:173], v[102:105]
	v_mfma_f32_16x16x32_bf16 v[98:101], v[154:157], v[170:173], v[98:101]
	v_mfma_f32_16x16x32_bf16 v[78:81], v[146:149], v[178:181], v[78:81]
	v_mfma_f32_16x16x32_bf16 v[74:77], v[154:157], v[178:181], v[74:77]
	v_mfma_f32_16x16x32_bf16 v[70:73], v[146:149], v[186:189], v[70:73]
	v_mfma_f32_16x16x32_bf16 v[66:69], v[154:157], v[186:189], v[66:69]
	v_mfma_f32_16x16x32_bf16 v[118:121], v[150:153], v[166:169], v[118:121]
	v_mfma_f32_16x16x32_bf16 v[110:113], v[158:161], v[166:169], v[110:113]
	v_mfma_f32_16x16x32_bf16 v[102:105], v[150:153], v[174:177], v[102:105]
	v_mfma_f32_16x16x32_bf16 v[98:101], v[158:161], v[174:177], v[98:101]
	v_mfma_f32_16x16x32_bf16 v[78:81], v[150:153], v[182:185], v[78:81]
	v_mfma_f32_16x16x32_bf16 v[74:77], v[158:161], v[182:185], v[74:77]
	v_mfma_f32_16x16x32_bf16 v[70:73], v[150:153], v[190:193], v[70:73]
	v_mfma_f32_16x16x32_bf16 v[66:69], v[158:161], v[190:193], v[66:69]
	s_barrier
	s_setprio 0
	s_add_i32 s18, s38, s46
	v_lshl_add_u64 v[194:195], v[194:195], 0, s[2:3]
	s_mov_b32 m0, s18
	ds_read_b128 v[162:165], v247 offset:49152
	ds_read_b128 v[166:169], v247 offset:50176
	ds_read_b128 v[170:173], v247 offset:51200
	ds_read_b128 v[174:177], v247 offset:52224
	ds_read_b128 v[178:181], v247 offset:53248
	ds_read_b128 v[182:185], v247 offset:54272
	ds_read_b128 v[186:189], v247 offset:55296
	ds_read_b128 v[190:193], v247 offset:56320
	global_load_lds_dwordx4 v[194:195], off
	s_add_i32 m0, s18, 0x2000
	s_add_u32 s16, s16, 0x164080
	v_lshl_add_u64 v[194:195], v[196:197], 0, s[2:3]
	s_addc_u32 s17, s17, 0
	s_add_i32 s18, s39, s46
	global_load_lds_dwordx4 v[194:195], off
	v_lshl_add_u64 v[194:195], s[16:17], 0, v[222:223]
	s_mov_b32 m0, s18
	s_nop 0
	global_load_lds_dwordx4 v[194:195], off
	v_lshl_add_u64 v[194:195], s[16:17], 0, v[226:227]
	s_add_i32 m0, s18, 0x2000
	s_nop 0
	global_load_lds_dwordx4 v[194:195], off
	v_lshl_add_u64 v[194:195], s[14:15], 0, v[220:221]
	s_mov_b32 m0, s50
	s_nop 0
	global_load_lds_dwordx4 v[194:195], off
	v_lshl_add_u64 v[194:195], s[14:15], 0, v[224:225]
	s_mov_b32 m0, s51
	s_nop 0
	global_load_lds_dwordx4 v[194:195], off
	s_waitcnt vmcnt(8)
	s_waitcnt lgkmcnt(0)
	s_setprio 1
	s_barrier
	v_mfma_f32_16x16x32_bf16 v[62:65], v[130:133], v[162:165], v[62:65]
	v_mfma_f32_16x16x32_bf16 v[58:61], v[138:141], v[162:165], v[58:61]
	v_mfma_f32_16x16x32_bf16 v[54:57], v[130:133], v[170:173], v[54:57]
	v_mfma_f32_16x16x32_bf16 v[50:53], v[138:141], v[170:173], v[50:53]
	v_mfma_f32_16x16x32_bf16 v[30:33], v[130:133], v[178:181], v[30:33]
	v_mfma_f32_16x16x32_bf16 v[26:29], v[138:141], v[178:181], v[26:29]
	v_mfma_f32_16x16x32_bf16 v[22:25], v[130:133], v[186:189], v[22:25]
	v_mfma_f32_16x16x32_bf16 v[18:21], v[138:141], v[186:189], v[18:21]
	v_mfma_f32_16x16x32_bf16 v[62:65], v[134:137], v[166:169], v[62:65]
	v_mfma_f32_16x16x32_bf16 v[58:61], v[142:145], v[166:169], v[58:61]
	v_mfma_f32_16x16x32_bf16 v[54:57], v[134:137], v[174:177], v[54:57]
	v_mfma_f32_16x16x32_bf16 v[50:53], v[142:145], v[174:177], v[50:53]
	v_mfma_f32_16x16x32_bf16 v[30:33], v[134:137], v[182:185], v[30:33]
	v_mfma_f32_16x16x32_bf16 v[26:29], v[142:145], v[182:185], v[26:29]
	v_mfma_f32_16x16x32_bf16 v[22:25], v[134:137], v[190:193], v[22:25]
	v_mfma_f32_16x16x32_bf16 v[18:21], v[142:145], v[190:193], v[18:21]
	s_setprio 0
	s_setprio 1
	v_mfma_f32_16x16x32_bf16 v[46:49], v[146:149], v[162:165], v[46:49]
	v_mfma_f32_16x16x32_bf16 v[42:45], v[154:157], v[162:165], v[42:45]
	v_mfma_f32_16x16x32_bf16 v[38:41], v[146:149], v[170:173], v[38:41]
	v_mfma_f32_16x16x32_bf16 v[34:37], v[154:157], v[170:173], v[34:37]
	v_mfma_f32_16x16x32_bf16 v[14:17], v[146:149], v[178:181], v[14:17]
	v_mfma_f32_16x16x32_bf16 v[10:13], v[154:157], v[178:181], v[10:13]
	v_mfma_f32_16x16x32_bf16 v[6:9], v[146:149], v[186:189], v[6:9]
	v_mfma_f32_16x16x32_bf16 v[2:5], v[154:157], v[186:189], v[2:5]
	v_mfma_f32_16x16x32_bf16 v[46:49], v[150:153], v[166:169], v[46:49]
	v_mfma_f32_16x16x32_bf16 v[42:45], v[158:161], v[166:169], v[42:45]
	v_mfma_f32_16x16x32_bf16 v[38:41], v[150:153], v[174:177], v[38:41]
	v_mfma_f32_16x16x32_bf16 v[34:37], v[158:161], v[174:177], v[34:37]
	v_mfma_f32_16x16x32_bf16 v[14:17], v[150:153], v[182:185], v[14:17]
	v_mfma_f32_16x16x32_bf16 v[10:13], v[158:161], v[182:185], v[10:13]
	v_mfma_f32_16x16x32_bf16 v[6:9], v[150:153], v[190:193], v[6:9]
	v_mfma_f32_16x16x32_bf16 v[2:5], v[158:161], v[190:193], v[2:5]
	s_barrier
	s_setprio 0
	s_add_i32 s37, s37, 2
	s_add_u32 s11, s11, 0x100
	s_addc_u32 s36, s36, 0
	s_add_u32 s12, s12, 0x10000
	s_addc_u32 s13, s13, 0
	s_cmpk_gt_u32 s37, 0x55
	s_cbranch_scc0 .LBB0_1844

.LBB0_2016:
	s_add_u32 s36, s12, 0x100
	s_addc_u32 s37, s13, 0
	s_add_u32 s12, s14, 0xc000
	s_addc_u32 s13, s15, 0
	s_mov_b32 s50, -2
	s_add_u32 s14, s12, 0x4000
	s_addc_u32 s15, s13, 0
	s_cmp_eq_u32 s50, 18
	s_cselect_b32 s18, s8, s14
	s_cselect_b32 s19, s9, s15
	s_cselect_b32 s16, s10, s36
	s_cselect_b32 s17, s11, s37
	s_add_u32 s14, s18, 0x8000
	s_addc_u32 s15, s19, 0
	s_add_i32 s51, 0, 0x10000
	s_add_i32 s54, 0, 0x14000
	v_add_u32_e32 v156, s51, v140
	v_add_u32_e32 v172, s54, v140
	ds_read_b128 v[144:147], v156
	ds_read_b128 v[148:151], v156 offset:1024
	ds_read_b128 v[152:155], v156 offset:2048
	ds_read_b128 v[156:159], v156 offset:3072
	ds_read_b128 v[160:163], v172
	ds_read_b128 v[164:167], v172 offset:1024
	ds_read_b128 v[168:171], v172 offset:2048
	ds_read_b128 v[172:175], v172 offset:3072
	v_lshl_add_u64 v[208:209], s[12:13], 0, v[136:137]
	s_add_i32 m0, s38, 0xc000
	ds_read_b128 v[176:179], v143
	ds_read_b128 v[180:183], v143 offset:1024
	ds_read_b128 v[184:187], v143 offset:2048
	ds_read_b128 v[188:191], v143 offset:3072
	ds_read_b128 v[192:195], v143 offset:4096
	ds_read_b128 v[196:199], v143 offset:5120
	ds_read_b128 v[200:203], v143 offset:6144
	ds_read_b128 v[204:207], v143 offset:7168
	global_load_lds_dwordx4 v[208:209], off
	v_lshl_add_u64 v[208:209], s[12:13], 0, v[138:139]
	s_add_i32 m0, s38, 0xe000
	s_nop 0
	global_load_lds_dwordx4 v[208:209], off
	s_waitcnt vmcnt(8)
	s_waitcnt lgkmcnt(0)
	s_setprio 1
	s_barrier
	v_mfma_f32_16x16x32_bf16 v[126:129], v[144:147], v[176:179], 0
	v_mfma_f32_16x16x32_bf16 v[122:125], v[152:155], v[176:179], 0
	v_mfma_f32_16x16x32_bf16 v[118:121], v[144:147], v[184:187], 0
	v_mfma_f32_16x16x32_bf16 v[114:117], v[152:155], v[184:187], 0
	v_mfma_f32_16x16x32_bf16 v[102:105], v[144:147], v[192:195], 0
	v_mfma_f32_16x16x32_bf16 v[98:101], v[152:155], v[192:195], 0
	v_mfma_f32_16x16x32_bf16 v[86:89], v[144:147], v[200:203], 0
	v_mfma_f32_16x16x32_bf16 v[82:85], v[152:155], v[200:203], 0
	v_mfma_f32_16x16x32_bf16 v[126:129], v[148:151], v[180:183], v[126:129]
	v_mfma_f32_16x16x32_bf16 v[122:125], v[156:159], v[180:183], v[122:125]
	v_mfma_f32_16x16x32_bf16 v[118:121], v[148:151], v[188:191], v[118:121]
	v_mfma_f32_16x16x32_bf16 v[114:117], v[156:159], v[188:191], v[114:117]
	v_mfma_f32_16x16x32_bf16 v[102:105], v[148:151], v[196:199], v[102:105]
	v_mfma_f32_16x16x32_bf16 v[98:101], v[156:159], v[196:199], v[98:101]
	v_mfma_f32_16x16x32_bf16 v[86:89], v[148:151], v[204:207], v[86:89]
	v_mfma_f32_16x16x32_bf16 v[82:85], v[156:159], v[204:207], v[82:85]
	s_setprio 0
	s_setprio 1
	v_mfma_f32_16x16x32_bf16 v[110:113], v[160:163], v[176:179], 0
	v_mfma_f32_16x16x32_bf16 v[106:109], v[168:171], v[176:179], 0
	v_mfma_f32_16x16x32_bf16 v[94:97], v[160:163], v[184:187], 0
	v_mfma_f32_16x16x32_bf16 v[90:93], v[168:171], v[184:187], 0
	v_mfma_f32_16x16x32_bf16 v[78:81], v[160:163], v[192:195], 0
	v_mfma_f32_16x16x32_bf16 v[74:77], v[168:171], v[192:195], 0
	v_mfma_f32_16x16x32_bf16 v[70:73], v[160:163], v[200:203], 0
	v_mfma_f32_16x16x32_bf16 v[66:69], v[168:171], v[200:203], 0
	v_mfma_f32_16x16x32_bf16 v[110:113], v[164:167], v[180:183], v[110:113]
	v_mfma_f32_16x16x32_bf16 v[106:109], v[172:175], v[180:183], v[106:109]
	v_mfma_f32_16x16x32_bf16 v[94:97], v[164:167], v[188:191], v[94:97]
	v_mfma_f32_16x16x32_bf16 v[90:93], v[172:175], v[188:191], v[90:93]
	v_mfma_f32_16x16x32_bf16 v[78:81], v[164:167], v[196:199], v[78:81]
	v_mfma_f32_16x16x32_bf16 v[74:77], v[172:175], v[196:199], v[74:77]
	v_mfma_f32_16x16x32_bf16 v[70:73], v[164:167], v[204:207], v[70:73]
	v_mfma_f32_16x16x32_bf16 v[66:69], v[172:175], v[204:207], v[66:69]
	s_barrier
	s_setprio 0
	s_add_i32 s51, s51, s24
	v_lshl_add_u64 v[208:209], s[16:17], 0, v[0:1]
	s_mov_b32 m0, s51
	ds_read_b128 v[176:179], v143 offset:16384
	ds_read_b128 v[180:183], v143 offset:17408
	ds_read_b128 v[184:187], v143 offset:18432
	ds_read_b128 v[188:191], v143 offset:19456
	ds_read_b128 v[192:195], v143 offset:20480
	ds_read_b128 v[196:199], v143 offset:21504
	ds_read_b128 v[200:203], v143 offset:22528
	ds_read_b128 v[204:207], v143 offset:23552
	global_load_lds_dwordx4 v[208:209], off
	s_add_i32 m0, s51, 0x2000
	s_add_u32 s52, s16, 0x164000
	v_lshl_add_u64 v[216:217], s[16:17], 0, v[130:131]
	s_addc_u32 s53, s17, 0
	s_add_i32 s51, s54, s24
	global_load_lds_dwordx4 v[216:217], off
	v_lshl_add_u64 v[220:221], s[52:53], 0, v[0:1]
	s_mov_b32 m0, s51
	s_nop 0
	global_load_lds_dwordx4 v[220:221], off
	v_lshl_add_u64 v[220:221], s[52:53], 0, v[130:131]
	s_add_i32 m0, s51, 0x2000
	s_nop 0
	global_load_lds_dwordx4 v[220:221], off
	v_lshl_add_u64 v[220:221], s[18:19], 0, v[134:135]
	s_mov_b32 m0, s38
	s_nop 0
	global_load_lds_dwordx4 v[220:221], off
	v_lshl_add_u64 v[220:221], s[18:19], 0, v[132:133]
	s_mov_b32 m0, s39
	s_nop 0
	global_load_lds_dwordx4 v[220:221], off
	s_waitcnt vmcnt(8)
	s_waitcnt lgkmcnt(0)
	s_setprio 1
	s_barrier
	v_mfma_f32_16x16x32_bf16 v[62:65], v[144:147], v[176:179], 0
	v_mfma_f32_16x16x32_bf16 v[58:61], v[152:155], v[176:179], 0
	v_mfma_f32_16x16x32_bf16 v[54:57], v[144:147], v[184:187], 0
	v_mfma_f32_16x16x32_bf16 v[50:53], v[152:155], v[184:187], 0
	v_mfma_f32_16x16x32_bf16 v[38:41], v[144:147], v[192:195], 0
	v_mfma_f32_16x16x32_bf16 v[34:37], v[152:155], v[192:195], 0
	v_mfma_f32_16x16x32_bf16 v[22:25], v[144:147], v[200:203], 0
	v_mfma_f32_16x16x32_bf16 v[18:21], v[152:155], v[200:203], 0
	v_mfma_f32_16x16x32_bf16 v[62:65], v[148:151], v[180:183], v[62:65]
	v_mfma_f32_16x16x32_bf16 v[58:61], v[156:159], v[180:183], v[58:61]
	v_mfma_f32_16x16x32_bf16 v[54:57], v[148:151], v[188:191], v[54:57]
	v_mfma_f32_16x16x32_bf16 v[50:53], v[156:159], v[188:191], v[50:53]
	v_mfma_f32_16x16x32_bf16 v[38:41], v[148:151], v[196:199], v[38:41]
	v_mfma_f32_16x16x32_bf16 v[34:37], v[156:159], v[196:199], v[34:37]
	v_mfma_f32_16x16x32_bf16 v[22:25], v[148:151], v[204:207], v[22:25]
	v_mfma_f32_16x16x32_bf16 v[18:21], v[156:159], v[204:207], v[18:21]
	s_setprio 0
	s_setprio 1
	v_mfma_f32_16x16x32_bf16 v[46:49], v[160:163], v[176:179], 0
	v_mfma_f32_16x16x32_bf16 v[42:45], v[168:171], v[176:179], 0
	v_mfma_f32_16x16x32_bf16 v[30:33], v[160:163], v[184:187], 0
	v_mfma_f32_16x16x32_bf16 v[26:29], v[168:171], v[184:187], 0
	v_mfma_f32_16x16x32_bf16 v[14:17], v[160:163], v[192:195], 0
	v_mfma_f32_16x16x32_bf16 v[10:13], v[168:171], v[192:195], 0
	v_mfma_f32_16x16x32_bf16 v[6:9], v[160:163], v[200:203], 0
	v_mfma_f32_16x16x32_bf16 v[2:5], v[168:171], v[200:203], 0
	v_mfma_f32_16x16x32_bf16 v[46:49], v[164:167], v[180:183], v[46:49]
	v_mfma_f32_16x16x32_bf16 v[42:45], v[172:175], v[180:183], v[42:45]
	v_mfma_f32_16x16x32_bf16 v[30:33], v[164:167], v[188:191], v[30:33]
	v_mfma_f32_16x16x32_bf16 v[26:29], v[172:175], v[188:191], v[26:29]
	v_mfma_f32_16x16x32_bf16 v[14:17], v[164:167], v[196:199], v[14:17]
	v_mfma_f32_16x16x32_bf16 v[10:13], v[172:175], v[196:199], v[10:13]
	v_mfma_f32_16x16x32_bf16 v[6:9], v[164:167], v[204:207], v[6:9]
	v_mfma_f32_16x16x32_bf16 v[2:5], v[172:175], v[204:207], v[2:5]
	s_barrier
	s_setprio 0
	s_add_i32 s51, 0, 0x18000
	s_add_i32 s52, 0, 0x1c000
	v_add_u32_e32 v156, s51, v140
	v_add_u32_e32 v172, s52, v140
	ds_read_b128 v[144:147], v156
	ds_read_b128 v[148:151], v156 offset:1024
	ds_read_b128 v[152:155], v156 offset:2048
	ds_read_b128 v[156:159], v156 offset:3072
	ds_read_b128 v[160:163], v172
	ds_read_b128 v[164:167], v172 offset:1024
	ds_read_b128 v[168:171], v172 offset:2048
	ds_read_b128 v[172:175], v172 offset:3072
	s_add_u32 s18, s18, 0x4000
	s_addc_u32 s19, s19, 0
	s_mov_b32 m0, s40
	v_lshl_add_u64 v[220:221], s[18:19], 0, v[134:135]
	ds_read_b128 v[176:179], v143 offset:32768
	ds_read_b128 v[180:183], v143 offset:33792
	ds_read_b128 v[184:187], v143 offset:34816
	ds_read_b128 v[188:191], v143 offset:35840
	ds_read_b128 v[192:195], v143 offset:36864
	ds_read_b128 v[196:199], v143 offset:37888
	ds_read_b128 v[200:203], v143 offset:38912
	ds_read_b128 v[204:207], v143 offset:39936
	global_load_lds_dwordx4 v[220:221], off
	v_lshl_add_u64 v[220:221], s[18:19], 0, v[132:133]
	s_mov_b32 m0, s41
	s_nop 0
	global_load_lds_dwordx4 v[220:221], off
	s_waitcnt vmcnt(8)
	s_waitcnt lgkmcnt(0)
	s_setprio 1
	s_barrier
	v_mfma_f32_16x16x32_bf16 v[126:129], v[144:147], v[176:179], v[126:129]
	v_mfma_f32_16x16x32_bf16 v[122:125], v[152:155], v[176:179], v[122:125]
	v_mfma_f32_16x16x32_bf16 v[118:121], v[144:147], v[184:187], v[118:121]
	v_mfma_f32_16x16x32_bf16 v[114:117], v[152:155], v[184:187], v[114:117]
	v_mfma_f32_16x16x32_bf16 v[102:105], v[144:147], v[192:195], v[102:105]
	v_mfma_f32_16x16x32_bf16 v[98:101], v[152:155], v[192:195], v[98:101]
	v_mfma_f32_16x16x32_bf16 v[86:89], v[144:147], v[200:203], v[86:89]
	v_mfma_f32_16x16x32_bf16 v[82:85], v[152:155], v[200:203], v[82:85]
	v_mfma_f32_16x16x32_bf16 v[126:129], v[148:151], v[180:183], v[126:129]
	v_mfma_f32_16x16x32_bf16 v[122:125], v[156:159], v[180:183], v[122:125]
	v_mfma_f32_16x16x32_bf16 v[118:121], v[148:151], v[188:191], v[118:121]
	v_mfma_f32_16x16x32_bf16 v[114:117], v[156:159], v[188:191], v[114:117]
	v_mfma_f32_16x16x32_bf16 v[102:105], v[148:151], v[196:199], v[102:105]
	v_mfma_f32_16x16x32_bf16 v[98:101], v[156:159], v[196:199], v[98:101]
	v_mfma_f32_16x16x32_bf16 v[86:89], v[148:151], v[204:207], v[86:89]
	v_mfma_f32_16x16x32_bf16 v[82:85], v[156:159], v[204:207], v[82:85]
	s_setprio 0
	s_setprio 1
	v_mfma_f32_16x16x32_bf16 v[110:113], v[160:163], v[176:179], v[110:113]
	v_mfma_f32_16x16x32_bf16 v[106:109], v[168:171], v[176:179], v[106:109]
	v_mfma_f32_16x16x32_bf16 v[94:97], v[160:163], v[184:187], v[94:97]
	v_mfma_f32_16x16x32_bf16 v[90:93], v[168:171], v[184:187], v[90:93]
	v_mfma_f32_16x16x32_bf16 v[78:81], v[160:163], v[192:195], v[78:81]
	v_mfma_f32_16x16x32_bf16 v[74:77], v[168:171], v[192:195], v[74:77]
	v_mfma_f32_16x16x32_bf16 v[70:73], v[160:163], v[200:203], v[70:73]
	v_mfma_f32_16x16x32_bf16 v[66:69], v[168:171], v[200:203], v[66:69]
	v_mfma_f32_16x16x32_bf16 v[110:113], v[164:167], v[180:183], v[110:113]
	v_mfma_f32_16x16x32_bf16 v[106:109], v[172:175], v[180:183], v[106:109]
	v_mfma_f32_16x16x32_bf16 v[94:97], v[164:167], v[188:191], v[94:97]
	v_mfma_f32_16x16x32_bf16 v[90:93], v[172:175], v[188:191], v[90:93]
	v_mfma_f32_16x16x32_bf16 v[78:81], v[164:167], v[196:199], v[78:81]
	v_mfma_f32_16x16x32_bf16 v[74:77], v[172:175], v[196:199], v[74:77]
	v_mfma_f32_16x16x32_bf16 v[70:73], v[164:167], v[204:207], v[70:73]
	v_mfma_f32_16x16x32_bf16 v[66:69], v[172:175], v[204:207], v[66:69]
	s_barrier
	s_setprio 0
	s_add_i32 s18, s51, s24
	v_lshl_add_u64 v[208:209], v[208:209], 0, s[2:3]
	s_mov_b32 m0, s18
	ds_read_b128 v[176:179], v143 offset:49152
	ds_read_b128 v[180:183], v143 offset:50176
	ds_read_b128 v[184:187], v143 offset:51200
	ds_read_b128 v[188:191], v143 offset:52224
	ds_read_b128 v[192:195], v143 offset:53248
	ds_read_b128 v[196:199], v143 offset:54272
	ds_read_b128 v[200:203], v143 offset:55296
	ds_read_b128 v[204:207], v143 offset:56320
	global_load_lds_dwordx4 v[208:209], off
	s_add_i32 m0, s18, 0x2000
	s_add_u32 s16, s16, 0x164080
	v_lshl_add_u64 v[208:209], v[216:217], 0, s[2:3]
	s_addc_u32 s17, s17, 0
	s_add_i32 s18, s52, s24
	global_load_lds_dwordx4 v[208:209], off
	v_lshl_add_u64 v[208:209], s[16:17], 0, v[0:1]
	s_mov_b32 m0, s18
	s_nop 0
	global_load_lds_dwordx4 v[208:209], off
	v_lshl_add_u64 v[208:209], s[16:17], 0, v[130:131]
	s_add_i32 m0, s18, 0x2000
	s_nop 0
	global_load_lds_dwordx4 v[208:209], off
	v_lshl_add_u64 v[208:209], s[14:15], 0, v[134:135]
	s_mov_b32 m0, s42
	s_nop 0
	global_load_lds_dwordx4 v[208:209], off
	v_lshl_add_u64 v[208:209], s[14:15], 0, v[132:133]
	s_mov_b32 m0, s43
	s_nop 0
	global_load_lds_dwordx4 v[208:209], off
	s_waitcnt vmcnt(8)
	s_waitcnt lgkmcnt(0)
	s_setprio 1
	s_barrier
	v_mfma_f32_16x16x32_bf16 v[62:65], v[144:147], v[176:179], v[62:65]
	v_mfma_f32_16x16x32_bf16 v[58:61], v[152:155], v[176:179], v[58:61]
	v_mfma_f32_16x16x32_bf16 v[54:57], v[144:147], v[184:187], v[54:57]
	v_mfma_f32_16x16x32_bf16 v[50:53], v[152:155], v[184:187], v[50:53]
	v_mfma_f32_16x16x32_bf16 v[38:41], v[144:147], v[192:195], v[38:41]
	v_mfma_f32_16x16x32_bf16 v[34:37], v[152:155], v[192:195], v[34:37]
	v_mfma_f32_16x16x32_bf16 v[22:25], v[144:147], v[200:203], v[22:25]
	v_mfma_f32_16x16x32_bf16 v[18:21], v[152:155], v[200:203], v[18:21]
	v_mfma_f32_16x16x32_bf16 v[62:65], v[148:151], v[180:183], v[62:65]
	v_mfma_f32_16x16x32_bf16 v[58:61], v[156:159], v[180:183], v[58:61]
	v_mfma_f32_16x16x32_bf16 v[54:57], v[148:151], v[188:191], v[54:57]
	v_mfma_f32_16x16x32_bf16 v[50:53], v[156:159], v[188:191], v[50:53]
	v_mfma_f32_16x16x32_bf16 v[38:41], v[148:151], v[196:199], v[38:41]
	v_mfma_f32_16x16x32_bf16 v[34:37], v[156:159], v[196:199], v[34:37]
	v_mfma_f32_16x16x32_bf16 v[22:25], v[148:151], v[204:207], v[22:25]
	v_mfma_f32_16x16x32_bf16 v[18:21], v[156:159], v[204:207], v[18:21]
	s_setprio 0
	s_setprio 1
	v_mfma_f32_16x16x32_bf16 v[46:49], v[160:163], v[176:179], v[46:49]
	v_mfma_f32_16x16x32_bf16 v[42:45], v[168:171], v[176:179], v[42:45]
	v_mfma_f32_16x16x32_bf16 v[30:33], v[160:163], v[184:187], v[30:33]
	v_mfma_f32_16x16x32_bf16 v[26:29], v[168:171], v[184:187], v[26:29]
	v_mfma_f32_16x16x32_bf16 v[14:17], v[160:163], v[192:195], v[14:17]
	v_mfma_f32_16x16x32_bf16 v[10:13], v[168:171], v[192:195], v[10:13]
	v_mfma_f32_16x16x32_bf16 v[6:9], v[160:163], v[200:203], v[6:9]
	v_mfma_f32_16x16x32_bf16 v[2:5], v[168:171], v[200:203], v[2:5]
	v_mfma_f32_16x16x32_bf16 v[46:49], v[164:167], v[180:183], v[46:49]
	v_mfma_f32_16x16x32_bf16 v[42:45], v[172:175], v[180:183], v[42:45]
	v_mfma_f32_16x16x32_bf16 v[30:33], v[164:167], v[188:191], v[30:33]
	v_mfma_f32_16x16x32_bf16 v[26:29], v[172:175], v[188:191], v[26:29]
	v_mfma_f32_16x16x32_bf16 v[14:17], v[164:167], v[196:199], v[14:17]
	v_mfma_f32_16x16x32_bf16 v[10:13], v[172:175], v[196:199], v[10:13]
	v_mfma_f32_16x16x32_bf16 v[6:9], v[164:167], v[204:207], v[6:9]
	v_mfma_f32_16x16x32_bf16 v[2:5], v[172:175], v[204:207], v[2:5]
	s_barrier
	s_setprio 0
	s_add_i32 s50, s50, 2
	s_add_u32 s36, s36, 0x100
	s_addc_u32 s37, s37, 0
	s_add_u32 s12, s12, 0x10000
	s_addc_u32 s13, s13, 0
	s_cmp_gt_u32 s50, 19
	s_cbranch_scc1 .Lpeel_done_6
.LBB0_2017:
	s_add_u32 s14, s12, 0x4000
	s_addc_u32 s15, s13, 0
	s_cmp_eq_u32 s50, 18
	s_cselect_b32 s18, s8, s14
	s_cselect_b32 s19, s9, s15
	s_cselect_b32 s16, s10, s36
	s_cselect_b32 s17, s11, s37
	s_add_u32 s14, s18, 0x8000
	s_addc_u32 s15, s19, 0
	s_add_i32 s51, 0, 0x10000
	s_add_i32 s54, 0, 0x14000
	v_add_u32_e32 v156, s51, v140
	v_add_u32_e32 v172, s54, v140
	ds_read_b128 v[144:147], v156
	ds_read_b128 v[148:151], v156 offset:1024
	ds_read_b128 v[152:155], v156 offset:2048
	ds_read_b128 v[156:159], v156 offset:3072
	ds_read_b128 v[160:163], v172
	ds_read_b128 v[164:167], v172 offset:1024
	ds_read_b128 v[168:171], v172 offset:2048
	ds_read_b128 v[172:175], v172 offset:3072
	v_lshl_add_u64 v[208:209], s[12:13], 0, v[136:137]
	s_add_i32 m0, s38, 0xc000
	ds_read_b128 v[176:179], v143
	ds_read_b128 v[180:183], v143 offset:1024
	ds_read_b128 v[184:187], v143 offset:2048
	ds_read_b128 v[188:191], v143 offset:3072
	ds_read_b128 v[192:195], v143 offset:4096
	ds_read_b128 v[196:199], v143 offset:5120
	ds_read_b128 v[200:203], v143 offset:6144
	ds_read_b128 v[204:207], v143 offset:7168
	global_load_lds_dwordx4 v[208:209], off
	v_lshl_add_u64 v[208:209], s[12:13], 0, v[138:139]
	s_add_i32 m0, s38, 0xe000
	s_nop 0
	global_load_lds_dwordx4 v[208:209], off
	s_waitcnt vmcnt(8)
	s_waitcnt lgkmcnt(0)
	s_setprio 1
	s_barrier
	v_mfma_f32_16x16x32_bf16 v[126:129], v[144:147], v[176:179], v[126:129]
	v_mfma_f32_16x16x32_bf16 v[122:125], v[152:155], v[176:179], v[122:125]
	v_mfma_f32_16x16x32_bf16 v[118:121], v[144:147], v[184:187], v[118:121]
	v_mfma_f32_16x16x32_bf16 v[114:117], v[152:155], v[184:187], v[114:117]
	v_mfma_f32_16x16x32_bf16 v[102:105], v[144:147], v[192:195], v[102:105]
	v_mfma_f32_16x16x32_bf16 v[98:101], v[152:155], v[192:195], v[98:101]
	v_mfma_f32_16x16x32_bf16 v[86:89], v[144:147], v[200:203], v[86:89]
	v_mfma_f32_16x16x32_bf16 v[82:85], v[152:155], v[200:203], v[82:85]
	v_mfma_f32_16x16x32_bf16 v[126:129], v[148:151], v[180:183], v[126:129]
	v_mfma_f32_16x16x32_bf16 v[122:125], v[156:159], v[180:183], v[122:125]
	v_mfma_f32_16x16x32_bf16 v[118:121], v[148:151], v[188:191], v[118:121]
	v_mfma_f32_16x16x32_bf16 v[114:117], v[156:159], v[188:191], v[114:117]
	v_mfma_f32_16x16x32_bf16 v[102:105], v[148:151], v[196:199], v[102:105]
	v_mfma_f32_16x16x32_bf16 v[98:101], v[156:159], v[196:199], v[98:101]
	v_mfma_f32_16x16x32_bf16 v[86:89], v[148:151], v[204:207], v[86:89]
	v_mfma_f32_16x16x32_bf16 v[82:85], v[156:159], v[204:207], v[82:85]
	s_setprio 0
	s_setprio 1
	v_mfma_f32_16x16x32_bf16 v[110:113], v[160:163], v[176:179], v[110:113]
	v_mfma_f32_16x16x32_bf16 v[106:109], v[168:171], v[176:179], v[106:109]
	v_mfma_f32_16x16x32_bf16 v[94:97], v[160:163], v[184:187], v[94:97]
	v_mfma_f32_16x16x32_bf16 v[90:93], v[168:171], v[184:187], v[90:93]
	v_mfma_f32_16x16x32_bf16 v[78:81], v[160:163], v[192:195], v[78:81]
	v_mfma_f32_16x16x32_bf16 v[74:77], v[168:171], v[192:195], v[74:77]
	v_mfma_f32_16x16x32_bf16 v[70:73], v[160:163], v[200:203], v[70:73]
	v_mfma_f32_16x16x32_bf16 v[66:69], v[168:171], v[200:203], v[66:69]
	v_mfma_f32_16x16x32_bf16 v[110:113], v[164:167], v[180:183], v[110:113]
	v_mfma_f32_16x16x32_bf16 v[106:109], v[172:175], v[180:183], v[106:109]
	v_mfma_f32_16x16x32_bf16 v[94:97], v[164:167], v[188:191], v[94:97]
	v_mfma_f32_16x16x32_bf16 v[90:93], v[172:175], v[188:191], v[90:93]
	v_mfma_f32_16x16x32_bf16 v[78:81], v[164:167], v[196:199], v[78:81]
	v_mfma_f32_16x16x32_bf16 v[74:77], v[172:175], v[196:199], v[74:77]
	v_mfma_f32_16x16x32_bf16 v[70:73], v[164:167], v[204:207], v[70:73]
	v_mfma_f32_16x16x32_bf16 v[66:69], v[172:175], v[204:207], v[66:69]
	s_barrier
	s_setprio 0
	s_add_i32 s51, s51, s24
	v_lshl_add_u64 v[208:209], s[16:17], 0, v[0:1]
	s_mov_b32 m0, s51
	ds_read_b128 v[176:179], v143 offset:16384
	ds_read_b128 v[180:183], v143 offset:17408
	ds_read_b128 v[184:187], v143 offset:18432
	ds_read_b128 v[188:191], v143 offset:19456
	ds_read_b128 v[192:195], v143 offset:20480
	ds_read_b128 v[196:199], v143 offset:21504
	ds_read_b128 v[200:203], v143 offset:22528
	ds_read_b128 v[204:207], v143 offset:23552
	global_load_lds_dwordx4 v[208:209], off
	s_add_i32 m0, s51, 0x2000
	s_add_u32 s52, s16, 0x164000
	v_lshl_add_u64 v[216:217], s[16:17], 0, v[130:131]
	s_addc_u32 s53, s17, 0
	s_add_i32 s51, s54, s24
	global_load_lds_dwordx4 v[216:217], off
	v_lshl_add_u64 v[220:221], s[52:53], 0, v[0:1]
	s_mov_b32 m0, s51
	s_nop 0
	global_load_lds_dwordx4 v[220:221], off
	v_lshl_add_u64 v[220:221], s[52:53], 0, v[130:131]
	s_add_i32 m0, s51, 0x2000
	s_nop 0
	global_load_lds_dwordx4 v[220:221], off
	v_lshl_add_u64 v[220:221], s[18:19], 0, v[134:135]
	s_mov_b32 m0, s38
	s_nop 0
	global_load_lds_dwordx4 v[220:221], off
	v_lshl_add_u64 v[220:221], s[18:19], 0, v[132:133]
	s_mov_b32 m0, s39
	s_nop 0
	global_load_lds_dwordx4 v[220:221], off
	s_waitcnt vmcnt(8)
	s_waitcnt lgkmcnt(0)
	s_setprio 1
	s_barrier
	v_mfma_f32_16x16x32_bf16 v[62:65], v[144:147], v[176:179], v[62:65]
	v_mfma_f32_16x16x32_bf16 v[58:61], v[152:155], v[176:179], v[58:61]
	v_mfma_f32_16x16x32_bf16 v[54:57], v[144:147], v[184:187], v[54:57]
	v_mfma_f32_16x16x32_bf16 v[50:53], v[152:155], v[184:187], v[50:53]
	v_mfma_f32_16x16x32_bf16 v[38:41], v[144:147], v[192:195], v[38:41]
	v_mfma_f32_16x16x32_bf16 v[34:37], v[152:155], v[192:195], v[34:37]
	v_mfma_f32_16x16x32_bf16 v[22:25], v[144:147], v[200:203], v[22:25]
	v_mfma_f32_16x16x32_bf16 v[18:21], v[152:155], v[200:203], v[18:21]
	v_mfma_f32_16x16x32_bf16 v[62:65], v[148:151], v[180:183], v[62:65]
	v_mfma_f32_16x16x32_bf16 v[58:61], v[156:159], v[180:183], v[58:61]
	v_mfma_f32_16x16x32_bf16 v[54:57], v[148:151], v[188:191], v[54:57]
	v_mfma_f32_16x16x32_bf16 v[50:53], v[156:159], v[188:191], v[50:53]
	v_mfma_f32_16x16x32_bf16 v[38:41], v[148:151], v[196:199], v[38:41]
	v_mfma_f32_16x16x32_bf16 v[34:37], v[156:159], v[196:199], v[34:37]
	v_mfma_f32_16x16x32_bf16 v[22:25], v[148:151], v[204:207], v[22:25]
	v_mfma_f32_16x16x32_bf16 v[18:21], v[156:159], v[204:207], v[18:21]
	s_setprio 0
	s_setprio 1
	v_mfma_f32_16x16x32_bf16 v[46:49], v[160:163], v[176:179], v[46:49]
	v_mfma_f32_16x16x32_bf16 v[42:45], v[168:171], v[176:179], v[42:45]
	v_mfma_f32_16x16x32_bf16 v[30:33], v[160:163], v[184:187], v[30:33]
	v_mfma_f32_16x16x32_bf16 v[26:29], v[168:171], v[184:187], v[26:29]
	v_mfma_f32_16x16x32_bf16 v[14:17], v[160:163], v[192:195], v[14:17]
	v_mfma_f32_16x16x32_bf16 v[10:13], v[168:171], v[192:195], v[10:13]
	v_mfma_f32_16x16x32_bf16 v[6:9], v[160:163], v[200:203], v[6:9]
	v_mfma_f32_16x16x32_bf16 v[2:5], v[168:171], v[200:203], v[2:5]
	v_mfma_f32_16x16x32_bf16 v[46:49], v[164:167], v[180:183], v[46:49]
	v_mfma_f32_16x16x32_bf16 v[42:45], v[172:175], v[180:183], v[42:45]
	v_mfma_f32_16x16x32_bf16 v[30:33], v[164:167], v[188:191], v[30:33]
	v_mfma_f32_16x16x32_bf16 v[26:29], v[172:175], v[188:191], v[26:29]
	v_mfma_f32_16x16x32_bf16 v[14:17], v[164:167], v[196:199], v[14:17]
	v_mfma_f32_16x16x32_bf16 v[10:13], v[172:175], v[196:199], v[10:13]
	v_mfma_f32_16x16x32_bf16 v[6:9], v[164:167], v[204:207], v[6:9]
	v_mfma_f32_16x16x32_bf16 v[2:5], v[172:175], v[204:207], v[2:5]
	s_barrier
	s_setprio 0
	s_add_i32 s51, 0, 0x18000
	s_add_i32 s52, 0, 0x1c000
	v_add_u32_e32 v156, s51, v140
	v_add_u32_e32 v172, s52, v140
	ds_read_b128 v[144:147], v156
	ds_read_b128 v[148:151], v156 offset:1024
	ds_read_b128 v[152:155], v156 offset:2048
	ds_read_b128 v[156:159], v156 offset:3072
	ds_read_b128 v[160:163], v172
	ds_read_b128 v[164:167], v172 offset:1024
	ds_read_b128 v[168:171], v172 offset:2048
	ds_read_b128 v[172:175], v172 offset:3072
	s_add_u32 s18, s18, 0x4000
	s_addc_u32 s19, s19, 0
	s_mov_b32 m0, s40
	v_lshl_add_u64 v[220:221], s[18:19], 0, v[134:135]
	ds_read_b128 v[176:179], v143 offset:32768
	ds_read_b128 v[180:183], v143 offset:33792
	ds_read_b128 v[184:187], v143 offset:34816
	ds_read_b128 v[188:191], v143 offset:35840
	ds_read_b128 v[192:195], v143 offset:36864
	ds_read_b128 v[196:199], v143 offset:37888
	ds_read_b128 v[200:203], v143 offset:38912
	ds_read_b128 v[204:207], v143 offset:39936
	global_load_lds_dwordx4 v[220:221], off
	v_lshl_add_u64 v[220:221], s[18:19], 0, v[132:133]
	s_mov_b32 m0, s41
	s_nop 0
	global_load_lds_dwordx4 v[220:221], off
	s_waitcnt vmcnt(8)
	s_waitcnt lgkmcnt(0)
	s_setprio 1
	s_barrier
	v_mfma_f32_16x16x32_bf16 v[126:129], v[144:147], v[176:179], v[126:129]
	v_mfma_f32_16x16x32_bf16 v[122:125], v[152:155], v[176:179], v[122:125]
	v_mfma_f32_16x16x32_bf16 v[118:121], v[144:147], v[184:187], v[118:121]
	v_mfma_f32_16x16x32_bf16 v[114:117], v[152:155], v[184:187], v[114:117]
	v_mfma_f32_16x16x32_bf16 v[102:105], v[144:147], v[192:195], v[102:105]
	v_mfma_f32_16x16x32_bf16 v[98:101], v[152:155], v[192:195], v[98:101]
	v_mfma_f32_16x16x32_bf16 v[86:89], v[144:147], v[200:203], v[86:89]
	v_mfma_f32_16x16x32_bf16 v[82:85], v[152:155], v[200:203], v[82:85]
	v_mfma_f32_16x16x32_bf16 v[126:129], v[148:151], v[180:183], v[126:129]
	v_mfma_f32_16x16x32_bf16 v[122:125], v[156:159], v[180:183], v[122:125]
	v_mfma_f32_16x16x32_bf16 v[118:121], v[148:151], v[188:191], v[118:121]
	v_mfma_f32_16x16x32_bf16 v[114:117], v[156:159], v[188:191], v[114:117]
	v_mfma_f32_16x16x32_bf16 v[102:105], v[148:151], v[196:199], v[102:105]
	v_mfma_f32_16x16x32_bf16 v[98:101], v[156:159], v[196:199], v[98:101]
	v_mfma_f32_16x16x32_bf16 v[86:89], v[148:151], v[204:207], v[86:89]
	v_mfma_f32_16x16x32_bf16 v[82:85], v[156:159], v[204:207], v[82:85]
	s_setprio 0
	s_setprio 1
	v_mfma_f32_16x16x32_bf16 v[110:113], v[160:163], v[176:179], v[110:113]
	v_mfma_f32_16x16x32_bf16 v[106:109], v[168:171], v[176:179], v[106:109]
	v_mfma_f32_16x16x32_bf16 v[94:97], v[160:163], v[184:187], v[94:97]
	v_mfma_f32_16x16x32_bf16 v[90:93], v[168:171], v[184:187], v[90:93]
	v_mfma_f32_16x16x32_bf16 v[78:81], v[160:163], v[192:195], v[78:81]
	v_mfma_f32_16x16x32_bf16 v[74:77], v[168:171], v[192:195], v[74:77]
	v_mfma_f32_16x16x32_bf16 v[70:73], v[160:163], v[200:203], v[70:73]
	v_mfma_f32_16x16x32_bf16 v[66:69], v[168:171], v[200:203], v[66:69]
	v_mfma_f32_16x16x32_bf16 v[110:113], v[164:167], v[180:183], v[110:113]
	v_mfma_f32_16x16x32_bf16 v[106:109], v[172:175], v[180:183], v[106:109]
	v_mfma_f32_16x16x32_bf16 v[94:97], v[164:167], v[188:191], v[94:97]
	v_mfma_f32_16x16x32_bf16 v[90:93], v[172:175], v[188:191], v[90:93]
	v_mfma_f32_16x16x32_bf16 v[78:81], v[164:167], v[196:199], v[78:81]
	v_mfma_f32_16x16x32_bf16 v[74:77], v[172:175], v[196:199], v[74:77]
	v_mfma_f32_16x16x32_bf16 v[70:73], v[164:167], v[204:207], v[70:73]
	v_mfma_f32_16x16x32_bf16 v[66:69], v[172:175], v[204:207], v[66:69]
	s_barrier
	s_setprio 0
	s_add_i32 s18, s51, s24
	v_lshl_add_u64 v[208:209], v[208:209], 0, s[2:3]
	s_mov_b32 m0, s18
	ds_read_b128 v[176:179], v143 offset:49152
	ds_read_b128 v[180:183], v143 offset:50176
	ds_read_b128 v[184:187], v143 offset:51200
	ds_read_b128 v[188:191], v143 offset:52224
	ds_read_b128 v[192:195], v143 offset:53248
	ds_read_b128 v[196:199], v143 offset:54272
	ds_read_b128 v[200:203], v143 offset:55296
	ds_read_b128 v[204:207], v143 offset:56320
	global_load_lds_dwordx4 v[208:209], off
	s_add_i32 m0, s18, 0x2000
	s_add_u32 s16, s16, 0x164080
	v_lshl_add_u64 v[208:209], v[216:217], 0, s[2:3]
	s_addc_u32 s17, s17, 0
	s_add_i32 s18, s52, s24
	global_load_lds_dwordx4 v[208:209], off
	v_lshl_add_u64 v[208:209], s[16:17], 0, v[0:1]
	s_mov_b32 m0, s18
	s_nop 0
	global_load_lds_dwordx4 v[208:209], off
	v_lshl_add_u64 v[208:209], s[16:17], 0, v[130:131]
	s_add_i32 m0, s18, 0x2000
	s_nop 0
	global_load_lds_dwordx4 v[208:209], off
	v_lshl_add_u64 v[208:209], s[14:15], 0, v[134:135]
	s_mov_b32 m0, s42
	s_nop 0
	global_load_lds_dwordx4 v[208:209], off
	v_lshl_add_u64 v[208:209], s[14:15], 0, v[132:133]
	s_mov_b32 m0, s43
	s_nop 0
	global_load_lds_dwordx4 v[208:209], off
	s_waitcnt vmcnt(8)
	s_waitcnt lgkmcnt(0)
	s_setprio 1
	s_barrier
	v_mfma_f32_16x16x32_bf16 v[62:65], v[144:147], v[176:179], v[62:65]
	v_mfma_f32_16x16x32_bf16 v[58:61], v[152:155], v[176:179], v[58:61]
	v_mfma_f32_16x16x32_bf16 v[54:57], v[144:147], v[184:187], v[54:57]
	v_mfma_f32_16x16x32_bf16 v[50:53], v[152:155], v[184:187], v[50:53]
	v_mfma_f32_16x16x32_bf16 v[38:41], v[144:147], v[192:195], v[38:41]
	v_mfma_f32_16x16x32_bf16 v[34:37], v[152:155], v[192:195], v[34:37]
	v_mfma_f32_16x16x32_bf16 v[22:25], v[144:147], v[200:203], v[22:25]
	v_mfma_f32_16x16x32_bf16 v[18:21], v[152:155], v[200:203], v[18:21]
	v_mfma_f32_16x16x32_bf16 v[62:65], v[148:151], v[180:183], v[62:65]
	v_mfma_f32_16x16x32_bf16 v[58:61], v[156:159], v[180:183], v[58:61]
	v_mfma_f32_16x16x32_bf16 v[54:57], v[148:151], v[188:191], v[54:57]
	v_mfma_f32_16x16x32_bf16 v[50:53], v[156:159], v[188:191], v[50:53]
	v_mfma_f32_16x16x32_bf16 v[38:41], v[148:151], v[196:199], v[38:41]
	v_mfma_f32_16x16x32_bf16 v[34:37], v[156:159], v[196:199], v[34:37]
	v_mfma_f32_16x16x32_bf16 v[22:25], v[148:151], v[204:207], v[22:25]
	v_mfma_f32_16x16x32_bf16 v[18:21], v[156:159], v[204:207], v[18:21]
	s_setprio 0
	s_setprio 1
	v_mfma_f32_16x16x32_bf16 v[46:49], v[160:163], v[176:179], v[46:49]
	v_mfma_f32_16x16x32_bf16 v[42:45], v[168:171], v[176:179], v[42:45]
	v_mfma_f32_16x16x32_bf16 v[30:33], v[160:163], v[184:187], v[30:33]
	v_mfma_f32_16x16x32_bf16 v[26:29], v[168:171], v[184:187], v[26:29]
	v_mfma_f32_16x16x32_bf16 v[14:17], v[160:163], v[192:195], v[14:17]
	v_mfma_f32_16x16x32_bf16 v[10:13], v[168:171], v[192:195], v[10:13]
	v_mfma_f32_16x16x32_bf16 v[6:9], v[160:163], v[200:203], v[6:9]
	v_mfma_f32_16x16x32_bf16 v[2:5], v[168:171], v[200:203], v[2:5]
	v_mfma_f32_16x16x32_bf16 v[46:49], v[164:167], v[180:183], v[46:49]
	v_mfma_f32_16x16x32_bf16 v[42:45], v[172:175], v[180:183], v[42:45]
	v_mfma_f32_16x16x32_bf16 v[30:33], v[164:167], v[188:191], v[30:33]
	v_mfma_f32_16x16x32_bf16 v[26:29], v[172:175], v[188:191], v[26:29]
	v_mfma_f32_16x16x32_bf16 v[14:17], v[164:167], v[196:199], v[14:17]
	v_mfma_f32_16x16x32_bf16 v[10:13], v[172:175], v[196:199], v[10:13]
	v_mfma_f32_16x16x32_bf16 v[6:9], v[164:167], v[204:207], v[6:9]
	v_mfma_f32_16x16x32_bf16 v[2:5], v[172:175], v[204:207], v[2:5]
	s_barrier
	s_setprio 0
	s_add_i32 s50, s50, 2
	s_add_u32 s36, s36, 0x100
	s_addc_u32 s37, s37, 0
	s_add_u32 s12, s12, 0x10000
	s_addc_u32 s13, s13, 0
	s_cmp_gt_u32 s50, 19
	s_cbranch_scc0 .LBB0_2017
